# KV+Q epilogue ssq/pos loads batched, P0 plain transposer loops unrolled (32 loads in flight)
# baseline (speedup 1.0000x reference)
; template <int KIND> __device__ __forceinline__ void tr_item(const float* __restrict__ W, int K, int Nsrc, const float* __restrict__ gk, bf16_t* WT, LAS float* scr, int item, int nblk, int lane) {
;     const int kb = item / nblk, nb = item - kb * nblk, k0 = 64 * kb, n0 = 32 * nb;
;     const int src = srcmap<KIND>(n0 + (lane & 31));
; #pragma unroll 8
;     for (int i = 0; i < 32; ++i) { const int kk = 2 * i + (lane >> 5); float v = 0.f; if (src >= 0) v = __builtin_nontemporal_load(&W[(size_t)(k0 + kk) * Nsrc + src]); if (gk) v *= gk[k0 + kk]; scr[kk * 33 + (lane & 31)] = v; }
.LBB0_34:
	v_add_u32_e32 v13, s7, v7
	v_add_u32_e32 v2, 0xffff8a80, v13
	v_lshlrev_b64 v[14:15], 13, v[2:3]
	v_add_u32_e32 v2, 0xffff8a82, v13
	v_lshlrev_b64 v[16:17], 13, v[2:3]
	v_add_u32_e32 v2, 0xffff8a84, v13
	v_lshl_add_u64 v[14:15], v[10:11], 0, v[14:15]
	v_lshl_add_u64 v[16:17], v[10:11], 0, v[16:17]
	v_lshlrev_b64 v[18:19], 13, v[2:3]
	v_add_u32_e32 v2, 0xffff8a86, v13
	global_load_dword v100, v[14:15], off nt
	global_load_dword v101, v[16:17], off nt
	v_lshlrev_b64 v[16:17], 13, v[2:3]
	v_add_u32_e32 v2, 0xffff8a88, v13
	v_lshl_add_u64 v[14:15], v[10:11], 0, v[18:19]
	v_lshl_add_u64 v[16:17], v[10:11], 0, v[16:17]
	v_lshlrev_b64 v[18:19], 13, v[2:3]
	v_add_u32_e32 v2, 0xffff8a8a, v13
	global_load_dword v102, v[14:15], off nt
	global_load_dword v103, v[16:17], off nt
	v_lshlrev_b64 v[16:17], 13, v[2:3]
	v_add_u32_e32 v2, 0xffff8a8c, v13
	v_lshl_add_u64 v[14:15], v[10:11], 0, v[18:19]
	v_lshl_add_u64 v[16:17], v[10:11], 0, v[16:17]
	v_lshlrev_b64 v[18:19], 13, v[2:3]
	v_add_u32_e32 v2, 0xffff8a8e, v13
	global_load_dword v104, v[14:15], off nt
	global_load_dword v105, v[16:17], off nt
	v_lshl_add_u64 v[14:15], v[10:11], 0, v[18:19]
	v_lshlrev_b64 v[16:17], 13, v[2:3]
	v_lshl_add_u64 v[16:17], v[10:11], 0, v[16:17]
	global_load_dword v106, v[14:15], off nt
	s_nop 0
	global_load_dword v107, v[16:17], off nt
	s_add_i32 s7, s7, 16
	v_add_u32_e32 v13, s7, v7
	v_add_u32_e32 v2, 0xffff8a80, v13
	v_lshlrev_b64 v[14:15], 13, v[2:3]
	v_add_u32_e32 v2, 0xffff8a82, v13
	v_lshlrev_b64 v[16:17], 13, v[2:3]
	v_add_u32_e32 v2, 0xffff8a84, v13
	v_lshl_add_u64 v[14:15], v[10:11], 0, v[14:15]
	v_lshl_add_u64 v[16:17], v[10:11], 0, v[16:17]
	v_lshlrev_b64 v[18:19], 13, v[2:3]
	v_add_u32_e32 v2, 0xffff8a86, v13
	global_load_dword v108, v[14:15], off nt
	global_load_dword v109, v[16:17], off nt
	v_lshlrev_b64 v[16:17], 13, v[2:3]
	v_add_u32_e32 v2, 0xffff8a88, v13
	v_lshl_add_u64 v[14:15], v[10:11], 0, v[18:19]
	v_lshl_add_u64 v[16:17], v[10:11], 0, v[16:17]
	v_lshlrev_b64 v[18:19], 13, v[2:3]
	v_add_u32_e32 v2, 0xffff8a8a, v13
	global_load_dword v110, v[14:15], off nt
	global_load_dword v111, v[16:17], off nt
	v_lshlrev_b64 v[16:17], 13, v[2:3]
	v_add_u32_e32 v2, 0xffff8a8c, v13
	v_lshl_add_u64 v[14:15], v[10:11], 0, v[18:19]
	v_lshl_add_u64 v[16:17], v[10:11], 0, v[16:17]
	v_lshlrev_b64 v[18:19], 13, v[2:3]
	v_add_u32_e32 v2, 0xffff8a8e, v13
	global_load_dword v112, v[14:15], off nt
	global_load_dword v113, v[16:17], off nt
	v_lshl_add_u64 v[14:15], v[10:11], 0, v[18:19]
	v_lshlrev_b64 v[16:17], 13, v[2:3]
	v_lshl_add_u64 v[16:17], v[10:11], 0, v[16:17]
	global_load_dword v114, v[14:15], off nt
	s_nop 0
	global_load_dword v115, v[16:17], off nt
	s_add_i32 s7, s7, 16
	v_add_u32_e32 v13, s7, v7
	v_add_u32_e32 v2, 0xffff8a80, v13
	v_lshlrev_b64 v[14:15], 13, v[2:3]
	v_add_u32_e32 v2, 0xffff8a82, v13
	v_lshlrev_b64 v[16:17], 13, v[2:3]
	v_add_u32_e32 v2, 0xffff8a84, v13
	v_lshl_add_u64 v[14:15], v[10:11], 0, v[14:15]
	v_lshl_add_u64 v[16:17], v[10:11], 0, v[16:17]
	v_lshlrev_b64 v[18:19], 13, v[2:3]
	v_add_u32_e32 v2, 0xffff8a86, v13
	global_load_dword v116, v[14:15], off nt
	global_load_dword v117, v[16:17], off nt
	v_lshlrev_b64 v[16:17], 13, v[2:3]
	v_add_u32_e32 v2, 0xffff8a88, v13
	v_lshl_add_u64 v[14:15], v[10:11], 0, v[18:19]
	v_lshl_add_u64 v[16:17], v[10:11], 0, v[16:17]
	v_lshlrev_b64 v[18:19], 13, v[2:3]
	v_add_u32_e32 v2, 0xffff8a8a, v13
	global_load_dword v118, v[14:15], off nt
	global_load_dword v119, v[16:17], off nt
	v_lshlrev_b64 v[16:17], 13, v[2:3]
	v_add_u32_e32 v2, 0xffff8a8c, v13
	v_lshl_add_u64 v[14:15], v[10:11], 0, v[18:19]
	v_lshl_add_u64 v[16:17], v[10:11], 0, v[16:17]
	v_lshlrev_b64 v[18:19], 13, v[2:3]
	v_add_u32_e32 v2, 0xffff8a8e, v13
	global_load_dword v120, v[14:15], off nt
	global_load_dword v121, v[16:17], off nt
	v_lshl_add_u64 v[14:15], v[10:11], 0, v[18:19]
	v_lshlrev_b64 v[16:17], 13, v[2:3]
	v_lshl_add_u64 v[16:17], v[10:11], 0, v[16:17]
	global_load_dword v122, v[14:15], off nt
	s_nop 0
	global_load_dword v123, v[16:17], off nt
	s_add_i32 s7, s7, 16
	v_add_u32_e32 v13, s7, v7
	v_add_u32_e32 v2, 0xffff8a80, v13
	v_lshlrev_b64 v[14:15], 13, v[2:3]
	v_add_u32_e32 v2, 0xffff8a82, v13
	v_lshlrev_b64 v[16:17], 13, v[2:3]
	v_add_u32_e32 v2, 0xffff8a84, v13
	v_lshl_add_u64 v[14:15], v[10:11], 0, v[14:15]
	v_lshl_add_u64 v[16:17], v[10:11], 0, v[16:17]
	v_lshlrev_b64 v[18:19], 13, v[2:3]
	v_add_u32_e32 v2, 0xffff8a86, v13
	global_load_dword v124, v[14:15], off nt
	global_load_dword v125, v[16:17], off nt
	v_lshlrev_b64 v[16:17], 13, v[2:3]
	v_add_u32_e32 v2, 0xffff8a88, v13
	v_lshl_add_u64 v[14:15], v[10:11], 0, v[18:19]
	v_lshl_add_u64 v[16:17], v[10:11], 0, v[16:17]
	v_lshlrev_b64 v[18:19], 13, v[2:3]
	v_add_u32_e32 v2, 0xffff8a8a, v13
	global_load_dword v126, v[14:15], off nt
	global_load_dword v127, v[16:17], off nt
	v_lshlrev_b64 v[16:17], 13, v[2:3]
	v_add_u32_e32 v2, 0xffff8a8c, v13
	v_lshl_add_u64 v[14:15], v[10:11], 0, v[18:19]
	v_lshl_add_u64 v[16:17], v[10:11], 0, v[16:17]
	v_lshlrev_b64 v[18:19], 13, v[2:3]
	v_add_u32_e32 v2, 0xffff8a8e, v13
	global_load_dword v128, v[14:15], off nt
	global_load_dword v129, v[16:17], off nt
	v_lshl_add_u64 v[14:15], v[10:11], 0, v[18:19]
	v_lshlrev_b64 v[16:17], 13, v[2:3]
	v_lshl_add_u64 v[16:17], v[10:11], 0, v[16:17]
	global_load_dword v130, v[14:15], off nt
	s_nop 0
	global_load_dword v131, v[16:17], off nt
	s_add_i32 s7, s7, 16
	v_add_u32_e32 v15, 0x400, v9
	s_waitcnt vmcnt(30)
; #define LAS __attribute__((address_space(3)))
; __device__ __forceinline__ unsigned pk2(float lo, float hi) { return pg8::cvt_pk_bf16(lo, hi); }
; template <int KIND> __device__ __forceinline__ void tr_item(const float* __restrict__ W, int K, int Nsrc, const float* __restrict__ gk, bf16_t* WT, LAS float* scr, int item, int nblk, int lane) {
;     ...
;     for (int i = 0; i < 32; ++i) { const int kk = 2 * i + (lane >> 5); float v = 0.f; if (src >= 0) v = __builtin_nontemporal_load(&W[(size_t)(k0 + kk) * Nsrc + src]); if (gk) v *= gk[k0 + kk]; scr[kk * 33 + (lane & 31)] = v; }
;     asm volatile("s_waitcnt lgkmcnt(0)" ::: "memory");
;     const int c = lane & 7;
; #pragma unroll
;     for (int j = 0; j < 4; ++j) { const int n = (lane >> 3) + 8 * j; const LAS float* s = scr + (8 * c) * 33 + n;
;         u32x4 o; o.x = pk2(s[0 * 33], s[1 * 33]); o.y = pk2(s[2 * 33], s[3 * 33]); o.z = pk2(s[4 * 33], s[5 * 33]); o.w = pk2(s[6 * 33], s[7 * 33]);
;         *(u32x4*)(WT + (size_t)(n0 + n) * K + k0 + 8 * c) = o; }
;     asm volatile("s_waitcnt lgkmcnt(0)" ::: "memory");
	ds_write2_b32 v9, v100, v101 offset1:66
	s_waitcnt vmcnt(28)
	ds_write2_b32 v9, v102, v103 offset0:132 offset1:198
	v_add_u32_e32 v9, 0x840, v9
	s_waitcnt vmcnt(26)
	ds_write2_b32 v15, v104, v105 offset0:8 offset1:74
	s_waitcnt vmcnt(24)
	ds_write2_b32 v15, v106, v107 offset0:140 offset1:206
	v_add_u32_e32 v15, 0x400, v9
	s_waitcnt vmcnt(22)
	ds_write2_b32 v9, v108, v109 offset1:66
	s_waitcnt vmcnt(20)
	ds_write2_b32 v9, v110, v111 offset0:132 offset1:198
	v_add_u32_e32 v9, 0x840, v9
	s_waitcnt vmcnt(18)
	ds_write2_b32 v15, v112, v113 offset0:8 offset1:74
	s_waitcnt vmcnt(16)
	ds_write2_b32 v15, v114, v115 offset0:140 offset1:206
	v_add_u32_e32 v15, 0x400, v9
	s_waitcnt vmcnt(14)
	ds_write2_b32 v9, v116, v117 offset1:66
	s_waitcnt vmcnt(12)
	ds_write2_b32 v9, v118, v119 offset0:132 offset1:198
	v_add_u32_e32 v9, 0x840, v9
	s_waitcnt vmcnt(10)
	ds_write2_b32 v15, v120, v121 offset0:8 offset1:74
	s_waitcnt vmcnt(8)
	ds_write2_b32 v15, v122, v123 offset0:140 offset1:206
	v_add_u32_e32 v15, 0x400, v9
	s_waitcnt vmcnt(6)
	ds_write2_b32 v9, v124, v125 offset1:66
	s_waitcnt vmcnt(4)
	ds_write2_b32 v9, v126, v127 offset0:132 offset1:198
	v_add_u32_e32 v9, 0x840, v9
	s_waitcnt vmcnt(2)
	ds_write2_b32 v15, v128, v129 offset0:8 offset1:74
	s_waitcnt vmcnt(0)
	ds_write2_b32 v15, v130, v131 offset0:140 offset1:206
	s_and_b32 s7, s50, 0x7fffffc0
	s_add_i32 s8, s7, 0xffff8a80
	s_waitcnt lgkmcnt(0)
	s_lshl_b64 s[34:35], s[8:9], 1
	ds_read2_b32 v[18:19], v26 offset0:33 offset1:41
	ds_read2_b32 v[20:21], v26 offset1:8
	ds_read2_b32 v[22:23], v26 offset0:66 offset1:74
	ds_read2_b32 v[42:43], v26 offset0:99 offset1:107
	ds_read2_b32 v[44:45], v26 offset0:132 offset1:140
	ds_read2_b32 v[46:47], v26 offset0:165 offset1:173
	ds_read2_b32 v[48:49], v26 offset0:198 offset1:206
	ds_read2_b32 v[50:51], v26 offset0:231 offset1:239
	s_add_u32 s4, s4, s34
	s_addc_u32 s5, s5, s35
	v_mov_b32_e32 v7, v3
	v_lshl_add_u64 v[10:11], s[4:5], 0, v[6:7]
	v_or_b32_e32 v2, s6, v25
	v_lshl_add_u64 v[10:11], v[10:11], 0, s[10:11]
	v_lshlrev_b32_e32 v2, 12, v2
	s_waitcnt lgkmcnt(6)
	v_cvt_pk_bf16_f32 v14, v20, v18
	s_waitcnt lgkmcnt(4)
	v_cvt_pk_bf16_f32 v15, v22, v42
	s_waitcnt lgkmcnt(2)
	v_cvt_pk_bf16_f32 v16, v44, v46
	s_waitcnt lgkmcnt(0)
	v_cvt_pk_bf16_f32 v17, v48, v50
	v_lshl_add_u64 v[52:53], v[10:11], 0, v[2:3]
	global_store_dwordx4 v[52:53], v[14:17], off
	v_or_b32_e32 v2, s6, v27
	v_lshlrev_b32_e32 v2, 12, v2
	v_cvt_pk_bf16_f32 v14, v21, v19
	v_cvt_pk_bf16_f32 v15, v23, v43
	v_cvt_pk_bf16_f32 v16, v45, v47
	v_cvt_pk_bf16_f32 v17, v49, v51
	ds_read2_b32 v[20:21], v26 offset0:49 offset1:57
	ds_read2_b32 v[22:23], v26 offset0:16 offset1:24
	ds_read2_b32 v[42:43], v26 offset0:82 offset1:90
	ds_read2_b32 v[44:45], v26 offset0:115 offset1:123
	ds_read2_b32 v[46:47], v26 offset0:148 offset1:156
	ds_read2_b32 v[48:49], v26 offset0:181 offset1:189
	ds_read2_b32 v[50:51], v26 offset0:214 offset1:222
	ds_read2_b32 v[52:53], v26 offset0:247 offset1:255
	v_lshl_add_u64 v[18:19], v[10:11], 0, v[2:3]
	v_or_b32_e32 v2, s6, v28
	v_lshlrev_b32_e32 v2, 12, v2
	global_store_dwordx4 v[18:19], v[14:17], off
	v_lshl_add_u64 v[18:19], v[10:11], 0, v[2:3]
	v_or_b32_e32 v2, s6, v29
	s_waitcnt lgkmcnt(6)
	v_cvt_pk_bf16_f32 v14, v22, v20
	s_waitcnt lgkmcnt(4)
	v_cvt_pk_bf16_f32 v15, v42, v44
	s_waitcnt lgkmcnt(2)
	v_cvt_pk_bf16_f32 v16, v46, v48
	s_waitcnt lgkmcnt(0)
	v_cvt_pk_bf16_f32 v17, v50, v52
	v_lshlrev_b32_e32 v2, 12, v2
	global_store_dwordx4 v[18:19], v[14:17], off
	v_lshl_add_u64 v[10:11], v[10:11], 0, v[2:3]
	s_mov_b64 s[4:5], 0
	v_cvt_pk_bf16_f32 v14, v23, v21
	v_cvt_pk_bf16_f32 v15, v43, v45
	v_cvt_pk_bf16_f32 v16, v47, v49
	v_cvt_pk_bf16_f32 v17, v51, v53
	global_store_dwordx4 v[10:11], v[14:17], off
	s_waitcnt lgkmcnt(0)

; template <int KIND> __device__ __forceinline__ void tr_item(const float* __restrict__ W, int K, int Nsrc, const float* __restrict__ gk, bf16_t* WT, LAS float* scr, int item, int nblk, int lane) {
;     const int kb = item / nblk, nb = item - kb * nblk, k0 = 64 * kb, n0 = 32 * nb;
;     const int src = srcmap<KIND>(n0 + (lane & 31));
; #pragma unroll 8
;     for (int i = 0; i < 32; ++i) { const int kk = 2 * i + (lane >> 5); float v = 0.f; if (src >= 0) v = __builtin_nontemporal_load(&W[(size_t)(k0 + kk) * Nsrc + src]); if (gk) v *= gk[k0 + kk]; scr[kk * 33 + (lane & 31)] = v; }
.LBB0_38:
	v_add_u32_e32 v13, s7, v12
	v_add_u32_e32 v2, 0xffff8b80, v13
	v_lshlrev_b64 v[10:11], 13, v[2:3]
	v_add_u32_e32 v2, 0xffff8b82, v13
	v_lshlrev_b64 v[14:15], 13, v[2:3]
	v_add_u32_e32 v2, 0xffff8b84, v13
	v_lshl_add_u64 v[10:11], v[8:9], 0, v[10:11]
	v_lshl_add_u64 v[14:15], v[8:9], 0, v[14:15]
	v_lshlrev_b64 v[16:17], 13, v[2:3]
	v_add_u32_e32 v2, 0xffff8b86, v13
	global_load_dword v100, v[10:11], off nt
	global_load_dword v101, v[14:15], off nt
	v_lshlrev_b64 v[14:15], 13, v[2:3]
	v_add_u32_e32 v2, 0xffff8b88, v13
	v_lshl_add_u64 v[10:11], v[8:9], 0, v[16:17]
	v_lshl_add_u64 v[14:15], v[8:9], 0, v[14:15]
	v_lshlrev_b64 v[16:17], 13, v[2:3]
	v_add_u32_e32 v2, 0xffff8b8a, v13
	global_load_dword v102, v[10:11], off nt
	global_load_dword v103, v[14:15], off nt
	v_lshlrev_b64 v[14:15], 13, v[2:3]
	v_add_u32_e32 v2, 0xffff8b8c, v13
	v_lshl_add_u64 v[10:11], v[8:9], 0, v[16:17]
	v_lshl_add_u64 v[14:15], v[8:9], 0, v[14:15]
	v_lshlrev_b64 v[16:17], 13, v[2:3]
	v_add_u32_e32 v2, 0xffff8b8e, v13
	global_load_dword v104, v[10:11], off nt
	global_load_dword v105, v[14:15], off nt
	v_lshl_add_u64 v[10:11], v[8:9], 0, v[16:17]
	v_lshlrev_b64 v[14:15], 13, v[2:3]
	v_lshl_add_u64 v[14:15], v[8:9], 0, v[14:15]
	global_load_dword v106, v[10:11], off nt
	s_nop 0
	global_load_dword v107, v[14:15], off nt
	s_add_i32 s7, s7, 16
	v_add_u32_e32 v13, s7, v12
	v_add_u32_e32 v2, 0xffff8b80, v13
	v_lshlrev_b64 v[10:11], 13, v[2:3]
	v_add_u32_e32 v2, 0xffff8b82, v13
	v_lshlrev_b64 v[14:15], 13, v[2:3]
	v_add_u32_e32 v2, 0xffff8b84, v13
	v_lshl_add_u64 v[10:11], v[8:9], 0, v[10:11]
	v_lshl_add_u64 v[14:15], v[8:9], 0, v[14:15]
	v_lshlrev_b64 v[16:17], 13, v[2:3]
	v_add_u32_e32 v2, 0xffff8b86, v13
	global_load_dword v108, v[10:11], off nt
	global_load_dword v109, v[14:15], off nt
	v_lshlrev_b64 v[14:15], 13, v[2:3]
	v_add_u32_e32 v2, 0xffff8b88, v13
	v_lshl_add_u64 v[10:11], v[8:9], 0, v[16:17]
	v_lshl_add_u64 v[14:15], v[8:9], 0, v[14:15]
	v_lshlrev_b64 v[16:17], 13, v[2:3]
	v_add_u32_e32 v2, 0xffff8b8a, v13
	global_load_dword v110, v[10:11], off nt
	global_load_dword v111, v[14:15], off nt
	v_lshlrev_b64 v[14:15], 13, v[2:3]
	v_add_u32_e32 v2, 0xffff8b8c, v13
	v_lshl_add_u64 v[10:11], v[8:9], 0, v[16:17]
	v_lshl_add_u64 v[14:15], v[8:9], 0, v[14:15]
	v_lshlrev_b64 v[16:17], 13, v[2:3]
	v_add_u32_e32 v2, 0xffff8b8e, v13
	global_load_dword v112, v[10:11], off nt
	global_load_dword v113, v[14:15], off nt
	v_lshl_add_u64 v[10:11], v[8:9], 0, v[16:17]
	v_lshlrev_b64 v[14:15], 13, v[2:3]
	v_lshl_add_u64 v[14:15], v[8:9], 0, v[14:15]
	global_load_dword v114, v[10:11], off nt
	s_nop 0
	global_load_dword v115, v[14:15], off nt
	s_add_i32 s7, s7, 16
	v_add_u32_e32 v13, s7, v12
	v_add_u32_e32 v2, 0xffff8b80, v13
	v_lshlrev_b64 v[10:11], 13, v[2:3]
	v_add_u32_e32 v2, 0xffff8b82, v13
	v_lshlrev_b64 v[14:15], 13, v[2:3]
	v_add_u32_e32 v2, 0xffff8b84, v13
	v_lshl_add_u64 v[10:11], v[8:9], 0, v[10:11]
	v_lshl_add_u64 v[14:15], v[8:9], 0, v[14:15]
	v_lshlrev_b64 v[16:17], 13, v[2:3]
	v_add_u32_e32 v2, 0xffff8b86, v13
	global_load_dword v116, v[10:11], off nt
	global_load_dword v117, v[14:15], off nt
	v_lshlrev_b64 v[14:15], 13, v[2:3]
	v_add_u32_e32 v2, 0xffff8b88, v13
	v_lshl_add_u64 v[10:11], v[8:9], 0, v[16:17]
	v_lshl_add_u64 v[14:15], v[8:9], 0, v[14:15]
	v_lshlrev_b64 v[16:17], 13, v[2:3]
	v_add_u32_e32 v2, 0xffff8b8a, v13
	global_load_dword v118, v[10:11], off nt
	global_load_dword v119, v[14:15], off nt
	v_lshlrev_b64 v[14:15], 13, v[2:3]
	v_add_u32_e32 v2, 0xffff8b8c, v13
	v_lshl_add_u64 v[10:11], v[8:9], 0, v[16:17]
	v_lshl_add_u64 v[14:15], v[8:9], 0, v[14:15]
	v_lshlrev_b64 v[16:17], 13, v[2:3]
	v_add_u32_e32 v2, 0xffff8b8e, v13
	global_load_dword v120, v[10:11], off nt
	global_load_dword v121, v[14:15], off nt
	v_lshl_add_u64 v[10:11], v[8:9], 0, v[16:17]
	v_lshlrev_b64 v[14:15], 13, v[2:3]
	v_lshl_add_u64 v[14:15], v[8:9], 0, v[14:15]
	global_load_dword v122, v[10:11], off nt
	s_nop 0
	global_load_dword v123, v[14:15], off nt
	s_add_i32 s7, s7, 16
	v_add_u32_e32 v13, s7, v12
	v_add_u32_e32 v2, 0xffff8b80, v13
	v_lshlrev_b64 v[10:11], 13, v[2:3]
	v_add_u32_e32 v2, 0xffff8b82, v13
	v_lshlrev_b64 v[14:15], 13, v[2:3]
	v_add_u32_e32 v2, 0xffff8b84, v13
	v_lshl_add_u64 v[10:11], v[8:9], 0, v[10:11]
	v_lshl_add_u64 v[14:15], v[8:9], 0, v[14:15]
	v_lshlrev_b64 v[16:17], 13, v[2:3]
	v_add_u32_e32 v2, 0xffff8b86, v13
	global_load_dword v124, v[10:11], off nt
	global_load_dword v125, v[14:15], off nt
	v_lshlrev_b64 v[14:15], 13, v[2:3]
	v_add_u32_e32 v2, 0xffff8b88, v13
	v_lshl_add_u64 v[10:11], v[8:9], 0, v[16:17]
	v_lshl_add_u64 v[14:15], v[8:9], 0, v[14:15]
	v_lshlrev_b64 v[16:17], 13, v[2:3]
	v_add_u32_e32 v2, 0xffff8b8a, v13
	global_load_dword v126, v[10:11], off nt
	global_load_dword v127, v[14:15], off nt
	v_lshlrev_b64 v[14:15], 13, v[2:3]
	v_add_u32_e32 v2, 0xffff8b8c, v13
	v_lshl_add_u64 v[10:11], v[8:9], 0, v[16:17]
	v_lshl_add_u64 v[14:15], v[8:9], 0, v[14:15]
	v_lshlrev_b64 v[16:17], 13, v[2:3]
	v_add_u32_e32 v2, 0xffff8b8e, v13
	global_load_dword v128, v[10:11], off nt
	global_load_dword v129, v[14:15], off nt
	v_lshl_add_u64 v[10:11], v[8:9], 0, v[16:17]
	v_lshlrev_b64 v[14:15], 13, v[2:3]
	v_lshl_add_u64 v[14:15], v[8:9], 0, v[14:15]
	global_load_dword v130, v[10:11], off nt
	s_nop 0
	global_load_dword v131, v[14:15], off nt
	s_add_i32 s7, s7, 16
	v_add_u32_e32 v11, 0x400, v7
	s_waitcnt vmcnt(30)
; #define LAS __attribute__((address_space(3)))
; __device__ __forceinline__ unsigned pk2(float lo, float hi) { return pg8::cvt_pk_bf16(lo, hi); }
; template <int KIND> __device__ __forceinline__ void tr_item(const float* __restrict__ W, int K, int Nsrc, const float* __restrict__ gk, bf16_t* WT, LAS float* scr, int item, int nblk, int lane) {
;     ...
;     for (int i = 0; i < 32; ++i) { const int kk = 2 * i + (lane >> 5); float v = 0.f; if (src >= 0) v = __builtin_nontemporal_load(&W[(size_t)(k0 + kk) * Nsrc + src]); if (gk) v *= gk[k0 + kk]; scr[kk * 33 + (lane & 31)] = v; }
;     asm volatile("s_waitcnt lgkmcnt(0)" ::: "memory");
;     const int c = lane & 7;
; #pragma unroll
;     for (int j = 0; j < 4; ++j) { const int n = (lane >> 3) + 8 * j; const LAS float* s = scr + (8 * c) * 33 + n;
;         u32x4 o; o.x = pk2(s[0 * 33], s[1 * 33]); o.y = pk2(s[2 * 33], s[3 * 33]); o.z = pk2(s[4 * 33], s[5 * 33]); o.w = pk2(s[6 * 33], s[7 * 33]);
;         *(u32x4*)(WT + (size_t)(n0 + n) * K + k0 + 8 * c) = o; }
;     asm volatile("s_waitcnt lgkmcnt(0)" ::: "memory");
	ds_write2_b32 v7, v100, v101 offset1:66
	s_waitcnt vmcnt(28)
	ds_write2_b32 v7, v102, v103 offset0:132 offset1:198
	v_add_u32_e32 v7, 0x840, v7
	s_waitcnt vmcnt(26)
	ds_write2_b32 v11, v104, v105 offset0:8 offset1:74
	s_waitcnt vmcnt(24)
	ds_write2_b32 v11, v106, v107 offset0:140 offset1:206
	v_add_u32_e32 v11, 0x400, v7
	s_waitcnt vmcnt(22)
	ds_write2_b32 v7, v108, v109 offset1:66
	s_waitcnt vmcnt(20)
	ds_write2_b32 v7, v110, v111 offset0:132 offset1:198
	v_add_u32_e32 v7, 0x840, v7
	s_waitcnt vmcnt(18)
	ds_write2_b32 v11, v112, v113 offset0:8 offset1:74
	s_waitcnt vmcnt(16)
	ds_write2_b32 v11, v114, v115 offset0:140 offset1:206
	v_add_u32_e32 v11, 0x400, v7
	s_waitcnt vmcnt(14)
	ds_write2_b32 v7, v116, v117 offset1:66
	s_waitcnt vmcnt(12)
	ds_write2_b32 v7, v118, v119 offset0:132 offset1:198
	v_add_u32_e32 v7, 0x840, v7
	s_waitcnt vmcnt(10)
	ds_write2_b32 v11, v120, v121 offset0:8 offset1:74
	s_waitcnt vmcnt(8)
	ds_write2_b32 v11, v122, v123 offset0:140 offset1:206
	v_add_u32_e32 v11, 0x400, v7
	s_waitcnt vmcnt(6)
	ds_write2_b32 v7, v124, v125 offset1:66
	s_waitcnt vmcnt(4)
	ds_write2_b32 v7, v126, v127 offset0:132 offset1:198
	v_add_u32_e32 v7, 0x840, v7
	s_waitcnt vmcnt(2)
	ds_write2_b32 v11, v128, v129 offset0:8 offset1:74
	s_waitcnt vmcnt(0)
	ds_write2_b32 v11, v130, v131 offset0:140 offset1:206
	s_and_b32 s7, s50, 0x7fc0
	s_add_i32 s8, s7, 0xffff8b80
	s_waitcnt lgkmcnt(0)
	s_lshl_b64 s[34:35], s[8:9], 1
	ds_read2_b32 v[14:15], v26 offset0:33 offset1:41
	ds_read2_b32 v[16:17], v26 offset1:8
	ds_read2_b32 v[18:19], v26 offset0:66 offset1:74
	ds_read2_b32 v[20:21], v26 offset0:99 offset1:107
	ds_read2_b32 v[22:23], v26 offset0:132 offset1:140
	ds_read2_b32 v[42:43], v26 offset0:165 offset1:173
	ds_read2_b32 v[44:45], v26 offset0:198 offset1:206
	ds_read2_b32 v[46:47], v26 offset0:231 offset1:239
	s_add_u32 s4, s4, s34
	s_addc_u32 s5, s5, s35
	v_mov_b32_e32 v7, v3
	v_lshl_add_u64 v[8:9], s[4:5], 0, v[6:7]
	v_or_b32_e32 v2, s6, v25
	v_lshl_add_u64 v[48:49], v[8:9], 0, s[12:13]
	v_lshlrev_b32_e32 v2, 9, v2
	s_waitcnt lgkmcnt(6)
	v_cvt_pk_bf16_f32 v8, v16, v14
	s_waitcnt lgkmcnt(4)
	v_cvt_pk_bf16_f32 v9, v18, v20
	s_waitcnt lgkmcnt(2)
	v_cvt_pk_bf16_f32 v10, v22, v42
	s_waitcnt lgkmcnt(0)
	v_cvt_pk_bf16_f32 v11, v44, v46
	v_lshl_add_u64 v[50:51], v[48:49], 0, v[2:3]
	global_store_dwordx4 v[50:51], v[8:11], off
	v_or_b32_e32 v2, s6, v27
	v_lshlrev_b32_e32 v2, 9, v2
	v_cvt_pk_bf16_f32 v8, v17, v15
	v_cvt_pk_bf16_f32 v9, v19, v21
	v_cvt_pk_bf16_f32 v10, v23, v43
	v_cvt_pk_bf16_f32 v11, v45, v47
	ds_read2_b32 v[16:17], v26 offset0:49 offset1:57
	ds_read2_b32 v[18:19], v26 offset0:16 offset1:24
	ds_read2_b32 v[20:21], v26 offset0:82 offset1:90
	ds_read2_b32 v[22:23], v26 offset0:115 offset1:123
	ds_read2_b32 v[42:43], v26 offset0:148 offset1:156
	ds_read2_b32 v[44:45], v26 offset0:181 offset1:189
	ds_read2_b32 v[46:47], v26 offset0:214 offset1:222
	ds_read2_b32 v[50:51], v26 offset0:247 offset1:255
	v_lshl_add_u64 v[14:15], v[48:49], 0, v[2:3]
	v_or_b32_e32 v2, s6, v28
	v_lshlrev_b32_e32 v2, 9, v2
	global_store_dwordx4 v[14:15], v[8:11], off
	v_lshl_add_u64 v[14:15], v[48:49], 0, v[2:3]
	v_or_b32_e32 v2, s6, v29
	s_waitcnt lgkmcnt(6)
	v_cvt_pk_bf16_f32 v8, v18, v16
	s_waitcnt lgkmcnt(4)
	v_cvt_pk_bf16_f32 v9, v20, v22
	s_waitcnt lgkmcnt(2)
	v_cvt_pk_bf16_f32 v10, v42, v44
	s_waitcnt lgkmcnt(0)
	v_cvt_pk_bf16_f32 v11, v46, v50
	v_lshlrev_b32_e32 v2, 9, v2
	global_store_dwordx4 v[14:15], v[8:11], off
	v_lshl_add_u64 v[14:15], v[48:49], 0, v[2:3]
	s_nop 0
	v_cvt_pk_bf16_f32 v8, v19, v17
	v_cvt_pk_bf16_f32 v9, v21, v23
	v_cvt_pk_bf16_f32 v10, v43, v45
	v_cvt_pk_bf16_f32 v11, v47, v51
	global_store_dwordx4 v[14:15], v[8:11], off
	s_waitcnt lgkmcnt(0)

; template <int KIND> __device__ __forceinline__ void tr_item(const float* __restrict__ W, int K, int Nsrc, const float* __restrict__ gk, bf16_t* WT, LAS float* scr, int item, int nblk, int lane) {
;     const int kb = item / nblk, nb = item - kb * nblk, k0 = 64 * kb, n0 = 32 * nb;
;     const int src = srcmap<KIND>(n0 + (lane & 31));
; #pragma unroll 8
;     for (int i = 0; i < 32; ++i) { const int kk = 2 * i + (lane >> 5); float v = 0.f; if (src >= 0) v = __builtin_nontemporal_load(&W[(size_t)(k0 + kk) * Nsrc + src]); if (gk) v *= gk[k0 + kk]; scr[kk * 33 + (lane & 31)] = v; }
.LBB0_43:
	v_add_u32_e32 v13, s7, v12
	v_add_u32_e32 v2, 0xffffab80, v13
	v_lshlrev_b64 v[10:11], 13, v[2:3]
	v_add_u32_e32 v2, 0xffffab82, v13
	v_lshlrev_b64 v[14:15], 13, v[2:3]
	v_add_u32_e32 v2, 0xffffab84, v13
	v_lshl_add_u64 v[10:11], v[8:9], 0, v[10:11]
	v_lshl_add_u64 v[14:15], v[8:9], 0, v[14:15]
	v_lshlrev_b64 v[16:17], 13, v[2:3]
	v_add_u32_e32 v2, 0xffffab86, v13
	global_load_dword v100, v[10:11], off nt
	global_load_dword v101, v[14:15], off nt
	v_lshlrev_b64 v[14:15], 13, v[2:3]
	v_add_u32_e32 v2, 0xffffab88, v13
	v_lshl_add_u64 v[10:11], v[8:9], 0, v[16:17]
	v_lshl_add_u64 v[14:15], v[8:9], 0, v[14:15]
	v_lshlrev_b64 v[16:17], 13, v[2:3]
	v_add_u32_e32 v2, 0xffffab8a, v13
	global_load_dword v102, v[10:11], off nt
	global_load_dword v103, v[14:15], off nt
	v_lshlrev_b64 v[14:15], 13, v[2:3]
	v_add_u32_e32 v2, 0xffffab8c, v13
	v_lshl_add_u64 v[10:11], v[8:9], 0, v[16:17]
	v_lshl_add_u64 v[14:15], v[8:9], 0, v[14:15]
	v_lshlrev_b64 v[16:17], 13, v[2:3]
	v_add_u32_e32 v2, 0xffffab8e, v13
	global_load_dword v104, v[10:11], off nt
	global_load_dword v105, v[14:15], off nt
	v_lshl_add_u64 v[10:11], v[8:9], 0, v[16:17]
	v_lshlrev_b64 v[14:15], 13, v[2:3]
	v_lshl_add_u64 v[14:15], v[8:9], 0, v[14:15]
	global_load_dword v106, v[10:11], off nt
	s_nop 0
	global_load_dword v107, v[14:15], off nt
	s_add_i32 s7, s7, 16
	v_add_u32_e32 v13, s7, v12
	v_add_u32_e32 v2, 0xffffab80, v13
	v_lshlrev_b64 v[10:11], 13, v[2:3]
	v_add_u32_e32 v2, 0xffffab82, v13
	v_lshlrev_b64 v[14:15], 13, v[2:3]
	v_add_u32_e32 v2, 0xffffab84, v13
	v_lshl_add_u64 v[10:11], v[8:9], 0, v[10:11]
	v_lshl_add_u64 v[14:15], v[8:9], 0, v[14:15]
	v_lshlrev_b64 v[16:17], 13, v[2:3]
	v_add_u32_e32 v2, 0xffffab86, v13
	global_load_dword v108, v[10:11], off nt
	global_load_dword v109, v[14:15], off nt
	v_lshlrev_b64 v[14:15], 13, v[2:3]
	v_add_u32_e32 v2, 0xffffab88, v13
	v_lshl_add_u64 v[10:11], v[8:9], 0, v[16:17]
	v_lshl_add_u64 v[14:15], v[8:9], 0, v[14:15]
	v_lshlrev_b64 v[16:17], 13, v[2:3]
	v_add_u32_e32 v2, 0xffffab8a, v13
	global_load_dword v110, v[10:11], off nt
	global_load_dword v111, v[14:15], off nt
	v_lshlrev_b64 v[14:15], 13, v[2:3]
	v_add_u32_e32 v2, 0xffffab8c, v13
	v_lshl_add_u64 v[10:11], v[8:9], 0, v[16:17]
	v_lshl_add_u64 v[14:15], v[8:9], 0, v[14:15]
	v_lshlrev_b64 v[16:17], 13, v[2:3]
	v_add_u32_e32 v2, 0xffffab8e, v13
	global_load_dword v112, v[10:11], off nt
	global_load_dword v113, v[14:15], off nt
	v_lshl_add_u64 v[10:11], v[8:9], 0, v[16:17]
	v_lshlrev_b64 v[14:15], 13, v[2:3]
	v_lshl_add_u64 v[14:15], v[8:9], 0, v[14:15]
	global_load_dword v114, v[10:11], off nt
	s_nop 0
	global_load_dword v115, v[14:15], off nt
	s_add_i32 s7, s7, 16
	v_add_u32_e32 v13, s7, v12
	v_add_u32_e32 v2, 0xffffab80, v13
	v_lshlrev_b64 v[10:11], 13, v[2:3]
	v_add_u32_e32 v2, 0xffffab82, v13
	v_lshlrev_b64 v[14:15], 13, v[2:3]
	v_add_u32_e32 v2, 0xffffab84, v13
	v_lshl_add_u64 v[10:11], v[8:9], 0, v[10:11]
	v_lshl_add_u64 v[14:15], v[8:9], 0, v[14:15]
	v_lshlrev_b64 v[16:17], 13, v[2:3]
	v_add_u32_e32 v2, 0xffffab86, v13
	global_load_dword v116, v[10:11], off nt
	global_load_dword v117, v[14:15], off nt
	v_lshlrev_b64 v[14:15], 13, v[2:3]
	v_add_u32_e32 v2, 0xffffab88, v13
	v_lshl_add_u64 v[10:11], v[8:9], 0, v[16:17]
	v_lshl_add_u64 v[14:15], v[8:9], 0, v[14:15]
	v_lshlrev_b64 v[16:17], 13, v[2:3]
	v_add_u32_e32 v2, 0xffffab8a, v13
	global_load_dword v118, v[10:11], off nt
	global_load_dword v119, v[14:15], off nt
	v_lshlrev_b64 v[14:15], 13, v[2:3]
	v_add_u32_e32 v2, 0xffffab8c, v13
	v_lshl_add_u64 v[10:11], v[8:9], 0, v[16:17]
	v_lshl_add_u64 v[14:15], v[8:9], 0, v[14:15]
	v_lshlrev_b64 v[16:17], 13, v[2:3]
	v_add_u32_e32 v2, 0xffffab8e, v13
	global_load_dword v120, v[10:11], off nt
	global_load_dword v121, v[14:15], off nt
	v_lshl_add_u64 v[10:11], v[8:9], 0, v[16:17]
	v_lshlrev_b64 v[14:15], 13, v[2:3]
	v_lshl_add_u64 v[14:15], v[8:9], 0, v[14:15]
	global_load_dword v122, v[10:11], off nt
	s_nop 0
	global_load_dword v123, v[14:15], off nt
	s_add_i32 s7, s7, 16
	v_add_u32_e32 v13, s7, v12
	v_add_u32_e32 v2, 0xffffab80, v13
	v_lshlrev_b64 v[10:11], 13, v[2:3]
	v_add_u32_e32 v2, 0xffffab82, v13
	v_lshlrev_b64 v[14:15], 13, v[2:3]
	v_add_u32_e32 v2, 0xffffab84, v13
	v_lshl_add_u64 v[10:11], v[8:9], 0, v[10:11]
	v_lshl_add_u64 v[14:15], v[8:9], 0, v[14:15]
	v_lshlrev_b64 v[16:17], 13, v[2:3]
	v_add_u32_e32 v2, 0xffffab86, v13
	global_load_dword v124, v[10:11], off nt
	global_load_dword v125, v[14:15], off nt
	v_lshlrev_b64 v[14:15], 13, v[2:3]
	v_add_u32_e32 v2, 0xffffab88, v13
	v_lshl_add_u64 v[10:11], v[8:9], 0, v[16:17]
	v_lshl_add_u64 v[14:15], v[8:9], 0, v[14:15]
	v_lshlrev_b64 v[16:17], 13, v[2:3]
	v_add_u32_e32 v2, 0xffffab8a, v13
	global_load_dword v126, v[10:11], off nt
	global_load_dword v127, v[14:15], off nt
	v_lshlrev_b64 v[14:15], 13, v[2:3]
	v_add_u32_e32 v2, 0xffffab8c, v13
	v_lshl_add_u64 v[10:11], v[8:9], 0, v[16:17]
	v_lshl_add_u64 v[14:15], v[8:9], 0, v[14:15]
	v_lshlrev_b64 v[16:17], 13, v[2:3]
	v_add_u32_e32 v2, 0xffffab8e, v13
	global_load_dword v128, v[10:11], off nt
	global_load_dword v129, v[14:15], off nt
	v_lshl_add_u64 v[10:11], v[8:9], 0, v[16:17]
	v_lshlrev_b64 v[14:15], 13, v[2:3]
	v_lshl_add_u64 v[14:15], v[8:9], 0, v[14:15]
	global_load_dword v130, v[10:11], off nt
	s_nop 0
	global_load_dword v131, v[14:15], off nt
	s_add_i32 s7, s7, 16
	v_add_u32_e32 v11, 0x400, v7
	s_waitcnt vmcnt(30)
; #define LAS __attribute__((address_space(3)))
; __device__ __forceinline__ unsigned pk2(float lo, float hi) { return pg8::cvt_pk_bf16(lo, hi); }
; template <int KIND> __device__ __forceinline__ void tr_item(const float* __restrict__ W, int K, int Nsrc, const float* __restrict__ gk, bf16_t* WT, LAS float* scr, int item, int nblk, int lane) {
;     ...
;     for (int i = 0; i < 32; ++i) { const int kk = 2 * i + (lane >> 5); float v = 0.f; if (src >= 0) v = __builtin_nontemporal_load(&W[(size_t)(k0 + kk) * Nsrc + src]); if (gk) v *= gk[k0 + kk]; scr[kk * 33 + (lane & 31)] = v; }
;     asm volatile("s_waitcnt lgkmcnt(0)" ::: "memory");
;     const int c = lane & 7;
; #pragma unroll
;     for (int j = 0; j < 4; ++j) { const int n = (lane >> 3) + 8 * j; const LAS float* s = scr + (8 * c) * 33 + n;
;         u32x4 o; o.x = pk2(s[0 * 33], s[1 * 33]); o.y = pk2(s[2 * 33], s[3 * 33]); o.z = pk2(s[4 * 33], s[5 * 33]); o.w = pk2(s[6 * 33], s[7 * 33]);
;         *(u32x4*)(WT + (size_t)(n0 + n) * K + k0 + 8 * c) = o; }
;     asm volatile("s_waitcnt lgkmcnt(0)" ::: "memory");
	ds_write2_b32 v7, v100, v101 offset1:66
	s_waitcnt vmcnt(28)
	ds_write2_b32 v7, v102, v103 offset0:132 offset1:198
	v_add_u32_e32 v7, 0x840, v7
	s_waitcnt vmcnt(26)
	ds_write2_b32 v11, v104, v105 offset0:8 offset1:74
	s_waitcnt vmcnt(24)
	ds_write2_b32 v11, v106, v107 offset0:140 offset1:206
	v_add_u32_e32 v11, 0x400, v7
	s_waitcnt vmcnt(22)
	ds_write2_b32 v7, v108, v109 offset1:66
	s_waitcnt vmcnt(20)
	ds_write2_b32 v7, v110, v111 offset0:132 offset1:198
	v_add_u32_e32 v7, 0x840, v7
	s_waitcnt vmcnt(18)
	ds_write2_b32 v11, v112, v113 offset0:8 offset1:74
	s_waitcnt vmcnt(16)
	ds_write2_b32 v11, v114, v115 offset0:140 offset1:206
	v_add_u32_e32 v11, 0x400, v7
	s_waitcnt vmcnt(14)
	ds_write2_b32 v7, v116, v117 offset1:66
	s_waitcnt vmcnt(12)
	ds_write2_b32 v7, v118, v119 offset0:132 offset1:198
	v_add_u32_e32 v7, 0x840, v7
	s_waitcnt vmcnt(10)
	ds_write2_b32 v11, v120, v121 offset0:8 offset1:74
	s_waitcnt vmcnt(8)
	ds_write2_b32 v11, v122, v123 offset0:140 offset1:206
	v_add_u32_e32 v11, 0x400, v7
	s_waitcnt vmcnt(6)
	ds_write2_b32 v7, v124, v125 offset1:66
	s_waitcnt vmcnt(4)
	ds_write2_b32 v7, v126, v127 offset0:132 offset1:198
	v_add_u32_e32 v7, 0x840, v7
	s_waitcnt vmcnt(2)
	ds_write2_b32 v11, v128, v129 offset0:8 offset1:74
	s_waitcnt vmcnt(0)
	ds_write2_b32 v11, v130, v131 offset0:140 offset1:206
	s_and_b32 s7, s50, 0x7fc0
	s_add_i32 s8, s7, 0xffffab80
	s_waitcnt lgkmcnt(0)
	s_lshl_b64 s[34:35], s[8:9], 1
	ds_read2_b32 v[12:13], v26 offset0:33 offset1:41
	ds_read2_b32 v[14:15], v26 offset1:8
	ds_read2_b32 v[16:17], v26 offset0:66 offset1:74
	ds_read2_b32 v[18:19], v26 offset0:99 offset1:107
	ds_read2_b32 v[20:21], v26 offset0:132 offset1:140
	ds_read2_b32 v[22:23], v26 offset0:165 offset1:173
	ds_read2_b32 v[42:43], v26 offset0:198 offset1:206
	ds_read2_b32 v[44:45], v26 offset0:231 offset1:239
	s_add_u32 s4, s4, s34
	s_addc_u32 s5, s5, s35
	v_mov_b32_e32 v7, v3
	v_lshl_add_u64 v[8:9], s[4:5], 0, v[6:7]
	v_or_b32_e32 v2, s6, v25
	v_lshl_add_u64 v[46:47], v[8:9], 0, s[14:15]
	v_lshlrev_b32_e32 v2, 14, v2
	s_waitcnt lgkmcnt(6)
	v_cvt_pk_bf16_f32 v8, v14, v12
	s_waitcnt lgkmcnt(4)
	v_cvt_pk_bf16_f32 v9, v16, v18
	s_waitcnt lgkmcnt(2)
	v_cvt_pk_bf16_f32 v10, v20, v22
	s_waitcnt lgkmcnt(0)
	v_cvt_pk_bf16_f32 v11, v42, v44
	v_lshl_add_u64 v[48:49], v[46:47], 0, v[2:3]
	global_store_dwordx4 v[48:49], v[8:11], off
	v_or_b32_e32 v2, s6, v27
	v_lshlrev_b32_e32 v2, 14, v2
	v_cvt_pk_bf16_f32 v8, v15, v13
	v_cvt_pk_bf16_f32 v9, v17, v19
	v_cvt_pk_bf16_f32 v10, v21, v23
	v_cvt_pk_bf16_f32 v11, v43, v45
	ds_read2_b32 v[14:15], v26 offset0:49 offset1:57
	ds_read2_b32 v[16:17], v26 offset0:16 offset1:24
	ds_read2_b32 v[18:19], v26 offset0:82 offset1:90
	ds_read2_b32 v[20:21], v26 offset0:115 offset1:123
	ds_read2_b32 v[22:23], v26 offset0:148 offset1:156
	ds_read2_b32 v[42:43], v26 offset0:181 offset1:189
	ds_read2_b32 v[44:45], v26 offset0:214 offset1:222
	ds_read2_b32 v[48:49], v26 offset0:247 offset1:255
	v_lshl_add_u64 v[12:13], v[46:47], 0, v[2:3]
	v_or_b32_e32 v2, s6, v28
	v_lshlrev_b32_e32 v2, 14, v2
	global_store_dwordx4 v[12:13], v[8:11], off
	v_lshl_add_u64 v[12:13], v[46:47], 0, v[2:3]
	v_or_b32_e32 v2, s6, v29
	s_waitcnt lgkmcnt(6)
	v_cvt_pk_bf16_f32 v8, v16, v14
	s_waitcnt lgkmcnt(4)
	v_cvt_pk_bf16_f32 v9, v18, v20
	s_waitcnt lgkmcnt(2)
	v_cvt_pk_bf16_f32 v10, v22, v42
	s_waitcnt lgkmcnt(0)
	v_cvt_pk_bf16_f32 v11, v44, v48
	v_lshlrev_b32_e32 v2, 14, v2
	global_store_dwordx4 v[12:13], v[8:11], off
	v_lshl_add_u64 v[12:13], v[46:47], 0, v[2:3]
	s_nop 0
	v_cvt_pk_bf16_f32 v8, v17, v15
	v_cvt_pk_bf16_f32 v9, v19, v21
	v_cvt_pk_bf16_f32 v10, v23, v43
	v_cvt_pk_bf16_f32 v11, v45, v49
	global_store_dwordx4 v[12:13], v[8:11], off
	s_waitcnt lgkmcnt(0)

; #define LAS __attribute__((address_space(3)))
; __device__ __forceinline__ unsigned pk2(float lo, float hi) { return pg8::cvt_pk_bf16(lo, hi); }
; template <int KIND> __device__ __forceinline__ void tr_item(const float* __restrict__ W, int K, int Nsrc, const float* __restrict__ gk, bf16_t* WT, LAS float* scr, int item, int nblk, int lane) {
;     ...
;     for (int i = 0; i < 32; ++i) { const int kk = 2 * i + (lane >> 5); float v = 0.f; if (src >= 0) v = __builtin_nontemporal_load(&W[(size_t)(k0 + kk) * Nsrc + src]); if (gk) v *= gk[k0 + kk]; scr[kk * 33 + (lane & 31)] = v; }
;     asm volatile("s_waitcnt lgkmcnt(0)" ::: "memory");
;     const int c = lane & 7;
; #pragma unroll
;     for (int j = 0; j < 4; ++j) { const int n = (lane >> 3) + 8 * j; const LAS float* s = scr + (8 * c) * 33 + n;
;         u32x4 o; o.x = pk2(s[0 * 33], s[1 * 33]); o.y = pk2(s[2 * 33], s[3 * 33]); o.z = pk2(s[4 * 33], s[5 * 33]); o.w = pk2(s[6 * 33], s[7 * 33]);
;         *(u32x4*)(WT + (size_t)(n0 + n) * K + k0 + 8 * c) = o; }
;     asm volatile("s_waitcnt lgkmcnt(0)" ::: "memory");
.LBB0_48:
	v_lshl_add_u64 v[42:43], v[22:23], 0, s[6:7]
	v_lshl_add_u64 v[44:45], v[20:21], 0, s[6:7]
	v_lshl_add_u64 v[46:47], v[18:19], 0, s[6:7]
	v_lshl_add_u64 v[48:49], v[16:17], 0, s[6:7]
	v_lshl_add_u64 v[50:51], v[14:15], 0, s[6:7]
	v_lshl_add_u64 v[52:53], v[12:13], 0, s[6:7]
	v_lshl_add_u64 v[54:55], v[10:11], 0, s[6:7]
	v_lshl_add_u64 v[56:57], v[8:9], 0, s[6:7]
	global_load_dword v100, v[42:43], off nt
	global_load_dword v101, v[44:45], off nt
	s_nop 0
	global_load_dword v102, v[46:47], off nt
	global_load_dword v103, v[48:49], off nt
	global_load_dword v104, v[50:51], off nt
	global_load_dword v105, v[52:53], off nt
	s_nop 0
	global_load_dword v106, v[54:55], off nt
	global_load_dword v107, v[56:57], off nt
	s_add_u32 s6, s6, 0x80000
	s_addc_u32 s7, s7, 0
	v_lshl_add_u64 v[42:43], v[22:23], 0, s[6:7]
	v_lshl_add_u64 v[44:45], v[20:21], 0, s[6:7]
	v_lshl_add_u64 v[46:47], v[18:19], 0, s[6:7]
	v_lshl_add_u64 v[48:49], v[16:17], 0, s[6:7]
	v_lshl_add_u64 v[50:51], v[14:15], 0, s[6:7]
	v_lshl_add_u64 v[52:53], v[12:13], 0, s[6:7]
	v_lshl_add_u64 v[54:55], v[10:11], 0, s[6:7]
	v_lshl_add_u64 v[56:57], v[8:9], 0, s[6:7]
	global_load_dword v108, v[42:43], off nt
	global_load_dword v109, v[44:45], off nt
	s_nop 0
	global_load_dword v110, v[46:47], off nt
	global_load_dword v111, v[48:49], off nt
	global_load_dword v112, v[50:51], off nt
	global_load_dword v113, v[52:53], off nt
	s_nop 0
	global_load_dword v114, v[54:55], off nt
	global_load_dword v115, v[56:57], off nt
	s_add_u32 s6, s6, 0x80000
	s_addc_u32 s7, s7, 0
	v_lshl_add_u64 v[42:43], v[22:23], 0, s[6:7]
	v_lshl_add_u64 v[44:45], v[20:21], 0, s[6:7]
	v_lshl_add_u64 v[46:47], v[18:19], 0, s[6:7]
	v_lshl_add_u64 v[48:49], v[16:17], 0, s[6:7]
	v_lshl_add_u64 v[50:51], v[14:15], 0, s[6:7]
	v_lshl_add_u64 v[52:53], v[12:13], 0, s[6:7]
	v_lshl_add_u64 v[54:55], v[10:11], 0, s[6:7]
	v_lshl_add_u64 v[56:57], v[8:9], 0, s[6:7]
	global_load_dword v116, v[42:43], off nt
	global_load_dword v117, v[44:45], off nt
	s_nop 0
	global_load_dword v118, v[46:47], off nt
	global_load_dword v119, v[48:49], off nt
	global_load_dword v120, v[50:51], off nt
	global_load_dword v121, v[52:53], off nt
	s_nop 0
	global_load_dword v122, v[54:55], off nt
	global_load_dword v123, v[56:57], off nt
	s_add_u32 s6, s6, 0x80000
	s_addc_u32 s7, s7, 0
	v_lshl_add_u64 v[42:43], v[22:23], 0, s[6:7]
	v_lshl_add_u64 v[44:45], v[20:21], 0, s[6:7]
	v_lshl_add_u64 v[46:47], v[18:19], 0, s[6:7]
	v_lshl_add_u64 v[48:49], v[16:17], 0, s[6:7]
	v_lshl_add_u64 v[50:51], v[14:15], 0, s[6:7]
	v_lshl_add_u64 v[52:53], v[12:13], 0, s[6:7]
	v_lshl_add_u64 v[54:55], v[10:11], 0, s[6:7]
	v_lshl_add_u64 v[56:57], v[8:9], 0, s[6:7]
	global_load_dword v124, v[42:43], off nt
	global_load_dword v125, v[44:45], off nt
	s_nop 0
	global_load_dword v126, v[46:47], off nt
	global_load_dword v127, v[48:49], off nt
	global_load_dword v128, v[50:51], off nt
	global_load_dword v129, v[52:53], off nt
	s_nop 0
	global_load_dword v130, v[54:55], off nt
	global_load_dword v131, v[56:57], off nt
	s_add_u32 s6, s6, 0x80000
	s_addc_u32 s7, s7, 0
	v_add_u32_e32 v48, 0x400, v2
	s_waitcnt vmcnt(30)
	ds_write2_b32 v2, v100, v101 offset1:66
	s_waitcnt vmcnt(28)
	ds_write2_b32 v2, v102, v103 offset0:132 offset1:198
	s_waitcnt vmcnt(26)
	ds_write2_b32 v48, v104, v105 offset0:8 offset1:74
	s_waitcnt vmcnt(24)
	ds_write2_b32 v48, v106, v107 offset0:140 offset1:206
	v_add_u32_e32 v2, 0x840, v2
	v_add_u32_e32 v48, 0x400, v2
	s_waitcnt vmcnt(22)
	ds_write2_b32 v2, v108, v109 offset1:66
	s_waitcnt vmcnt(20)
	ds_write2_b32 v2, v110, v111 offset0:132 offset1:198
	s_waitcnt vmcnt(18)
	ds_write2_b32 v48, v112, v113 offset0:8 offset1:74
	s_waitcnt vmcnt(16)
	ds_write2_b32 v48, v114, v115 offset0:140 offset1:206
	v_add_u32_e32 v2, 0x840, v2
	v_add_u32_e32 v48, 0x400, v2
	s_waitcnt vmcnt(14)
	ds_write2_b32 v2, v116, v117 offset1:66
	s_waitcnt vmcnt(12)
	ds_write2_b32 v2, v118, v119 offset0:132 offset1:198
	s_waitcnt vmcnt(10)
	ds_write2_b32 v48, v120, v121 offset0:8 offset1:74
	s_waitcnt vmcnt(8)
	ds_write2_b32 v48, v122, v123 offset0:140 offset1:206
	v_add_u32_e32 v2, 0x840, v2
	v_add_u32_e32 v48, 0x400, v2
	s_waitcnt vmcnt(6)
	ds_write2_b32 v2, v124, v125 offset1:66
	s_waitcnt vmcnt(4)
	ds_write2_b32 v2, v126, v127 offset0:132 offset1:198
	s_waitcnt vmcnt(2)
	ds_write2_b32 v48, v128, v129 offset0:8 offset1:74
	s_waitcnt vmcnt(0)
	ds_write2_b32 v48, v130, v131 offset0:140 offset1:206
	v_add_u32_e32 v2, 0x840, v2
	s_add_i32 s6, s50, 0xffffcb80
	s_lshl_b32 s7, s6, 5
	s_waitcnt lgkmcnt(0)
	s_lshr_b32 s6, s6, 1
	s_and_b32 s7, s7, 0x1fe0
	s_and_b32 s6, s6, 0x7fffff80
	ds_read2_b32 v[12:13], v26 offset0:33 offset1:41
	ds_read2_b32 v[14:15], v26 offset1:8
	ds_read2_b32 v[16:17], v26 offset0:66 offset1:74
	ds_read2_b32 v[18:19], v26 offset0:99 offset1:107
	ds_read2_b32 v[20:21], v26 offset0:132 offset1:140
	ds_read2_b32 v[22:23], v26 offset0:165 offset1:173
	ds_read2_b32 v[42:43], v26 offset0:198 offset1:206
	ds_read2_b32 v[44:45], v26 offset0:231 offset1:239
	s_add_u32 s4, s4, s6
	s_addc_u32 s5, s5, 0
	v_mov_b32_e32 v7, v3
	v_lshl_add_u64 v[8:9], s[4:5], 0, v[6:7]
	v_or_b32_e32 v2, s7, v25
	v_lshl_add_u64 v[46:47], v[8:9], 0, s[16:17]
	v_lshlrev_b32_e32 v2, 12, v2
	s_waitcnt lgkmcnt(6)
	v_cvt_pk_bf16_f32 v8, v14, v12
	s_waitcnt lgkmcnt(4)
	v_cvt_pk_bf16_f32 v9, v16, v18
	s_waitcnt lgkmcnt(2)
	v_cvt_pk_bf16_f32 v10, v20, v22
	s_waitcnt lgkmcnt(0)
	v_cvt_pk_bf16_f32 v11, v42, v44
	v_lshl_add_u64 v[48:49], v[46:47], 0, v[2:3]
	global_store_dwordx4 v[48:49], v[8:11], off
	v_or_b32_e32 v2, s7, v27
	v_lshlrev_b32_e32 v2, 12, v2
	v_cvt_pk_bf16_f32 v8, v15, v13
	v_cvt_pk_bf16_f32 v9, v17, v19
	v_cvt_pk_bf16_f32 v10, v21, v23
	v_cvt_pk_bf16_f32 v11, v43, v45
	ds_read2_b32 v[14:15], v26 offset0:49 offset1:57
	ds_read2_b32 v[16:17], v26 offset0:16 offset1:24
	ds_read2_b32 v[18:19], v26 offset0:82 offset1:90
	ds_read2_b32 v[20:21], v26 offset0:115 offset1:123
	ds_read2_b32 v[22:23], v26 offset0:148 offset1:156
	ds_read2_b32 v[42:43], v26 offset0:181 offset1:189
	ds_read2_b32 v[44:45], v26 offset0:214 offset1:222
	ds_read2_b32 v[48:49], v26 offset0:247 offset1:255
	v_lshl_add_u64 v[12:13], v[46:47], 0, v[2:3]
	v_or_b32_e32 v2, s7, v28
	v_lshlrev_b32_e32 v2, 12, v2
	global_store_dwordx4 v[12:13], v[8:11], off
	v_lshl_add_u64 v[12:13], v[46:47], 0, v[2:3]
	v_or_b32_e32 v2, s7, v29
	s_waitcnt lgkmcnt(6)
	v_cvt_pk_bf16_f32 v8, v16, v14
	s_waitcnt lgkmcnt(4)
	v_cvt_pk_bf16_f32 v9, v18, v20
	s_waitcnt lgkmcnt(2)
	v_cvt_pk_bf16_f32 v10, v22, v42
	s_waitcnt lgkmcnt(0)
	v_cvt_pk_bf16_f32 v11, v44, v48
	v_lshlrev_b32_e32 v2, 12, v2
	global_store_dwordx4 v[12:13], v[8:11], off
	v_lshl_add_u64 v[12:13], v[46:47], 0, v[2:3]
	s_nop 0
	v_cvt_pk_bf16_f32 v8, v17, v15
	v_cvt_pk_bf16_f32 v9, v19, v21
	v_cvt_pk_bf16_f32 v10, v23, v43
	v_cvt_pk_bf16_f32 v11, v45, v49
	global_store_dwordx4 v[12:13], v[8:11], off
	s_waitcnt lgkmcnt(0)

; template <int KIND> __device__ __forceinline__ void tr_item(const float* __restrict__ W, int K, int Nsrc, const float* __restrict__ gk, bf16_t* WT, LAS float* scr, int item, int nblk, int lane) {
;     const int kb = item / nblk, nb = item - kb * nblk, k0 = 64 * kb, n0 = 32 * nb;
;     const int src = srcmap<KIND>(n0 + (lane & 31));
; #pragma unroll 8
;     for (int i = 0; i < 32; ++i) { const int kk = 2 * i + (lane >> 5); float v = 0.f; if (src >= 0) v = __builtin_nontemporal_load(&W[(size_t)(k0 + kk) * Nsrc + src]); if (gk) v *= gk[k0 + kk]; scr[kk * 33 + (lane & 31)] = v; }
.LBB0_53:
	v_add_u32_e32 v16, s7, v40
	v_add_u32_e32 v2, 0xffffd380, v16
	v_lshlrev_b64 v[10:11], 13, v[2:3]
	v_add_u32_e32 v2, 0xffffd382, v16
	v_lshlrev_b64 v[12:13], 13, v[2:3]
	v_add_u32_e32 v2, 0xffffd384, v16
	v_lshl_add_u64 v[10:11], v[8:9], 0, v[10:11]
	v_lshl_add_u64 v[12:13], v[8:9], 0, v[12:13]
	v_lshlrev_b64 v[14:15], 13, v[2:3]
	v_add_u32_e32 v2, 0xffffd386, v16
	global_load_dword v100, v[10:11], off nt
	global_load_dword v101, v[12:13], off nt
	v_lshlrev_b64 v[12:13], 13, v[2:3]
	v_add_u32_e32 v2, 0xffffd388, v16
	v_lshl_add_u64 v[10:11], v[8:9], 0, v[14:15]
	v_lshl_add_u64 v[12:13], v[8:9], 0, v[12:13]
	v_lshlrev_b64 v[14:15], 13, v[2:3]
	v_add_u32_e32 v2, 0xffffd38a, v16
	global_load_dword v102, v[10:11], off nt
	global_load_dword v103, v[12:13], off nt
	v_lshlrev_b64 v[12:13], 13, v[2:3]
	v_add_u32_e32 v2, 0xffffd38c, v16
	v_lshl_add_u64 v[10:11], v[8:9], 0, v[14:15]
	v_lshl_add_u64 v[12:13], v[8:9], 0, v[12:13]
	v_lshlrev_b64 v[14:15], 13, v[2:3]
	v_add_u32_e32 v2, 0xffffd38e, v16
	global_load_dword v104, v[10:11], off nt
	global_load_dword v105, v[12:13], off nt
	v_lshl_add_u64 v[10:11], v[8:9], 0, v[14:15]
	v_lshlrev_b64 v[12:13], 13, v[2:3]
	v_lshl_add_u64 v[12:13], v[8:9], 0, v[12:13]
	global_load_dword v106, v[10:11], off nt
	s_nop 0
	global_load_dword v107, v[12:13], off nt
	s_add_i32 s7, s7, 16
	v_add_u32_e32 v16, s7, v40
	v_add_u32_e32 v2, 0xffffd380, v16
	v_lshlrev_b64 v[10:11], 13, v[2:3]
	v_add_u32_e32 v2, 0xffffd382, v16
	v_lshlrev_b64 v[12:13], 13, v[2:3]
	v_add_u32_e32 v2, 0xffffd384, v16
	v_lshl_add_u64 v[10:11], v[8:9], 0, v[10:11]
	v_lshl_add_u64 v[12:13], v[8:9], 0, v[12:13]
	v_lshlrev_b64 v[14:15], 13, v[2:3]
	v_add_u32_e32 v2, 0xffffd386, v16
	global_load_dword v108, v[10:11], off nt
	global_load_dword v109, v[12:13], off nt
	v_lshlrev_b64 v[12:13], 13, v[2:3]
	v_add_u32_e32 v2, 0xffffd388, v16
	v_lshl_add_u64 v[10:11], v[8:9], 0, v[14:15]
	v_lshl_add_u64 v[12:13], v[8:9], 0, v[12:13]
	v_lshlrev_b64 v[14:15], 13, v[2:3]
	v_add_u32_e32 v2, 0xffffd38a, v16
	global_load_dword v110, v[10:11], off nt
	global_load_dword v111, v[12:13], off nt
	v_lshlrev_b64 v[12:13], 13, v[2:3]
	v_add_u32_e32 v2, 0xffffd38c, v16
	v_lshl_add_u64 v[10:11], v[8:9], 0, v[14:15]
	v_lshl_add_u64 v[12:13], v[8:9], 0, v[12:13]
	v_lshlrev_b64 v[14:15], 13, v[2:3]
	v_add_u32_e32 v2, 0xffffd38e, v16
	global_load_dword v112, v[10:11], off nt
	global_load_dword v113, v[12:13], off nt
	v_lshl_add_u64 v[10:11], v[8:9], 0, v[14:15]
	v_lshlrev_b64 v[12:13], 13, v[2:3]
	v_lshl_add_u64 v[12:13], v[8:9], 0, v[12:13]
	global_load_dword v114, v[10:11], off nt
	s_nop 0
	global_load_dword v115, v[12:13], off nt
	s_add_i32 s7, s7, 16
	v_add_u32_e32 v16, s7, v40
	v_add_u32_e32 v2, 0xffffd380, v16
	v_lshlrev_b64 v[10:11], 13, v[2:3]
	v_add_u32_e32 v2, 0xffffd382, v16
	v_lshlrev_b64 v[12:13], 13, v[2:3]
	v_add_u32_e32 v2, 0xffffd384, v16
	v_lshl_add_u64 v[10:11], v[8:9], 0, v[10:11]
	v_lshl_add_u64 v[12:13], v[8:9], 0, v[12:13]
	v_lshlrev_b64 v[14:15], 13, v[2:3]
	v_add_u32_e32 v2, 0xffffd386, v16
	global_load_dword v116, v[10:11], off nt
	global_load_dword v117, v[12:13], off nt
	v_lshlrev_b64 v[12:13], 13, v[2:3]
	v_add_u32_e32 v2, 0xffffd388, v16
	v_lshl_add_u64 v[10:11], v[8:9], 0, v[14:15]
	v_lshl_add_u64 v[12:13], v[8:9], 0, v[12:13]
	v_lshlrev_b64 v[14:15], 13, v[2:3]
	v_add_u32_e32 v2, 0xffffd38a, v16
	global_load_dword v118, v[10:11], off nt
	global_load_dword v119, v[12:13], off nt
	v_lshlrev_b64 v[12:13], 13, v[2:3]
	v_add_u32_e32 v2, 0xffffd38c, v16
	v_lshl_add_u64 v[10:11], v[8:9], 0, v[14:15]
	v_lshl_add_u64 v[12:13], v[8:9], 0, v[12:13]
	v_lshlrev_b64 v[14:15], 13, v[2:3]
	v_add_u32_e32 v2, 0xffffd38e, v16
	global_load_dword v120, v[10:11], off nt
	global_load_dword v121, v[12:13], off nt
	v_lshl_add_u64 v[10:11], v[8:9], 0, v[14:15]
	v_lshlrev_b64 v[12:13], 13, v[2:3]
	v_lshl_add_u64 v[12:13], v[8:9], 0, v[12:13]
	global_load_dword v122, v[10:11], off nt
	s_nop 0
	global_load_dword v123, v[12:13], off nt
	s_add_i32 s7, s7, 16
	v_add_u32_e32 v16, s7, v40
	v_add_u32_e32 v2, 0xffffd380, v16
	v_lshlrev_b64 v[10:11], 13, v[2:3]
	v_add_u32_e32 v2, 0xffffd382, v16
	v_lshlrev_b64 v[12:13], 13, v[2:3]
	v_add_u32_e32 v2, 0xffffd384, v16
	v_lshl_add_u64 v[10:11], v[8:9], 0, v[10:11]
	v_lshl_add_u64 v[12:13], v[8:9], 0, v[12:13]
	v_lshlrev_b64 v[14:15], 13, v[2:3]
	v_add_u32_e32 v2, 0xffffd386, v16
	global_load_dword v124, v[10:11], off nt
	global_load_dword v125, v[12:13], off nt
	v_lshlrev_b64 v[12:13], 13, v[2:3]
	v_add_u32_e32 v2, 0xffffd388, v16
	v_lshl_add_u64 v[10:11], v[8:9], 0, v[14:15]
	v_lshl_add_u64 v[12:13], v[8:9], 0, v[12:13]
	v_lshlrev_b64 v[14:15], 13, v[2:3]
	v_add_u32_e32 v2, 0xffffd38a, v16
	global_load_dword v126, v[10:11], off nt
	global_load_dword v127, v[12:13], off nt
	v_lshlrev_b64 v[12:13], 13, v[2:3]
	v_add_u32_e32 v2, 0xffffd38c, v16
	v_lshl_add_u64 v[10:11], v[8:9], 0, v[14:15]
	v_lshl_add_u64 v[12:13], v[8:9], 0, v[12:13]
	v_lshlrev_b64 v[14:15], 13, v[2:3]
	v_add_u32_e32 v2, 0xffffd38e, v16
	global_load_dword v128, v[10:11], off nt
	global_load_dword v129, v[12:13], off nt
	v_lshl_add_u64 v[10:11], v[8:9], 0, v[14:15]
	v_lshlrev_b64 v[12:13], 13, v[2:3]
	v_lshl_add_u64 v[12:13], v[8:9], 0, v[12:13]
	global_load_dword v130, v[10:11], off nt
	s_nop 0
	global_load_dword v131, v[12:13], off nt
	s_add_i32 s7, s7, 16
	v_add_u32_e32 v11, 0x400, v7
	s_waitcnt vmcnt(30)
; #define LAS __attribute__((address_space(3)))
; __device__ __forceinline__ unsigned pk2(float lo, float hi) { return pg8::cvt_pk_bf16(lo, hi); }
; template <int KIND> __device__ __forceinline__ void tr_item(const float* __restrict__ W, int K, int Nsrc, const float* __restrict__ gk, bf16_t* WT, LAS float* scr, int item, int nblk, int lane) {
;     ...
;     for (int i = 0; i < 32; ++i) { const int kk = 2 * i + (lane >> 5); float v = 0.f; if (src >= 0) v = __builtin_nontemporal_load(&W[(size_t)(k0 + kk) * Nsrc + src]); if (gk) v *= gk[k0 + kk]; scr[kk * 33 + (lane & 31)] = v; }
;     asm volatile("s_waitcnt lgkmcnt(0)" ::: "memory");
;     const int c = lane & 7;
; #pragma unroll
;     for (int j = 0; j < 4; ++j) { const int n = (lane >> 3) + 8 * j; const LAS float* s = scr + (8 * c) * 33 + n;
;         u32x4 o; o.x = pk2(s[0 * 33], s[1 * 33]); o.y = pk2(s[2 * 33], s[3 * 33]); o.z = pk2(s[4 * 33], s[5 * 33]); o.w = pk2(s[6 * 33], s[7 * 33]);
;         *(u32x4*)(WT + (size_t)(n0 + n) * K + k0 + 8 * c) = o; }
;     asm volatile("s_waitcnt lgkmcnt(0)" ::: "memory");
	ds_write2_b32 v7, v100, v101 offset1:66
	s_waitcnt vmcnt(28)
	ds_write2_b32 v7, v102, v103 offset0:132 offset1:198
	v_add_u32_e32 v7, 0x840, v7
	s_waitcnt vmcnt(26)
	ds_write2_b32 v11, v104, v105 offset0:8 offset1:74
	s_waitcnt vmcnt(24)
	ds_write2_b32 v11, v106, v107 offset0:140 offset1:206
	v_add_u32_e32 v11, 0x400, v7
	s_waitcnt vmcnt(22)
	ds_write2_b32 v7, v108, v109 offset1:66
	s_waitcnt vmcnt(20)
	ds_write2_b32 v7, v110, v111 offset0:132 offset1:198
	v_add_u32_e32 v7, 0x840, v7
	s_waitcnt vmcnt(18)
	ds_write2_b32 v11, v112, v113 offset0:8 offset1:74
	s_waitcnt vmcnt(16)
	ds_write2_b32 v11, v114, v115 offset0:140 offset1:206
	v_add_u32_e32 v11, 0x400, v7
	s_waitcnt vmcnt(14)
	ds_write2_b32 v7, v116, v117 offset1:66
	s_waitcnt vmcnt(12)
	ds_write2_b32 v7, v118, v119 offset0:132 offset1:198
	v_add_u32_e32 v7, 0x840, v7
	s_waitcnt vmcnt(10)
	ds_write2_b32 v11, v120, v121 offset0:8 offset1:74
	s_waitcnt vmcnt(8)
	ds_write2_b32 v11, v122, v123 offset0:140 offset1:206
	v_add_u32_e32 v11, 0x400, v7
	s_waitcnt vmcnt(6)
	ds_write2_b32 v7, v124, v125 offset1:66
	s_waitcnt vmcnt(4)
	ds_write2_b32 v7, v126, v127 offset0:132 offset1:198
	v_add_u32_e32 v7, 0x840, v7
	s_waitcnt vmcnt(2)
	ds_write2_b32 v11, v128, v129 offset0:8 offset1:74
	s_waitcnt vmcnt(0)
	ds_write2_b32 v11, v130, v131 offset0:140 offset1:206
	s_add_i32 s8, s30, 0xffffd380
	s_waitcnt lgkmcnt(0)
	s_lshl_b64 s[34:35], s[8:9], 1
	ds_read2_b32 v[12:13], v26 offset0:33 offset1:41
	ds_read2_b32 v[14:15], v26 offset1:8
	ds_read2_b32 v[16:17], v26 offset0:66 offset1:74
	ds_read2_b32 v[18:19], v26 offset0:99 offset1:107
	ds_read2_b32 v[20:21], v26 offset0:132 offset1:140
	ds_read2_b32 v[22:23], v26 offset0:165 offset1:173
	ds_read2_b32 v[42:43], v26 offset0:198 offset1:206
	ds_read2_b32 v[44:45], v26 offset0:231 offset1:239
	s_add_u32 s4, s4, s34
	s_addc_u32 s5, s5, s35
	v_mov_b32_e32 v7, v3
	v_lshl_add_u64 v[8:9], s[4:5], 0, v[6:7]
	v_or_b32_e32 v2, s6, v25
	v_lshl_add_u64 v[46:47], v[8:9], 0, s[18:19]
	v_lshlrev_b32_e32 v2, 12, v2
	s_waitcnt lgkmcnt(6)
	v_cvt_pk_bf16_f32 v8, v14, v12
	s_waitcnt lgkmcnt(4)
	v_cvt_pk_bf16_f32 v9, v16, v18
	s_waitcnt lgkmcnt(2)
	v_cvt_pk_bf16_f32 v10, v20, v22
	s_waitcnt lgkmcnt(0)
	v_cvt_pk_bf16_f32 v11, v42, v44
	v_lshl_add_u64 v[48:49], v[46:47], 0, v[2:3]
	global_store_dwordx4 v[48:49], v[8:11], off
	v_or_b32_e32 v2, s6, v27
	v_lshlrev_b32_e32 v2, 12, v2
	v_cvt_pk_bf16_f32 v8, v15, v13
	v_cvt_pk_bf16_f32 v9, v17, v19
	v_cvt_pk_bf16_f32 v10, v21, v23
	v_cvt_pk_bf16_f32 v11, v43, v45
	ds_read2_b32 v[14:15], v26 offset0:49 offset1:57
	ds_read2_b32 v[16:17], v26 offset0:16 offset1:24
	ds_read2_b32 v[18:19], v26 offset0:82 offset1:90
	ds_read2_b32 v[20:21], v26 offset0:115 offset1:123
	ds_read2_b32 v[22:23], v26 offset0:148 offset1:156
	ds_read2_b32 v[42:43], v26 offset0:181 offset1:189
	ds_read2_b32 v[44:45], v26 offset0:214 offset1:222
	ds_read2_b32 v[48:49], v26 offset0:247 offset1:255
	v_lshl_add_u64 v[12:13], v[46:47], 0, v[2:3]
	v_or_b32_e32 v2, s6, v28
	v_lshlrev_b32_e32 v2, 12, v2
	global_store_dwordx4 v[12:13], v[8:11], off
	v_lshl_add_u64 v[12:13], v[46:47], 0, v[2:3]
	v_or_b32_e32 v2, s6, v29
	s_waitcnt lgkmcnt(6)
	v_cvt_pk_bf16_f32 v8, v16, v14
	s_waitcnt lgkmcnt(4)
	v_cvt_pk_bf16_f32 v9, v18, v20
	s_waitcnt lgkmcnt(2)
	v_cvt_pk_bf16_f32 v10, v22, v42
	s_waitcnt lgkmcnt(0)
	v_cvt_pk_bf16_f32 v11, v44, v48
	v_lshlrev_b32_e32 v2, 12, v2
	global_store_dwordx4 v[12:13], v[8:11], off
	v_lshl_add_u64 v[12:13], v[46:47], 0, v[2:3]
	s_nop 0
	v_cvt_pk_bf16_f32 v8, v17, v15
	v_cvt_pk_bf16_f32 v9, v19, v21
	v_cvt_pk_bf16_f32 v10, v23, v43
	v_cvt_pk_bf16_f32 v11, v45, v49
	global_store_dwordx4 v[12:13], v[8:11], off
	s_waitcnt lgkmcnt(0)

; template <int KIND> __device__ __forceinline__ void tr_item(const float* __restrict__ W, int K, int Nsrc, const float* __restrict__ gk, bf16_t* WT, LAS float* scr, int item, int nblk, int lane) {
;     const int kb = item / nblk, nb = item - kb * nblk, k0 = 64 * kb, n0 = 32 * nb;
;     const int src = srcmap<KIND>(n0 + (lane & 31));
; #pragma unroll 8
;     for (int i = 0; i < 32; ++i) { const int kk = 2 * i + (lane >> 5); float v = 0.f; if (src >= 0) v = __builtin_nontemporal_load(&W[(size_t)(k0 + kk) * Nsrc + src]); if (gk) v *= gk[k0 + kk]; scr[kk * 33 + (lane & 31)] = v; }
.LBB0_58:
	v_add_u32_e32 v16, s7, v40
	v_add_u32_e32 v2, 0xffffd780, v16
	v_lshlrev_b64 v[10:11], 13, v[2:3]
	v_add_u32_e32 v2, 0xffffd782, v16
	v_lshlrev_b64 v[12:13], 13, v[2:3]
	v_add_u32_e32 v2, 0xffffd784, v16
	v_lshl_add_u64 v[10:11], v[8:9], 0, v[10:11]
	v_lshl_add_u64 v[12:13], v[8:9], 0, v[12:13]
	v_lshlrev_b64 v[14:15], 13, v[2:3]
	v_add_u32_e32 v2, 0xffffd786, v16
	global_load_dword v100, v[10:11], off nt
	global_load_dword v101, v[12:13], off nt
	v_lshlrev_b64 v[12:13], 13, v[2:3]
	v_add_u32_e32 v2, 0xffffd788, v16
	v_lshl_add_u64 v[10:11], v[8:9], 0, v[14:15]
	v_lshl_add_u64 v[12:13], v[8:9], 0, v[12:13]
	v_lshlrev_b64 v[14:15], 13, v[2:3]
	v_add_u32_e32 v2, 0xffffd78a, v16
	global_load_dword v102, v[10:11], off nt
	global_load_dword v103, v[12:13], off nt
	v_lshlrev_b64 v[12:13], 13, v[2:3]
	v_add_u32_e32 v2, 0xffffd78c, v16
	v_lshl_add_u64 v[10:11], v[8:9], 0, v[14:15]
	v_lshl_add_u64 v[12:13], v[8:9], 0, v[12:13]
	v_lshlrev_b64 v[14:15], 13, v[2:3]
	v_add_u32_e32 v2, 0xffffd78e, v16
	global_load_dword v104, v[10:11], off nt
	global_load_dword v105, v[12:13], off nt
	v_lshl_add_u64 v[10:11], v[8:9], 0, v[14:15]
	v_lshlrev_b64 v[12:13], 13, v[2:3]
	v_lshl_add_u64 v[12:13], v[8:9], 0, v[12:13]
	global_load_dword v106, v[10:11], off nt
	s_nop 0
	global_load_dword v107, v[12:13], off nt
	s_add_i32 s7, s7, 16
	v_add_u32_e32 v16, s7, v40
	v_add_u32_e32 v2, 0xffffd780, v16
	v_lshlrev_b64 v[10:11], 13, v[2:3]
	v_add_u32_e32 v2, 0xffffd782, v16
	v_lshlrev_b64 v[12:13], 13, v[2:3]
	v_add_u32_e32 v2, 0xffffd784, v16
	v_lshl_add_u64 v[10:11], v[8:9], 0, v[10:11]
	v_lshl_add_u64 v[12:13], v[8:9], 0, v[12:13]
	v_lshlrev_b64 v[14:15], 13, v[2:3]
	v_add_u32_e32 v2, 0xffffd786, v16
	global_load_dword v108, v[10:11], off nt
	global_load_dword v109, v[12:13], off nt
	v_lshlrev_b64 v[12:13], 13, v[2:3]
	v_add_u32_e32 v2, 0xffffd788, v16
	v_lshl_add_u64 v[10:11], v[8:9], 0, v[14:15]
	v_lshl_add_u64 v[12:13], v[8:9], 0, v[12:13]
	v_lshlrev_b64 v[14:15], 13, v[2:3]
	v_add_u32_e32 v2, 0xffffd78a, v16
	global_load_dword v110, v[10:11], off nt
	global_load_dword v111, v[12:13], off nt
	v_lshlrev_b64 v[12:13], 13, v[2:3]
	v_add_u32_e32 v2, 0xffffd78c, v16
	v_lshl_add_u64 v[10:11], v[8:9], 0, v[14:15]
	v_lshl_add_u64 v[12:13], v[8:9], 0, v[12:13]
	v_lshlrev_b64 v[14:15], 13, v[2:3]
	v_add_u32_e32 v2, 0xffffd78e, v16
	global_load_dword v112, v[10:11], off nt
	global_load_dword v113, v[12:13], off nt
	v_lshl_add_u64 v[10:11], v[8:9], 0, v[14:15]
	v_lshlrev_b64 v[12:13], 13, v[2:3]
	v_lshl_add_u64 v[12:13], v[8:9], 0, v[12:13]
	global_load_dword v114, v[10:11], off nt
	s_nop 0
	global_load_dword v115, v[12:13], off nt
	s_add_i32 s7, s7, 16
	v_add_u32_e32 v16, s7, v40
	v_add_u32_e32 v2, 0xffffd780, v16
	v_lshlrev_b64 v[10:11], 13, v[2:3]
	v_add_u32_e32 v2, 0xffffd782, v16
	v_lshlrev_b64 v[12:13], 13, v[2:3]
	v_add_u32_e32 v2, 0xffffd784, v16
	v_lshl_add_u64 v[10:11], v[8:9], 0, v[10:11]
	v_lshl_add_u64 v[12:13], v[8:9], 0, v[12:13]
	v_lshlrev_b64 v[14:15], 13, v[2:3]
	v_add_u32_e32 v2, 0xffffd786, v16
	global_load_dword v116, v[10:11], off nt
	global_load_dword v117, v[12:13], off nt
	v_lshlrev_b64 v[12:13], 13, v[2:3]
	v_add_u32_e32 v2, 0xffffd788, v16
	v_lshl_add_u64 v[10:11], v[8:9], 0, v[14:15]
	v_lshl_add_u64 v[12:13], v[8:9], 0, v[12:13]
	v_lshlrev_b64 v[14:15], 13, v[2:3]
	v_add_u32_e32 v2, 0xffffd78a, v16
	global_load_dword v118, v[10:11], off nt
	global_load_dword v119, v[12:13], off nt
	v_lshlrev_b64 v[12:13], 13, v[2:3]
	v_add_u32_e32 v2, 0xffffd78c, v16
	v_lshl_add_u64 v[10:11], v[8:9], 0, v[14:15]
	v_lshl_add_u64 v[12:13], v[8:9], 0, v[12:13]
	v_lshlrev_b64 v[14:15], 13, v[2:3]
	v_add_u32_e32 v2, 0xffffd78e, v16
	global_load_dword v120, v[10:11], off nt
	global_load_dword v121, v[12:13], off nt
	v_lshl_add_u64 v[10:11], v[8:9], 0, v[14:15]
	v_lshlrev_b64 v[12:13], 13, v[2:3]
	v_lshl_add_u64 v[12:13], v[8:9], 0, v[12:13]
	global_load_dword v122, v[10:11], off nt
	s_nop 0
	global_load_dword v123, v[12:13], off nt
	s_add_i32 s7, s7, 16
	v_add_u32_e32 v16, s7, v40
	v_add_u32_e32 v2, 0xffffd780, v16
	v_lshlrev_b64 v[10:11], 13, v[2:3]
	v_add_u32_e32 v2, 0xffffd782, v16
	v_lshlrev_b64 v[12:13], 13, v[2:3]
	v_add_u32_e32 v2, 0xffffd784, v16
	v_lshl_add_u64 v[10:11], v[8:9], 0, v[10:11]
	v_lshl_add_u64 v[12:13], v[8:9], 0, v[12:13]
	v_lshlrev_b64 v[14:15], 13, v[2:3]
	v_add_u32_e32 v2, 0xffffd786, v16
	global_load_dword v124, v[10:11], off nt
	global_load_dword v125, v[12:13], off nt
	v_lshlrev_b64 v[12:13], 13, v[2:3]
	v_add_u32_e32 v2, 0xffffd788, v16
	v_lshl_add_u64 v[10:11], v[8:9], 0, v[14:15]
	v_lshl_add_u64 v[12:13], v[8:9], 0, v[12:13]
	v_lshlrev_b64 v[14:15], 13, v[2:3]
	v_add_u32_e32 v2, 0xffffd78a, v16
	global_load_dword v126, v[10:11], off nt
	global_load_dword v127, v[12:13], off nt
	v_lshlrev_b64 v[12:13], 13, v[2:3]
	v_add_u32_e32 v2, 0xffffd78c, v16
	v_lshl_add_u64 v[10:11], v[8:9], 0, v[14:15]
	v_lshl_add_u64 v[12:13], v[8:9], 0, v[12:13]
	v_lshlrev_b64 v[14:15], 13, v[2:3]
	v_add_u32_e32 v2, 0xffffd78e, v16
	global_load_dword v128, v[10:11], off nt
	global_load_dword v129, v[12:13], off nt
	v_lshl_add_u64 v[10:11], v[8:9], 0, v[14:15]
	v_lshlrev_b64 v[12:13], 13, v[2:3]
	v_lshl_add_u64 v[12:13], v[8:9], 0, v[12:13]
	global_load_dword v130, v[10:11], off nt
	s_nop 0
	global_load_dword v131, v[12:13], off nt
	s_add_i32 s7, s7, 16
	v_add_u32_e32 v11, 0x400, v7
	s_waitcnt vmcnt(30)
; #define LAS __attribute__((address_space(3)))
; __device__ __forceinline__ unsigned pk2(float lo, float hi) { return pg8::cvt_pk_bf16(lo, hi); }
; template <int KIND> __device__ __forceinline__ void tr_item(const float* __restrict__ W, int K, int Nsrc, const float* __restrict__ gk, bf16_t* WT, LAS float* scr, int item, int nblk, int lane) {
;     ...
;     for (int i = 0; i < 32; ++i) { const int kk = 2 * i + (lane >> 5); float v = 0.f; if (src >= 0) v = __builtin_nontemporal_load(&W[(size_t)(k0 + kk) * Nsrc + src]); if (gk) v *= gk[k0 + kk]; scr[kk * 33 + (lane & 31)] = v; }
;     asm volatile("s_waitcnt lgkmcnt(0)" ::: "memory");
;     const int c = lane & 7;
; #pragma unroll
;     for (int j = 0; j < 4; ++j) { const int n = (lane >> 3) + 8 * j; const LAS float* s = scr + (8 * c) * 33 + n;
;         u32x4 o; o.x = pk2(s[0 * 33], s[1 * 33]); o.y = pk2(s[2 * 33], s[3 * 33]); o.z = pk2(s[4 * 33], s[5 * 33]); o.w = pk2(s[6 * 33], s[7 * 33]);
;         *(u32x4*)(WT + (size_t)(n0 + n) * K + k0 + 8 * c) = o; }
;     asm volatile("s_waitcnt lgkmcnt(0)" ::: "memory");
	ds_write2_b32 v7, v100, v101 offset1:66
	s_waitcnt vmcnt(28)
	ds_write2_b32 v7, v102, v103 offset0:132 offset1:198
	v_add_u32_e32 v7, 0x840, v7
	s_waitcnt vmcnt(26)
	ds_write2_b32 v11, v104, v105 offset0:8 offset1:74
	s_waitcnt vmcnt(24)
	ds_write2_b32 v11, v106, v107 offset0:140 offset1:206
	v_add_u32_e32 v11, 0x400, v7
	s_waitcnt vmcnt(22)
	ds_write2_b32 v7, v108, v109 offset1:66
	s_waitcnt vmcnt(20)
	ds_write2_b32 v7, v110, v111 offset0:132 offset1:198
	v_add_u32_e32 v7, 0x840, v7
	s_waitcnt vmcnt(18)
	ds_write2_b32 v11, v112, v113 offset0:8 offset1:74
	s_waitcnt vmcnt(16)
	ds_write2_b32 v11, v114, v115 offset0:140 offset1:206
	v_add_u32_e32 v11, 0x400, v7
	s_waitcnt vmcnt(14)
	ds_write2_b32 v7, v116, v117 offset1:66
	s_waitcnt vmcnt(12)
	ds_write2_b32 v7, v118, v119 offset0:132 offset1:198
	v_add_u32_e32 v7, 0x840, v7
	s_waitcnt vmcnt(10)
	ds_write2_b32 v11, v120, v121 offset0:8 offset1:74
	s_waitcnt vmcnt(8)
	ds_write2_b32 v11, v122, v123 offset0:140 offset1:206
	v_add_u32_e32 v11, 0x400, v7
	s_waitcnt vmcnt(6)
	ds_write2_b32 v7, v124, v125 offset1:66
	s_waitcnt vmcnt(4)
	ds_write2_b32 v7, v126, v127 offset0:132 offset1:198
	v_add_u32_e32 v7, 0x840, v7
	s_waitcnt vmcnt(2)
	ds_write2_b32 v11, v128, v129 offset0:8 offset1:74
	s_waitcnt vmcnt(0)
	ds_write2_b32 v11, v130, v131 offset0:140 offset1:206
	s_add_i32 s8, s30, 0xffffd780
	s_waitcnt lgkmcnt(0)
	s_lshl_b64 s[34:35], s[8:9], 1
	ds_read2_b32 v[12:13], v26 offset0:33 offset1:41
	ds_read2_b32 v[14:15], v26 offset1:8
	ds_read2_b32 v[16:17], v26 offset0:66 offset1:74
	ds_read2_b32 v[18:19], v26 offset0:99 offset1:107
	ds_read2_b32 v[20:21], v26 offset0:132 offset1:140
	ds_read2_b32 v[22:23], v26 offset0:165 offset1:173
	ds_read2_b32 v[42:43], v26 offset0:198 offset1:206
	ds_read2_b32 v[44:45], v26 offset0:231 offset1:239
	s_add_u32 s4, s4, s34
	s_addc_u32 s5, s5, s35
	v_mov_b32_e32 v7, v3
	v_lshl_add_u64 v[8:9], s[4:5], 0, v[6:7]
	v_or_b32_e32 v2, s6, v25
	v_lshl_add_u64 v[46:47], v[8:9], 0, s[20:21]
	v_lshlrev_b32_e32 v2, 11, v2
	s_waitcnt lgkmcnt(6)
	v_cvt_pk_bf16_f32 v8, v14, v12
	s_waitcnt lgkmcnt(4)
	v_cvt_pk_bf16_f32 v9, v16, v18
	s_waitcnt lgkmcnt(2)
	v_cvt_pk_bf16_f32 v10, v20, v22
	s_waitcnt lgkmcnt(0)
	v_cvt_pk_bf16_f32 v11, v42, v44
	v_lshl_add_u64 v[48:49], v[46:47], 0, v[2:3]
	global_store_dwordx4 v[48:49], v[8:11], off
	v_or_b32_e32 v2, s6, v27
	v_lshlrev_b32_e32 v2, 11, v2
	v_cvt_pk_bf16_f32 v8, v15, v13
	v_cvt_pk_bf16_f32 v9, v17, v19
	v_cvt_pk_bf16_f32 v10, v21, v23
	v_cvt_pk_bf16_f32 v11, v43, v45
	ds_read2_b32 v[14:15], v26 offset0:49 offset1:57
	ds_read2_b32 v[16:17], v26 offset0:16 offset1:24
	ds_read2_b32 v[18:19], v26 offset0:82 offset1:90
	ds_read2_b32 v[20:21], v26 offset0:115 offset1:123
	ds_read2_b32 v[22:23], v26 offset0:148 offset1:156
	ds_read2_b32 v[42:43], v26 offset0:181 offset1:189
	ds_read2_b32 v[44:45], v26 offset0:214 offset1:222
	ds_read2_b32 v[48:49], v26 offset0:247 offset1:255
	v_lshl_add_u64 v[12:13], v[46:47], 0, v[2:3]
	v_or_b32_e32 v2, s6, v28
	v_lshlrev_b32_e32 v2, 11, v2
	global_store_dwordx4 v[12:13], v[8:11], off
	v_lshl_add_u64 v[12:13], v[46:47], 0, v[2:3]
	v_or_b32_e32 v2, s6, v29
	s_waitcnt lgkmcnt(6)
	v_cvt_pk_bf16_f32 v8, v16, v14
	s_waitcnt lgkmcnt(4)
	v_cvt_pk_bf16_f32 v9, v18, v20
	s_waitcnt lgkmcnt(2)
	v_cvt_pk_bf16_f32 v10, v22, v42
	s_waitcnt lgkmcnt(0)
	v_cvt_pk_bf16_f32 v11, v44, v48
	v_lshlrev_b32_e32 v2, 11, v2
	global_store_dwordx4 v[12:13], v[8:11], off
	v_lshl_add_u64 v[12:13], v[46:47], 0, v[2:3]
	s_nop 0
	v_cvt_pk_bf16_f32 v8, v17, v15
	v_cvt_pk_bf16_f32 v9, v19, v21
	v_cvt_pk_bf16_f32 v10, v23, v43
	v_cvt_pk_bf16_f32 v11, v45, v49
	global_store_dwordx4 v[12:13], v[8:11], off
	s_waitcnt lgkmcnt(0)

; template <int KIND> __device__ __forceinline__ void tr_item(const float* __restrict__ W, int K, int Nsrc, const float* __restrict__ gk, bf16_t* WT, LAS float* scr, int item, int nblk, int lane) {
;     const int kb = item / nblk, nb = item - kb * nblk, k0 = 64 * kb, n0 = 32 * nb;
;     const int src = srcmap<KIND>(n0 + (lane & 31));
; #pragma unroll 8
;     for (int i = 0; i < 32; ++i) { const int kk = 2 * i + (lane >> 5); float v = 0.f; if (src >= 0) v = __builtin_nontemporal_load(&W[(size_t)(k0 + kk) * Nsrc + src]); if (gk) v *= gk[k0 + kk]; scr[kk * 33 + (lane & 31)] = v; }
.LBB0_63:
	v_add_u32_e32 v16, s7, v40
	v_add_u32_e32 v2, 0xffffdb80, v16
	v_lshlrev_b64 v[10:11], 13, v[2:3]
	v_add_u32_e32 v2, 0xffffdb82, v16
	v_lshlrev_b64 v[12:13], 13, v[2:3]
	v_add_u32_e32 v2, 0xffffdb84, v16
	v_lshl_add_u64 v[10:11], v[8:9], 0, v[10:11]
	v_lshl_add_u64 v[12:13], v[8:9], 0, v[12:13]
	v_lshlrev_b64 v[14:15], 13, v[2:3]
	v_add_u32_e32 v2, 0xffffdb86, v16
	global_load_dword v100, v[10:11], off nt
	global_load_dword v101, v[12:13], off nt
	v_lshlrev_b64 v[12:13], 13, v[2:3]
	v_add_u32_e32 v2, 0xffffdb88, v16
	v_lshl_add_u64 v[10:11], v[8:9], 0, v[14:15]
	v_lshl_add_u64 v[12:13], v[8:9], 0, v[12:13]
	v_lshlrev_b64 v[14:15], 13, v[2:3]
	v_add_u32_e32 v2, 0xffffdb8a, v16
	global_load_dword v102, v[10:11], off nt
	global_load_dword v103, v[12:13], off nt
	v_lshlrev_b64 v[12:13], 13, v[2:3]
	v_add_u32_e32 v2, 0xffffdb8c, v16
	v_lshl_add_u64 v[10:11], v[8:9], 0, v[14:15]
	v_lshl_add_u64 v[12:13], v[8:9], 0, v[12:13]
	v_lshlrev_b64 v[14:15], 13, v[2:3]
	v_add_u32_e32 v2, 0xffffdb8e, v16
	global_load_dword v104, v[10:11], off nt
	global_load_dword v105, v[12:13], off nt
	v_lshl_add_u64 v[10:11], v[8:9], 0, v[14:15]
	v_lshlrev_b64 v[12:13], 13, v[2:3]
	v_lshl_add_u64 v[12:13], v[8:9], 0, v[12:13]
	global_load_dword v106, v[10:11], off nt
	s_nop 0
	global_load_dword v107, v[12:13], off nt
	s_add_i32 s7, s7, 16
	v_add_u32_e32 v16, s7, v40
	v_add_u32_e32 v2, 0xffffdb80, v16
	v_lshlrev_b64 v[10:11], 13, v[2:3]
	v_add_u32_e32 v2, 0xffffdb82, v16
	v_lshlrev_b64 v[12:13], 13, v[2:3]
	v_add_u32_e32 v2, 0xffffdb84, v16
	v_lshl_add_u64 v[10:11], v[8:9], 0, v[10:11]
	v_lshl_add_u64 v[12:13], v[8:9], 0, v[12:13]
	v_lshlrev_b64 v[14:15], 13, v[2:3]
	v_add_u32_e32 v2, 0xffffdb86, v16
	global_load_dword v108, v[10:11], off nt
	global_load_dword v109, v[12:13], off nt
	v_lshlrev_b64 v[12:13], 13, v[2:3]
	v_add_u32_e32 v2, 0xffffdb88, v16
	v_lshl_add_u64 v[10:11], v[8:9], 0, v[14:15]
	v_lshl_add_u64 v[12:13], v[8:9], 0, v[12:13]
	v_lshlrev_b64 v[14:15], 13, v[2:3]
	v_add_u32_e32 v2, 0xffffdb8a, v16
	global_load_dword v110, v[10:11], off nt
	global_load_dword v111, v[12:13], off nt
	v_lshlrev_b64 v[12:13], 13, v[2:3]
	v_add_u32_e32 v2, 0xffffdb8c, v16
	v_lshl_add_u64 v[10:11], v[8:9], 0, v[14:15]
	v_lshl_add_u64 v[12:13], v[8:9], 0, v[12:13]
	v_lshlrev_b64 v[14:15], 13, v[2:3]
	v_add_u32_e32 v2, 0xffffdb8e, v16
	global_load_dword v112, v[10:11], off nt
	global_load_dword v113, v[12:13], off nt
	v_lshl_add_u64 v[10:11], v[8:9], 0, v[14:15]
	v_lshlrev_b64 v[12:13], 13, v[2:3]
	v_lshl_add_u64 v[12:13], v[8:9], 0, v[12:13]
	global_load_dword v114, v[10:11], off nt
	s_nop 0
	global_load_dword v115, v[12:13], off nt
	s_add_i32 s7, s7, 16
	v_add_u32_e32 v16, s7, v40
	v_add_u32_e32 v2, 0xffffdb80, v16
	v_lshlrev_b64 v[10:11], 13, v[2:3]
	v_add_u32_e32 v2, 0xffffdb82, v16
	v_lshlrev_b64 v[12:13], 13, v[2:3]
	v_add_u32_e32 v2, 0xffffdb84, v16
	v_lshl_add_u64 v[10:11], v[8:9], 0, v[10:11]
	v_lshl_add_u64 v[12:13], v[8:9], 0, v[12:13]
	v_lshlrev_b64 v[14:15], 13, v[2:3]
	v_add_u32_e32 v2, 0xffffdb86, v16
	global_load_dword v116, v[10:11], off nt
	global_load_dword v117, v[12:13], off nt
	v_lshlrev_b64 v[12:13], 13, v[2:3]
	v_add_u32_e32 v2, 0xffffdb88, v16
	v_lshl_add_u64 v[10:11], v[8:9], 0, v[14:15]
	v_lshl_add_u64 v[12:13], v[8:9], 0, v[12:13]
	v_lshlrev_b64 v[14:15], 13, v[2:3]
	v_add_u32_e32 v2, 0xffffdb8a, v16
	global_load_dword v118, v[10:11], off nt
	global_load_dword v119, v[12:13], off nt
	v_lshlrev_b64 v[12:13], 13, v[2:3]
	v_add_u32_e32 v2, 0xffffdb8c, v16
	v_lshl_add_u64 v[10:11], v[8:9], 0, v[14:15]
	v_lshl_add_u64 v[12:13], v[8:9], 0, v[12:13]
	v_lshlrev_b64 v[14:15], 13, v[2:3]
	v_add_u32_e32 v2, 0xffffdb8e, v16
	global_load_dword v120, v[10:11], off nt
	global_load_dword v121, v[12:13], off nt
	v_lshl_add_u64 v[10:11], v[8:9], 0, v[14:15]
	v_lshlrev_b64 v[12:13], 13, v[2:3]
	v_lshl_add_u64 v[12:13], v[8:9], 0, v[12:13]
	global_load_dword v122, v[10:11], off nt
	s_nop 0
	global_load_dword v123, v[12:13], off nt
	s_add_i32 s7, s7, 16
	v_add_u32_e32 v16, s7, v40
	v_add_u32_e32 v2, 0xffffdb80, v16
	v_lshlrev_b64 v[10:11], 13, v[2:3]
	v_add_u32_e32 v2, 0xffffdb82, v16
	v_lshlrev_b64 v[12:13], 13, v[2:3]
	v_add_u32_e32 v2, 0xffffdb84, v16
	v_lshl_add_u64 v[10:11], v[8:9], 0, v[10:11]
	v_lshl_add_u64 v[12:13], v[8:9], 0, v[12:13]
	v_lshlrev_b64 v[14:15], 13, v[2:3]
	v_add_u32_e32 v2, 0xffffdb86, v16
	global_load_dword v124, v[10:11], off nt
	global_load_dword v125, v[12:13], off nt
	v_lshlrev_b64 v[12:13], 13, v[2:3]
	v_add_u32_e32 v2, 0xffffdb88, v16
	v_lshl_add_u64 v[10:11], v[8:9], 0, v[14:15]
	v_lshl_add_u64 v[12:13], v[8:9], 0, v[12:13]
	v_lshlrev_b64 v[14:15], 13, v[2:3]
	v_add_u32_e32 v2, 0xffffdb8a, v16
	global_load_dword v126, v[10:11], off nt
	global_load_dword v127, v[12:13], off nt
	v_lshlrev_b64 v[12:13], 13, v[2:3]
	v_add_u32_e32 v2, 0xffffdb8c, v16
	v_lshl_add_u64 v[10:11], v[8:9], 0, v[14:15]
	v_lshl_add_u64 v[12:13], v[8:9], 0, v[12:13]
	v_lshlrev_b64 v[14:15], 13, v[2:3]
	v_add_u32_e32 v2, 0xffffdb8e, v16
	global_load_dword v128, v[10:11], off nt
	global_load_dword v129, v[12:13], off nt
	v_lshl_add_u64 v[10:11], v[8:9], 0, v[14:15]
	v_lshlrev_b64 v[12:13], 13, v[2:3]
	v_lshl_add_u64 v[12:13], v[8:9], 0, v[12:13]
	global_load_dword v130, v[10:11], off nt
	s_nop 0
	global_load_dword v131, v[12:13], off nt
	s_add_i32 s7, s7, 16
	v_add_u32_e32 v11, 0x400, v7
	s_waitcnt vmcnt(30)
; #define LAS __attribute__((address_space(3)))
; __device__ __forceinline__ unsigned pk2(float lo, float hi) { return pg8::cvt_pk_bf16(lo, hi); }
; template <int KIND> __device__ __forceinline__ void tr_item(const float* __restrict__ W, int K, int Nsrc, const float* __restrict__ gk, bf16_t* WT, LAS float* scr, int item, int nblk, int lane) {
;     ...
;     for (int i = 0; i < 32; ++i) { const int kk = 2 * i + (lane >> 5); float v = 0.f; if (src >= 0) v = __builtin_nontemporal_load(&W[(size_t)(k0 + kk) * Nsrc + src]); if (gk) v *= gk[k0 + kk]; scr[kk * 33 + (lane & 31)] = v; }
;     asm volatile("s_waitcnt lgkmcnt(0)" ::: "memory");
;     const int c = lane & 7;
; #pragma unroll
;     for (int j = 0; j < 4; ++j) { const int n = (lane >> 3) + 8 * j; const LAS float* s = scr + (8 * c) * 33 + n;
;         u32x4 o; o.x = pk2(s[0 * 33], s[1 * 33]); o.y = pk2(s[2 * 33], s[3 * 33]); o.z = pk2(s[4 * 33], s[5 * 33]); o.w = pk2(s[6 * 33], s[7 * 33]);
;         *(u32x4*)(WT + (size_t)(n0 + n) * K + k0 + 8 * c) = o; }
;     asm volatile("s_waitcnt lgkmcnt(0)" ::: "memory");
	ds_write2_b32 v7, v100, v101 offset1:66
	s_waitcnt vmcnt(28)
	ds_write2_b32 v7, v102, v103 offset0:132 offset1:198
	v_add_u32_e32 v7, 0x840, v7
	s_waitcnt vmcnt(26)
	ds_write2_b32 v11, v104, v105 offset0:8 offset1:74
	s_waitcnt vmcnt(24)
	ds_write2_b32 v11, v106, v107 offset0:140 offset1:206
	v_add_u32_e32 v11, 0x400, v7
	s_waitcnt vmcnt(22)
	ds_write2_b32 v7, v108, v109 offset1:66
	s_waitcnt vmcnt(20)
	ds_write2_b32 v7, v110, v111 offset0:132 offset1:198
	v_add_u32_e32 v7, 0x840, v7
	s_waitcnt vmcnt(18)
	ds_write2_b32 v11, v112, v113 offset0:8 offset1:74
	s_waitcnt vmcnt(16)
	ds_write2_b32 v11, v114, v115 offset0:140 offset1:206
	v_add_u32_e32 v11, 0x400, v7
	s_waitcnt vmcnt(14)
	ds_write2_b32 v7, v116, v117 offset1:66
	s_waitcnt vmcnt(12)
	ds_write2_b32 v7, v118, v119 offset0:132 offset1:198
	v_add_u32_e32 v7, 0x840, v7
	s_waitcnt vmcnt(10)
	ds_write2_b32 v11, v120, v121 offset0:8 offset1:74
	s_waitcnt vmcnt(8)
	ds_write2_b32 v11, v122, v123 offset0:140 offset1:206
	v_add_u32_e32 v11, 0x400, v7
	s_waitcnt vmcnt(6)
	ds_write2_b32 v7, v124, v125 offset1:66
	s_waitcnt vmcnt(4)
	ds_write2_b32 v7, v126, v127 offset0:132 offset1:198
	v_add_u32_e32 v7, 0x840, v7
	s_waitcnt vmcnt(2)
	ds_write2_b32 v11, v128, v129 offset0:8 offset1:74
	s_waitcnt vmcnt(0)
	ds_write2_b32 v11, v130, v131 offset0:140 offset1:206
	s_add_i32 s8, s30, 0xffffdb80
	s_waitcnt lgkmcnt(0)
	s_lshl_b64 s[34:35], s[8:9], 1
	ds_read2_b32 v[12:13], v26 offset0:33 offset1:41
	ds_read2_b32 v[14:15], v26 offset1:8
	ds_read2_b32 v[16:17], v26 offset0:66 offset1:74
	ds_read2_b32 v[18:19], v26 offset0:99 offset1:107
	ds_read2_b32 v[20:21], v26 offset0:132 offset1:140
	ds_read2_b32 v[22:23], v26 offset0:165 offset1:173
	ds_read2_b32 v[42:43], v26 offset0:198 offset1:206
	ds_read2_b32 v[44:45], v26 offset0:231 offset1:239
	s_add_u32 s4, s4, s34
	s_addc_u32 s5, s5, s35
	v_mov_b32_e32 v7, v3
	v_lshl_add_u64 v[8:9], s[4:5], 0, v[6:7]
	v_or_b32_e32 v2, s6, v25
	v_lshl_add_u64 v[46:47], v[8:9], 0, s[22:23]
	v_lshlrev_b32_e32 v2, 11, v2
	s_waitcnt lgkmcnt(6)
	v_cvt_pk_bf16_f32 v8, v14, v12
	s_waitcnt lgkmcnt(4)
	v_cvt_pk_bf16_f32 v9, v16, v18
	s_waitcnt lgkmcnt(2)
	v_cvt_pk_bf16_f32 v10, v20, v22
	s_waitcnt lgkmcnt(0)
	v_cvt_pk_bf16_f32 v11, v42, v44
	v_lshl_add_u64 v[48:49], v[46:47], 0, v[2:3]
	global_store_dwordx4 v[48:49], v[8:11], off
	v_or_b32_e32 v2, s6, v27
	v_lshlrev_b32_e32 v2, 11, v2
	v_cvt_pk_bf16_f32 v8, v15, v13
	v_cvt_pk_bf16_f32 v9, v17, v19
	v_cvt_pk_bf16_f32 v10, v21, v23
	v_cvt_pk_bf16_f32 v11, v43, v45
	ds_read2_b32 v[14:15], v26 offset0:49 offset1:57
	ds_read2_b32 v[16:17], v26 offset0:16 offset1:24
	ds_read2_b32 v[18:19], v26 offset0:82 offset1:90
	ds_read2_b32 v[20:21], v26 offset0:115 offset1:123
	ds_read2_b32 v[22:23], v26 offset0:148 offset1:156
	ds_read2_b32 v[42:43], v26 offset0:181 offset1:189
	ds_read2_b32 v[44:45], v26 offset0:214 offset1:222
	ds_read2_b32 v[48:49], v26 offset0:247 offset1:255
	v_lshl_add_u64 v[12:13], v[46:47], 0, v[2:3]
	v_or_b32_e32 v2, s6, v28
	v_lshlrev_b32_e32 v2, 11, v2
	global_store_dwordx4 v[12:13], v[8:11], off
	v_lshl_add_u64 v[12:13], v[46:47], 0, v[2:3]
	v_or_b32_e32 v2, s6, v29
	s_waitcnt lgkmcnt(6)
	v_cvt_pk_bf16_f32 v8, v16, v14
	s_waitcnt lgkmcnt(4)
	v_cvt_pk_bf16_f32 v9, v18, v20
	s_waitcnt lgkmcnt(2)
	v_cvt_pk_bf16_f32 v10, v22, v42
	s_waitcnt lgkmcnt(0)
	v_cvt_pk_bf16_f32 v11, v44, v48
	v_lshlrev_b32_e32 v2, 11, v2
	global_store_dwordx4 v[12:13], v[8:11], off
	v_lshl_add_u64 v[12:13], v[46:47], 0, v[2:3]
	s_nop 0
	v_cvt_pk_bf16_f32 v8, v17, v15
	v_cvt_pk_bf16_f32 v9, v19, v21
	v_cvt_pk_bf16_f32 v10, v23, v43
	v_cvt_pk_bf16_f32 v11, v45, v49
	global_store_dwordx4 v[12:13], v[8:11], off
	s_waitcnt lgkmcnt(0)

; __device__ __forceinline__ void store8(bf16_t* dst, const float* v) { u32x4 w; w.x = pk2(v[0], v[1]); w.y = pk2(v[2], v[3]); w.z = pk2(v[4], v[5]); w.w = pk2(v[6], v[7]); *(u32x4*)dst = w; }
;     __device__ __forceinline__ void operator()(const pg8::f32x4 (&acc)[2][2][4][2], const pg8::Unit& u, int wr, int wc, int fr, int fq) const {
;     ...
;                 const int row = u.pm * 256 + ai * 128 + wr * 64 + m * 16 + fr;
;                 const int bb = row >> 13, ss = row & 8191;
;                 float ssq = 0.f;
;                 float rs = 1.f;
;                 if constexpr (KIND == EK_Q || KIND == EK_KV) rs = __builtin_amdgcn_rsqf(a.ssq0[row] * (1.f / 512.f) + EPS);
;     ...
;                         const int c = pn * 256 + cl, h = c / 192, dd = c - h * 192;
; #pragma unroll
;                         for (int j = 0; j < 8; ++j) v[j] *= rs;
;                         if (dd >= 128) {
;                             const int p = a.pos[row];
; #pragma unroll
;                             for (int j = 0; j < 4; ++j) rope_pair(v[2 * j], v[2 * j + 1], p, ((dd - 128) >> 1) + j);
;                         }
;                         store8(a.o0 + ((size_t)((bb * NH + h) * SEQ + ss)) * 192 + dd, v);
.LBB0_570:
	s_lshl_b32 s23, s30, 8
	s_add_i32 s23, s23, s50
	v_or_b32_e32 v148, s23, v153
	v_lshlrev_b32_e32 v192, 2, v148
	global_load_dword v193, v192, s[8:9]
	global_load_dword v194, v192, s[8:9] offset:64
	global_load_dword v195, v192, s[8:9] offset:128
	global_load_dword v196, v192, s[8:9] offset:192
	global_load_dword v197, v192, s[8:9] offset:512
	global_load_dword v198, v192, s[8:9] offset:576
	global_load_dword v199, v192, s[8:9] offset:640
	global_load_dword v200, v192, s[8:9] offset:704
	global_load_dword v201, v192, s[10:11]
	global_load_dword v202, v192, s[10:11] offset:64
	global_load_dword v203, v192, s[10:11] offset:128
	global_load_dword v204, v192, s[10:11] offset:192
	global_load_dword v205, v192, s[10:11] offset:512
	global_load_dword v206, v192, s[10:11] offset:576
	global_load_dword v207, v192, s[10:11] offset:640
	global_load_dword v208, v192, s[10:11] offset:704
	v_ashrrev_i32_e32 v149, 31, v148
	v_lshl_add_u64 v[150:151], v[148:149], 2, s[8:9]
	s_nop 0
	v_lshl_or_b32 v152, s6, 8, v157
	v_mul_hi_i32 v144, v152, s56
	v_lshrrev_b32_e32 v145, 31, v144
	v_ashrrev_i32_e32 v144, 5, v144
	v_add_u32_e32 v162, v144, v145
	v_mad_u64_u32 v[144:145], s[6:7], v162, s59, v[152:153]
	v_cmp_lt_i32_e32 vcc, s60, v144
	s_waitcnt vmcnt(15)
	v_fmamk_f32 v145, v193, 0x3b000000, v161
	v_rsq_f32_e32 v154, v145
	v_add_u32_e32 v145, 0xffffff80, v144
	v_lshl_add_u64 v[146:147], v[148:149], 2, s[10:11]
	v_lshrrev_b32_e32 v149, 1, v145
	v_pk_mul_f32 v[124:125], v[124:125], v[154:155] op_sel_hi:[1,0]
	v_pk_mul_f32 v[126:127], v[126:127], v[154:155] op_sel_hi:[1,0]
	v_pk_mul_f32 v[120:121], v[120:121], v[154:155] op_sel_hi:[1,0]
	v_pk_mul_f32 v[122:123], v[122:123], v[154:155] op_sel_hi:[1,0]
	s_and_saveexec_b64 s[6:7], vcc
	s_cbranch_execz .LBB0_572
	s_nop 0
	v_or_b32_e32 v163, 1, v149
	v_or_b32_e32 v164, 2, v149
	v_or_b32_e32 v165, 3, v149
	v_cvt_f32_u32_e32 v155, v149
	v_cvt_f32_u32_e32 v163, v163
	v_cvt_f32_u32_e32 v164, v164
	v_cvt_f32_u32_e32 v165, v165
	v_mul_f32_e32 v155, 0xbed49a78, v155
	v_mul_f32_e32 v163, 0xbed49a78, v163
	v_mul_f32_e32 v164, 0xbed49a78, v164
	v_mul_f32_e32 v165, 0xbed49a78, v165
	v_exp_f32_e32 v155, v155
	v_exp_f32_e32 v163, v163
	v_exp_f32_e32 v164, v164
	v_exp_f32_e32 v165, v165
	s_waitcnt vmcnt(7)
	v_cvt_f32_i32_e32 v145, v201
	v_mul_f32_e32 v155, v155, v145
	v_mul_f32_e32 v163, v163, v145
	v_mul_f32_e32 v167, v164, v145
	v_mul_f32_e32 v145, v165, v145
	v_cvt_f64_f32_e32 v[164:165], v155
	v_cvt_f64_f32_e32 v[168:169], v163
	v_cvt_f64_f32_e32 v[170:171], v167
	v_cvt_f64_f32_e32 v[172:173], v145
	v_mul_f64 v[174:175], v[164:165], s[20:21]
	v_mul_f64 v[176:177], v[168:169], s[20:21]
	v_mul_f64 v[182:183], v[170:171], s[20:21]
	v_mul_f64 v[184:185], v[172:173], s[20:21]
	v_rndne_f64_e32 v[174:175], v[174:175]
	v_rndne_f64_e32 v[176:177], v[176:177]
	v_rndne_f64_e32 v[182:183], v[182:183]
	v_rndne_f64_e32 v[184:185], v[184:185]
	v_fma_f64 v[164:165], v[164:165], s[20:21], -v[174:175]
	v_fma_f64 v[168:169], v[168:169], s[20:21], -v[176:177]
	v_fma_f64 v[170:171], v[170:171], s[20:21], -v[182:183]
	v_fma_f64 v[172:173], v[172:173], s[20:21], -v[184:185]
	v_cvt_f32_f64_e32 v145, v[164:165]
	v_cvt_f32_f64_e32 v155, v[168:169]
	v_cvt_f32_f64_e32 v163, v[170:171]
	v_cvt_f32_f64_e32 v165, v[172:173]
	v_sin_f32_e32 v164, v145
	v_sin_f32_e32 v170, v155
	v_sin_f32_e32 v174, v163
	v_sin_f32_e32 v183, v165
	v_cos_f32_e32 v182, v165
	v_cos_f32_e32 v168, v145
	v_cos_f32_e32 v172, v155
	v_cos_f32_e32 v176, v163
	v_pk_mul_f32 v[164:165], v[124:125], v[164:165] op_sel:[1,0] op_sel_hi:[0,0]
	v_pk_mul_f32 v[170:171], v[126:127], v[170:171] op_sel:[1,0] op_sel_hi:[0,0]
	v_pk_mul_f32 v[174:175], v[120:121], v[174:175] op_sel:[1,0] op_sel_hi:[0,0]
	v_mul_f32_e32 v186, v123, v183
	v_mov_b32_e32 v188, v183
	v_mov_b32_e32 v189, v182
	v_mul_f32_e32 v190, v123, v182
	v_pk_mul_f32 v[184:185], v[124:125], v[168:169] op_sel_hi:[1,0]
	v_pk_fma_f32 v[124:125], v[124:125], v[168:169], v[164:165] op_sel_hi:[1,0,1]
	v_pk_fma_f32 v[168:169], v[126:127], v[172:173], v[170:171] op_sel_hi:[1,0,1] neg_lo:[0,0,1] neg_hi:[0,0,1]
	v_pk_fma_f32 v[126:127], v[126:127], v[172:173], v[170:171] op_sel_hi:[1,0,1]
	v_pk_fma_f32 v[170:171], v[120:121], v[176:177], v[174:175] op_sel_hi:[1,0,1] neg_lo:[0,0,1] neg_hi:[0,0,1]
	v_pk_fma_f32 v[120:121], v[120:121], v[176:177], v[174:175] op_sel_hi:[1,0,1]
	v_pk_fma_f32 v[172:173], v[122:123], v[182:183], v[186:187] op_sel_hi:[1,1,0] neg_lo:[0,0,1] neg_hi:[0,0,1]
	v_pk_fma_f32 v[174:175], v[122:123], v[188:189], v[190:191] op_sel_hi:[1,1,0]
	v_sub_f32_e32 v124, v184, v164
	v_mov_b32_e32 v126, v168
	v_mov_b32_e32 v120, v170
	v_mov_b32_e32 v122, v172
	v_mov_b32_e32 v123, v174
; __device__ __forceinline__ void store8(bf16_t* dst, const float* v) { u32x4 w; w.x = pk2(v[0], v[1]); w.y = pk2(v[2], v[3]); w.z = pk2(v[4], v[5]); w.w = pk2(v[6], v[7]); *(u32x4*)dst = w; }
; __device__ __forceinline__ void rope_pair(float& a, float& b, int pos, int i) {
;     const float inv = __builtin_amdgcn_exp2f(-(float)i * 0.41524101186092029f);
;     const float ang = (float)pos * inv;
;     double rev = (double)ang * 0.15915494309189535;
;     rev -= __builtin_rint(rev);
;     const float fr = (float)rev;
;     const float s = __builtin_amdgcn_sinf(fr), c = __builtin_amdgcn_cosf(fr);
;     const float na = a * c - b * s, nb = a * s + b * c; a = na; b = nb;
; }
;     __device__ __forceinline__ void operator()(const pg8::f32x4 (&acc)[2][2][4][2], const pg8::Unit& u, int wr, int wc, int fr, int fq) const {
;     ...
;                         const int c = pn * 256 + cl, h = c / 192, dd = c - h * 192;
; #pragma unroll
;                         for (int j = 0; j < 8; ++j) v[j] *= rs;
;                         if (dd >= 128) {
;                             const int p = a.pos[row];
; #pragma unroll
;                             for (int j = 0; j < 4; ++j) rope_pair(v[2 * j], v[2 * j + 1], p, ((dd - 128) >> 1) + j);
;                         }
;                         store8(a.o0 + ((size_t)((bb * NH + h) * SEQ + ss)) * 192 + dd, v);
.LBB0_572:
	s_or_b64 exec, exec, s[6:7]
	v_cvt_pk_bf16_f32 v124, v124, v125
	v_cvt_pk_bf16_f32 v125, v126, v127
	v_cvt_pk_bf16_f32 v127, v122, v123
	v_or_b32_e32 v122, 0x80, v152
	s_ashr_i32 s6, s23, 10
	v_cvt_pk_bf16_f32 v126, v120, v121
	v_mul_hi_i32 v120, v122, s56
	s_and_b32 s25, s6, -8
	v_lshrrev_b32_e32 v121, 31, v120
	v_ashrrev_i32_e32 v120, 5, v120
	v_mov_b32_e32 v155, v154
	v_and_b32_e32 v164, 0x1fcf, v148
	v_add_lshl_u32 v163, s25, v162, 13
	v_add_u32_e32 v123, v120, v121
	v_or_b32_e32 v145, v163, v164
	v_mov_b64_e32 v[168:169], s[14:15]
	v_pk_mul_f32 v[120:121], v[112:113], v[154:155]
	v_mad_u64_u32 v[112:113], s[6:7], v123, s59, v[122:123]
	v_mad_i64_i32 v[168:169], s[6:7], v145, s61, v[168:169]
	v_ashrrev_i32_e32 v145, 31, v144
	v_add_u32_e32 v113, 0xffffff80, v112
	v_lshl_add_u64 v[168:169], v[144:145], 1, v[168:169]
	v_pk_mul_f32 v[116:117], v[116:117], v[154:155]
	v_pk_mul_f32 v[118:119], v[118:119], v[154:155]
	v_pk_mul_f32 v[114:115], v[114:115], v[154:155]
	v_cmp_lt_i32_e64 s[6:7], s60, v112
	v_lshrrev_b32_e32 v122, 1, v113
	global_store_dwordx4 v[168:169], v[124:127], off
	s_and_saveexec_b64 s[30:31], s[6:7]
	s_cbranch_execz .LBB0_574
	s_nop 0
	v_add_u32_e32 v125, 1, v122
	v_add_u32_e32 v126, 2, v122
	v_add_u32_e32 v127, 3, v122
	v_cvt_f32_u32_e32 v124, v122
	v_cvt_f32_u32_e32 v125, v125
	v_cvt_f32_u32_e32 v126, v126
	v_cvt_f32_u32_e32 v127, v127
	v_mul_f32_e32 v124, 0xbed49a78, v124
	v_mul_f32_e32 v125, 0xbed49a78, v125
	v_mul_f32_e32 v126, 0xbed49a78, v126
	v_mul_f32_e32 v127, 0xbed49a78, v127
	v_exp_f32_e32 v124, v124
	v_exp_f32_e32 v125, v125
	v_exp_f32_e32 v126, v126
	v_exp_f32_e32 v127, v127
	s_waitcnt vmcnt(8)
	v_cvt_f32_i32_e32 v113, v201
	v_mul_f32_e32 v124, v124, v113
	v_mul_f32_e32 v152, v125, v113
	v_mul_f32_e32 v154, v126, v113
	v_mul_f32_e32 v113, v127, v113
	v_cvt_f64_f32_e32 v[124:125], v124
	v_cvt_f64_f32_e32 v[126:127], v152
	v_cvt_f64_f32_e32 v[154:155], v154
	v_cvt_f64_f32_e32 v[168:169], v113
	v_mul_f64 v[170:171], v[124:125], s[20:21]
	v_mul_f64 v[172:173], v[126:127], s[20:21]
	v_mul_f64 v[174:175], v[154:155], s[20:21]
	v_mul_f64 v[176:177], v[168:169], s[20:21]
	v_rndne_f64_e32 v[170:171], v[170:171]
	v_rndne_f64_e32 v[172:173], v[172:173]
	v_rndne_f64_e32 v[174:175], v[174:175]
	v_rndne_f64_e32 v[176:177], v[176:177]
	v_fma_f64 v[124:125], v[124:125], s[20:21], -v[170:171]
	v_fma_f64 v[126:127], v[126:127], s[20:21], -v[172:173]
	v_fma_f64 v[154:155], v[154:155], s[20:21], -v[174:175]
	v_fma_f64 v[168:169], v[168:169], s[20:21], -v[176:177]
	v_cvt_f32_f64_e32 v113, v[124:125]
	v_cvt_f32_f64_e32 v125, v[126:127]
	v_cvt_f32_f64_e32 v127, v[154:155]
	v_cvt_f32_f64_e32 v155, v[168:169]
	v_sin_f32_e32 v124, v113
	v_sin_f32_e32 v152, v125
	v_sin_f32_e32 v168, v127
	v_sin_f32_e32 v173, v155
	v_cos_f32_e32 v172, v155
	v_cos_f32_e32 v126, v113
	v_cos_f32_e32 v154, v125
	v_cos_f32_e32 v170, v127
	v_pk_mul_f32 v[124:125], v[116:117], v[124:125] op_sel:[1,0] op_sel_hi:[0,0]
	v_pk_mul_f32 v[176:177], v[118:119], v[152:153] op_sel:[1,0] op_sel_hi:[0,0]
	v_pk_mul_f32 v[168:169], v[120:121], v[168:169] op_sel:[1,0] op_sel_hi:[0,0]
	v_mul_f32_e32 v152, v115, v173
	v_mov_b32_e32 v182, v173
	v_mov_b32_e32 v183, v172
	v_mul_f32_e32 v184, v115, v172
	v_pk_mul_f32 v[174:175], v[116:117], v[126:127] op_sel_hi:[1,0]
	v_pk_fma_f32 v[116:117], v[116:117], v[126:127], v[124:125] op_sel_hi:[1,0,1]
	v_pk_fma_f32 v[126:127], v[118:119], v[154:155], v[176:177] op_sel_hi:[1,0,1] neg_lo:[0,0,1] neg_hi:[0,0,1]
	v_pk_fma_f32 v[118:119], v[118:119], v[154:155], v[176:177] op_sel_hi:[1,0,1]
	v_pk_fma_f32 v[154:155], v[120:121], v[170:171], v[168:169] op_sel_hi:[1,0,1] neg_lo:[0,0,1] neg_hi:[0,0,1]
	v_pk_fma_f32 v[120:121], v[120:121], v[170:171], v[168:169] op_sel_hi:[1,0,1]
	v_pk_fma_f32 v[168:169], v[114:115], v[172:173], v[152:153] op_sel_hi:[1,1,0] neg_lo:[0,0,1] neg_hi:[0,0,1]
	v_pk_fma_f32 v[170:171], v[114:115], v[182:183], v[184:185] op_sel_hi:[1,1,0]
	v_sub_f32_e32 v116, v174, v124
	v_mov_b32_e32 v118, v126
	v_mov_b32_e32 v120, v154
	v_mov_b32_e32 v114, v168
	v_mov_b32_e32 v115, v170
.LBB0_574:
	s_or_b64 exec, exec, s[30:31]
	v_add_lshl_u32 v124, v123, s25, 13
	v_or_b32_e32 v113, v124, v164
	v_mov_b64_e32 v[126:127], s[14:15]
	v_mad_i64_i32 v[126:127], s[30:31], v113, s61, v[126:127]
	v_ashrrev_i32_e32 v113, 31, v112
	v_lshl_add_u64 v[126:127], v[112:113], 1, v[126:127]
	v_cvt_pk_bf16_f32 v116, v116, v117
	v_cvt_pk_bf16_f32 v117, v118, v119
	v_cvt_pk_bf16_f32 v118, v120, v121
	v_cvt_pk_bf16_f32 v119, v114, v115
	global_store_dwordx4 v[126:127], v[116:119], off
	s_nop 0
	s_waitcnt vmcnt(16)
	v_fmamk_f32 v114, v194, 0x3b000000, v161
	v_rsq_f32_e32 v114, v114
	s_nop 0
	v_pk_mul_f32 v[108:109], v[108:109], v[114:115] op_sel_hi:[1,0]
	v_pk_mul_f32 v[110:111], v[110:111], v[114:115] op_sel_hi:[1,0]
	v_pk_mul_f32 v[104:105], v[104:105], v[114:115] op_sel_hi:[1,0]
	v_pk_mul_f32 v[106:107], v[106:107], v[114:115] op_sel_hi:[1,0]
	s_and_saveexec_b64 s[30:31], vcc
	s_cbranch_execz .LBB0_576
; __device__ __forceinline__ void store8(bf16_t* dst, const float* v) { u32x4 w; w.x = pk2(v[0], v[1]); w.y = pk2(v[2], v[3]); w.z = pk2(v[4], v[5]); w.w = pk2(v[6], v[7]); *(u32x4*)dst = w; }
; __device__ __forceinline__ void rope_pair(float& a, float& b, int pos, int i) {
;     const float inv = __builtin_amdgcn_exp2f(-(float)i * 0.41524101186092029f);
;     const float ang = (float)pos * inv;
;     double rev = (double)ang * 0.15915494309189535;
;     rev -= __builtin_rint(rev);
;     const float fr = (float)rev;
;     const float s = __builtin_amdgcn_sinf(fr), c = __builtin_amdgcn_cosf(fr);
;     const float na = a * c - b * s, nb = a * s + b * c; a = na; b = nb;
; }
;     __device__ __forceinline__ void operator()(const pg8::f32x4 (&acc)[2][2][4][2], const pg8::Unit& u, int wr, int wc, int fr, int fq) const {
;     ...
;                         const int c = pn * 256 + cl, h = c / 192, dd = c - h * 192;
; #pragma unroll
;                         for (int j = 0; j < 8; ++j) v[j] *= rs;
;                         if (dd >= 128) {
;                             const int p = a.pos[row];
; #pragma unroll
;                             for (int j = 0; j < 4; ++j) rope_pair(v[2 * j], v[2 * j + 1], p, ((dd - 128) >> 1) + j);
;                         }
;                         store8(a.o0 + ((size_t)((bb * NH + h) * SEQ + ss)) * 192 + dd, v);
	s_nop 0
	v_or_b32_e32 v117, 1, v149
	v_or_b32_e32 v118, 2, v149
	v_or_b32_e32 v119, 3, v149
	v_cvt_f32_u32_e32 v116, v149
	v_cvt_f32_u32_e32 v117, v117
	v_cvt_f32_u32_e32 v118, v118
	v_cvt_f32_u32_e32 v119, v119
	v_mul_f32_e32 v116, 0xbed49a78, v116
	v_mul_f32_e32 v117, 0xbed49a78, v117
	v_mul_f32_e32 v118, 0xbed49a78, v118
	v_mul_f32_e32 v119, 0xbed49a78, v119
	v_exp_f32_e32 v116, v116
	v_exp_f32_e32 v117, v117
	v_exp_f32_e32 v118, v118
	v_exp_f32_e32 v119, v119
	s_waitcnt vmcnt(8)
	v_cvt_f32_i32_e32 v115, v202
	v_mul_f32_e32 v116, v116, v115
	v_mul_f32_e32 v120, v117, v115
	v_mul_f32_e32 v121, v118, v115
	v_mul_f32_e32 v115, v119, v115
	v_cvt_f64_f32_e32 v[116:117], v116
	v_cvt_f64_f32_e32 v[118:119], v120
	v_cvt_f64_f32_e32 v[120:121], v121
	v_cvt_f64_f32_e32 v[126:127], v115
	v_mul_f64 v[154:155], v[116:117], s[20:21]
	v_mul_f64 v[164:165], v[118:119], s[20:21]
	v_mul_f64 v[168:169], v[120:121], s[20:21]
	v_mul_f64 v[170:171], v[126:127], s[20:21]
	v_rndne_f64_e32 v[154:155], v[154:155]
	v_rndne_f64_e32 v[164:165], v[164:165]
	v_rndne_f64_e32 v[168:169], v[168:169]
	v_rndne_f64_e32 v[170:171], v[170:171]
	v_fma_f64 v[116:117], v[116:117], s[20:21], -v[154:155]
	v_fma_f64 v[118:119], v[118:119], s[20:21], -v[164:165]
	v_fma_f64 v[120:121], v[120:121], s[20:21], -v[168:169]
	v_fma_f64 v[126:127], v[126:127], s[20:21], -v[170:171]
	v_cvt_f32_f64_e32 v115, v[116:117]
	v_cvt_f32_f64_e32 v117, v[118:119]
	v_cvt_f32_f64_e32 v119, v[120:121]
	v_cvt_f32_f64_e32 v121, v[126:127]
	v_sin_f32_e32 v116, v115
	v_sin_f32_e32 v120, v117
	v_sin_f32_e32 v152, v119
	v_sin_f32_e32 v165, v121
	v_cos_f32_e32 v164, v121
	v_cos_f32_e32 v118, v115
	v_cos_f32_e32 v126, v117
	v_cos_f32_e32 v154, v119
	v_pk_mul_f32 v[116:117], v[108:109], v[116:117] op_sel:[1,0] op_sel_hi:[0,0]
	v_pk_mul_f32 v[120:121], v[110:111], v[120:121] op_sel:[1,0] op_sel_hi:[0,0]
	v_pk_mul_f32 v[170:171], v[104:105], v[152:153] op_sel:[1,0] op_sel_hi:[0,0]
	v_mul_f32_e32 v152, v107, v165
	v_mov_b32_e32 v172, v165
	v_mov_b32_e32 v173, v164
	v_mul_f32_e32 v174, v107, v164
	v_pk_mul_f32 v[168:169], v[108:109], v[118:119] op_sel_hi:[1,0]
	v_pk_fma_f32 v[108:109], v[108:109], v[118:119], v[116:117] op_sel_hi:[1,0,1]
	v_pk_fma_f32 v[118:119], v[110:111], v[126:127], v[120:121] op_sel_hi:[1,0,1] neg_lo:[0,0,1] neg_hi:[0,0,1]
	v_pk_fma_f32 v[110:111], v[110:111], v[126:127], v[120:121] op_sel_hi:[1,0,1]
	v_pk_fma_f32 v[120:121], v[104:105], v[154:155], v[170:171] op_sel_hi:[1,0,1] neg_lo:[0,0,1] neg_hi:[0,0,1]
	v_pk_fma_f32 v[104:105], v[104:105], v[154:155], v[170:171] op_sel_hi:[1,0,1]
	v_pk_fma_f32 v[126:127], v[106:107], v[164:165], v[152:153] op_sel_hi:[1,1,0] neg_lo:[0,0,1] neg_hi:[0,0,1]
	v_pk_fma_f32 v[154:155], v[106:107], v[172:173], v[174:175] op_sel_hi:[1,1,0]
	v_sub_f32_e32 v108, v168, v116
	v_mov_b32_e32 v110, v118
	v_mov_b32_e32 v104, v120
	v_mov_b32_e32 v106, v126
	v_mov_b32_e32 v107, v154
.LBB0_576:
	s_or_b64 exec, exec, s[30:31]
	v_bitop3_b32 v116, v148, s62, 16 bitop3:0xc8
	v_or_b32_e32 v117, v163, v116
	v_mov_b64_e32 v[118:119], s[14:15]
	v_mov_b32_e32 v115, v114
	v_mad_i64_i32 v[118:119], s[30:31], v117, s61, v[118:119]
	v_lshl_add_u64 v[118:119], v[144:145], 1, v[118:119]
	v_cvt_pk_bf16_f32 v108, v108, v109
	v_cvt_pk_bf16_f32 v109, v110, v111
	v_cvt_pk_bf16_f32 v110, v104, v105
	v_cvt_pk_bf16_f32 v111, v106, v107
	v_pk_mul_f32 v[100:101], v[100:101], v[114:115]
	v_pk_mul_f32 v[102:103], v[102:103], v[114:115]
	v_pk_mul_f32 v[96:97], v[96:97], v[114:115]
	v_pk_mul_f32 v[98:99], v[98:99], v[114:115]
	global_store_dwordx4 v[118:119], v[108:111], off
	s_and_saveexec_b64 s[30:31], s[6:7]
	s_cbranch_execz .LBB0_578
	s_nop 0
	v_add_u32_e32 v106, 1, v122
	v_add_u32_e32 v107, 2, v122
	v_add_u32_e32 v108, 3, v122
	v_cvt_f32_u32_e32 v105, v122
	v_cvt_f32_u32_e32 v106, v106
	v_cvt_f32_u32_e32 v107, v107
	v_cvt_f32_u32_e32 v108, v108
	v_mul_f32_e32 v105, 0xbed49a78, v105
	v_mul_f32_e32 v106, 0xbed49a78, v106
	v_mul_f32_e32 v107, 0xbed49a78, v107
	v_mul_f32_e32 v108, 0xbed49a78, v108
	v_exp_f32_e32 v105, v105
	v_exp_f32_e32 v106, v106
	v_exp_f32_e32 v107, v107
	v_exp_f32_e32 v108, v108
	s_waitcnt vmcnt(9)
	v_cvt_f32_i32_e32 v104, v202
	v_mul_f32_e32 v105, v105, v104
	v_mul_f32_e32 v106, v106, v104
	v_mul_f32_e32 v109, v107, v104
	v_mul_f32_e32 v110, v108, v104
	v_cvt_f64_f32_e32 v[104:105], v105
	v_cvt_f64_f32_e32 v[106:107], v106
	v_cvt_f64_f32_e32 v[108:109], v109
	v_cvt_f64_f32_e32 v[110:111], v110
	v_mul_f64 v[114:115], v[104:105], s[20:21]
	v_mul_f64 v[118:119], v[106:107], s[20:21]
	v_mul_f64 v[120:121], v[108:109], s[20:21]
	v_mul_f64 v[126:127], v[110:111], s[20:21]
	v_rndne_f64_e32 v[114:115], v[114:115]
	v_rndne_f64_e32 v[118:119], v[118:119]
	v_rndne_f64_e32 v[120:121], v[120:121]
	v_rndne_f64_e32 v[126:127], v[126:127]
	v_fma_f64 v[104:105], v[104:105], s[20:21], -v[114:115]
	v_fma_f64 v[106:107], v[106:107], s[20:21], -v[118:119]
	v_fma_f64 v[108:109], v[108:109], s[20:21], -v[120:121]
	v_fma_f64 v[110:111], v[110:111], s[20:21], -v[126:127]
	v_cvt_f32_f64_e32 v105, v[104:105]
	v_cvt_f32_f64_e32 v107, v[106:107]
	v_cvt_f32_f64_e32 v109, v[108:109]
	v_cvt_f32_f64_e32 v111, v[110:111]
	v_sin_f32_e32 v104, v105
	v_sin_f32_e32 v108, v107
	v_sin_f32_e32 v114, v109
	v_sin_f32_e32 v121, v111
	v_cos_f32_e32 v120, v111
	v_cos_f32_e32 v106, v105
	v_cos_f32_e32 v110, v107
	v_cos_f32_e32 v118, v109
	v_pk_mul_f32 v[104:105], v[100:101], v[104:105] op_sel:[1,0] op_sel_hi:[0,0]
	v_pk_mul_f32 v[108:109], v[102:103], v[108:109] op_sel:[1,0] op_sel_hi:[0,0]
	v_pk_mul_f32 v[114:115], v[96:97], v[114:115] op_sel:[1,0] op_sel_hi:[0,0]
	v_mul_f32_e32 v152, v99, v121
	v_mov_b32_e32 v154, v121
	v_mov_b32_e32 v155, v120
	v_mul_f32_e32 v164, v99, v120
	v_pk_mul_f32 v[126:127], v[100:101], v[106:107] op_sel_hi:[1,0]
	v_pk_fma_f32 v[100:101], v[100:101], v[106:107], v[104:105] op_sel_hi:[1,0,1]
	v_pk_fma_f32 v[106:107], v[102:103], v[110:111], v[108:109] op_sel_hi:[1,0,1] neg_lo:[0,0,1] neg_hi:[0,0,1]
	v_pk_fma_f32 v[102:103], v[102:103], v[110:111], v[108:109] op_sel_hi:[1,0,1]
	v_pk_fma_f32 v[108:109], v[96:97], v[118:119], v[114:115] op_sel_hi:[1,0,1] neg_lo:[0,0,1] neg_hi:[0,0,1]
	v_pk_fma_f32 v[96:97], v[96:97], v[118:119], v[114:115] op_sel_hi:[1,0,1]
	v_pk_fma_f32 v[110:111], v[98:99], v[120:121], v[152:153] op_sel_hi:[1,1,0] neg_lo:[0,0,1] neg_hi:[0,0,1]
	v_pk_fma_f32 v[114:115], v[98:99], v[154:155], v[164:165] op_sel_hi:[1,1,0]
	v_sub_f32_e32 v100, v126, v104
	v_mov_b32_e32 v102, v106
	v_mov_b32_e32 v96, v108
	v_mov_b32_e32 v98, v110
	v_mov_b32_e32 v99, v114
; __device__ __forceinline__ void store8(bf16_t* dst, const float* v) { u32x4 w; w.x = pk2(v[0], v[1]); w.y = pk2(v[2], v[3]); w.z = pk2(v[4], v[5]); w.w = pk2(v[6], v[7]); *(u32x4*)dst = w; }
;     __device__ __forceinline__ void operator()(const pg8::f32x4 (&acc)[2][2][4][2], const pg8::Unit& u, int wr, int wc, int fr, int fq) const {
;     ...
;                 const int row = u.pm * 256 + ai * 128 + wr * 64 + m * 16 + fr;
;                 const int bb = row >> 13, ss = row & 8191;
;                 float ssq = 0.f;
;                 float rs = 1.f;
;                 if constexpr (KIND == EK_Q || KIND == EK_KV) rs = __builtin_amdgcn_rsqf(a.ssq0[row] * (1.f / 512.f) + EPS);
;     ...
;                         const int c = pn * 256 + cl, h = c / 192, dd = c - h * 192;
; #pragma unroll
;                         for (int j = 0; j < 8; ++j) v[j] *= rs;
;                         if (dd >= 128) {
;                             const int p = a.pos[row];
; #pragma unroll
;                             for (int j = 0; j < 4; ++j) rope_pair(v[2 * j], v[2 * j + 1], p, ((dd - 128) >> 1) + j);
;                         }
;                         store8(a.o0 + ((size_t)((bb * NH + h) * SEQ + ss)) * 192 + dd, v);
.LBB0_578:
	s_or_b64 exec, exec, s[30:31]
	v_or_b32_e32 v106, v124, v116
	v_mov_b64_e32 v[104:105], s[14:15]
	v_mad_i64_i32 v[104:105], s[30:31], v106, s61, v[104:105]
	v_lshl_add_u64 v[104:105], v[112:113], 1, v[104:105]
	v_cvt_pk_bf16_f32 v100, v100, v101
	v_cvt_pk_bf16_f32 v101, v102, v103
	v_cvt_pk_bf16_f32 v102, v96, v97
	v_cvt_pk_bf16_f32 v103, v98, v99
	global_store_dwordx4 v[104:105], v[100:103], off
	s_nop 0
	s_waitcnt vmcnt(17)
	v_fmamk_f32 v96, v195, 0x3b000000, v161
	v_rsq_f32_e32 v96, v96
	s_nop 0
	v_pk_mul_f32 v[92:93], v[92:93], v[96:97] op_sel_hi:[1,0]
	v_pk_mul_f32 v[94:95], v[94:95], v[96:97] op_sel_hi:[1,0]
	v_pk_mul_f32 v[88:89], v[88:89], v[96:97] op_sel_hi:[1,0]
	v_pk_mul_f32 v[90:91], v[90:91], v[96:97] op_sel_hi:[1,0]
	s_and_saveexec_b64 s[30:31], vcc
	s_cbranch_execz .LBB0_580
	s_nop 0
	v_or_b32_e32 v99, 1, v149
	v_or_b32_e32 v100, 2, v149
	v_or_b32_e32 v101, 3, v149
	v_cvt_f32_u32_e32 v98, v149
	v_cvt_f32_u32_e32 v99, v99
	v_cvt_f32_u32_e32 v100, v100
	v_cvt_f32_u32_e32 v101, v101
	v_mul_f32_e32 v98, 0xbed49a78, v98
	v_mul_f32_e32 v99, 0xbed49a78, v99
	v_mul_f32_e32 v100, 0xbed49a78, v100
	v_mul_f32_e32 v101, 0xbed49a78, v101
	v_exp_f32_e32 v98, v98
	v_exp_f32_e32 v99, v99
	v_exp_f32_e32 v100, v100
	v_exp_f32_e32 v101, v101
	s_waitcnt vmcnt(9)
	v_cvt_f32_i32_e32 v97, v203
	v_mul_f32_e32 v98, v98, v97
	v_mul_f32_e32 v102, v99, v97
	v_mul_f32_e32 v103, v100, v97
	v_mul_f32_e32 v97, v101, v97
	v_cvt_f64_f32_e32 v[98:99], v98
	v_cvt_f64_f32_e32 v[100:101], v102
	v_cvt_f64_f32_e32 v[102:103], v103
	v_cvt_f64_f32_e32 v[104:105], v97
	v_mul_f64 v[106:107], v[98:99], s[20:21]
	v_mul_f64 v[108:109], v[100:101], s[20:21]
	v_mul_f64 v[110:111], v[102:103], s[20:21]
	v_mul_f64 v[114:115], v[104:105], s[20:21]
	v_rndne_f64_e32 v[106:107], v[106:107]
	v_rndne_f64_e32 v[108:109], v[108:109]
	v_rndne_f64_e32 v[110:111], v[110:111]
	v_rndne_f64_e32 v[114:115], v[114:115]
	v_fma_f64 v[98:99], v[98:99], s[20:21], -v[106:107]
	v_fma_f64 v[100:101], v[100:101], s[20:21], -v[108:109]
	v_fma_f64 v[102:103], v[102:103], s[20:21], -v[110:111]
	v_fma_f64 v[104:105], v[104:105], s[20:21], -v[114:115]
	v_cvt_f32_f64_e32 v97, v[98:99]
	v_cvt_f32_f64_e32 v99, v[100:101]
	v_cvt_f32_f64_e32 v101, v[102:103]
	v_cvt_f32_f64_e32 v103, v[104:105]
	v_sin_f32_e32 v98, v97
	v_sin_f32_e32 v102, v99
	v_sin_f32_e32 v106, v101
	v_sin_f32_e32 v111, v103
	v_cos_f32_e32 v110, v103
	v_cos_f32_e32 v100, v97
	v_cos_f32_e32 v104, v99
	v_cos_f32_e32 v108, v101
	v_pk_mul_f32 v[98:99], v[92:93], v[98:99] op_sel:[1,0] op_sel_hi:[0,0]
	v_pk_mul_f32 v[102:103], v[94:95], v[102:103] op_sel:[1,0] op_sel_hi:[0,0]
	v_pk_mul_f32 v[106:107], v[88:89], v[106:107] op_sel:[1,0] op_sel_hi:[0,0]
	v_mul_f32_e32 v116, v91, v111
	v_mov_b32_e32 v118, v111
	v_mov_b32_e32 v119, v110
	v_mul_f32_e32 v120, v91, v110
	v_pk_mul_f32 v[114:115], v[92:93], v[100:101] op_sel_hi:[1,0]
	v_pk_fma_f32 v[92:93], v[92:93], v[100:101], v[98:99] op_sel_hi:[1,0,1]
	v_pk_fma_f32 v[100:101], v[94:95], v[104:105], v[102:103] op_sel_hi:[1,0,1] neg_lo:[0,0,1] neg_hi:[0,0,1]
	v_pk_fma_f32 v[94:95], v[94:95], v[104:105], v[102:103] op_sel_hi:[1,0,1]
	v_pk_fma_f32 v[102:103], v[88:89], v[108:109], v[106:107] op_sel_hi:[1,0,1] neg_lo:[0,0,1] neg_hi:[0,0,1]
	v_pk_fma_f32 v[88:89], v[88:89], v[108:109], v[106:107] op_sel_hi:[1,0,1]
	v_pk_fma_f32 v[104:105], v[90:91], v[110:111], v[116:117] op_sel_hi:[1,1,0] neg_lo:[0,0,1] neg_hi:[0,0,1]
	v_pk_fma_f32 v[106:107], v[90:91], v[118:119], v[120:121] op_sel_hi:[1,1,0]
	v_sub_f32_e32 v92, v114, v98
	v_mov_b32_e32 v94, v100
	v_mov_b32_e32 v88, v102
	v_mov_b32_e32 v90, v104
	v_mov_b32_e32 v91, v106
.LBB0_580:
	s_or_b64 exec, exec, s[30:31]
	v_bitop3_b32 v98, v148, s63, 32 bitop3:0xc8
	v_or_b32_e32 v99, v163, v98
	v_mov_b64_e32 v[100:101], s[14:15]
	v_mov_b32_e32 v97, v96
	v_mad_i64_i32 v[100:101], s[30:31], v99, s61, v[100:101]
	v_lshl_add_u64 v[100:101], v[144:145], 1, v[100:101]
	v_cvt_pk_bf16_f32 v92, v92, v93
	v_cvt_pk_bf16_f32 v93, v94, v95
	v_cvt_pk_bf16_f32 v94, v88, v89
	v_cvt_pk_bf16_f32 v95, v90, v91
	v_pk_mul_f32 v[84:85], v[84:85], v[96:97]
	v_pk_mul_f32 v[86:87], v[86:87], v[96:97]
	v_pk_mul_f32 v[80:81], v[80:81], v[96:97]
	v_pk_mul_f32 v[82:83], v[82:83], v[96:97]
	global_store_dwordx4 v[100:101], v[92:95], off
	s_and_saveexec_b64 s[30:31], s[6:7]
	s_cbranch_execz .LBB0_582
; __device__ __forceinline__ void store8(bf16_t* dst, const float* v) { u32x4 w; w.x = pk2(v[0], v[1]); w.y = pk2(v[2], v[3]); w.z = pk2(v[4], v[5]); w.w = pk2(v[6], v[7]); *(u32x4*)dst = w; }
; __device__ __forceinline__ void rope_pair(float& a, float& b, int pos, int i) {
;     const float inv = __builtin_amdgcn_exp2f(-(float)i * 0.41524101186092029f);
;     const float ang = (float)pos * inv;
;     double rev = (double)ang * 0.15915494309189535;
;     rev -= __builtin_rint(rev);
;     const float fr = (float)rev;
;     const float s = __builtin_amdgcn_sinf(fr), c = __builtin_amdgcn_cosf(fr);
;     const float na = a * c - b * s, nb = a * s + b * c; a = na; b = nb;
; }
;     __device__ __forceinline__ void operator()(const pg8::f32x4 (&acc)[2][2][4][2], const pg8::Unit& u, int wr, int wc, int fr, int fq) const {
;     ...
;                         const int c = pn * 256 + cl, h = c / 192, dd = c - h * 192;
; #pragma unroll
;                         for (int j = 0; j < 8; ++j) v[j] *= rs;
;                         if (dd >= 128) {
;                             const int p = a.pos[row];
; #pragma unroll
;                             for (int j = 0; j < 4; ++j) rope_pair(v[2 * j], v[2 * j + 1], p, ((dd - 128) >> 1) + j);
;                         }
;                         store8(a.o0 + ((size_t)((bb * NH + h) * SEQ + ss)) * 192 + dd, v);
	s_nop 0
	v_add_u32_e32 v90, 1, v122
	v_add_u32_e32 v91, 2, v122
	v_add_u32_e32 v92, 3, v122
	v_cvt_f32_u32_e32 v89, v122
	v_cvt_f32_u32_e32 v90, v90
	v_cvt_f32_u32_e32 v91, v91
	v_cvt_f32_u32_e32 v92, v92
	v_mul_f32_e32 v89, 0xbed49a78, v89
	v_mul_f32_e32 v90, 0xbed49a78, v90
	v_mul_f32_e32 v91, 0xbed49a78, v91
	v_mul_f32_e32 v92, 0xbed49a78, v92
	v_exp_f32_e32 v89, v89
	v_exp_f32_e32 v90, v90
	v_exp_f32_e32 v91, v91
	v_exp_f32_e32 v92, v92
	s_waitcnt vmcnt(10)
	v_cvt_f32_i32_e32 v88, v203
	v_mul_f32_e32 v89, v89, v88
	v_mul_f32_e32 v90, v90, v88
	v_mul_f32_e32 v93, v91, v88
	v_mul_f32_e32 v94, v92, v88
	v_cvt_f64_f32_e32 v[88:89], v89
	v_cvt_f64_f32_e32 v[90:91], v90
	v_cvt_f64_f32_e32 v[92:93], v93
	v_cvt_f64_f32_e32 v[94:95], v94
	v_mul_f64 v[96:97], v[88:89], s[20:21]
	v_mul_f64 v[100:101], v[90:91], s[20:21]
	v_mul_f64 v[102:103], v[92:93], s[20:21]
	v_mul_f64 v[104:105], v[94:95], s[20:21]
	v_rndne_f64_e32 v[96:97], v[96:97]
	v_rndne_f64_e32 v[100:101], v[100:101]
	v_rndne_f64_e32 v[102:103], v[102:103]
	v_rndne_f64_e32 v[104:105], v[104:105]
	v_fma_f64 v[88:89], v[88:89], s[20:21], -v[96:97]
	v_fma_f64 v[90:91], v[90:91], s[20:21], -v[100:101]
	v_fma_f64 v[92:93], v[92:93], s[20:21], -v[102:103]
	v_fma_f64 v[94:95], v[94:95], s[20:21], -v[104:105]
	v_cvt_f32_f64_e32 v89, v[88:89]
	v_cvt_f32_f64_e32 v91, v[90:91]
	v_cvt_f32_f64_e32 v93, v[92:93]
	v_cvt_f32_f64_e32 v95, v[94:95]
	v_sin_f32_e32 v88, v89
	v_sin_f32_e32 v92, v91
	v_sin_f32_e32 v96, v93
	v_sin_f32_e32 v103, v95
	v_cos_f32_e32 v102, v95
	v_cos_f32_e32 v90, v89
	v_cos_f32_e32 v94, v91
	v_cos_f32_e32 v100, v93
	v_pk_mul_f32 v[88:89], v[84:85], v[88:89] op_sel:[1,0] op_sel_hi:[0,0]
	v_pk_mul_f32 v[92:93], v[86:87], v[92:93] op_sel:[1,0] op_sel_hi:[0,0]
	v_pk_mul_f32 v[96:97], v[80:81], v[96:97] op_sel:[1,0] op_sel_hi:[0,0]
	v_mul_f32_e32 v106, v83, v103
	v_mov_b32_e32 v108, v103
	v_mov_b32_e32 v109, v102
	v_mul_f32_e32 v110, v83, v102
	v_pk_mul_f32 v[104:105], v[84:85], v[90:91] op_sel_hi:[1,0]
	v_pk_fma_f32 v[84:85], v[84:85], v[90:91], v[88:89] op_sel_hi:[1,0,1]
	v_pk_fma_f32 v[90:91], v[86:87], v[94:95], v[92:93] op_sel_hi:[1,0,1] neg_lo:[0,0,1] neg_hi:[0,0,1]
	v_pk_fma_f32 v[86:87], v[86:87], v[94:95], v[92:93] op_sel_hi:[1,0,1]
	v_pk_fma_f32 v[92:93], v[80:81], v[100:101], v[96:97] op_sel_hi:[1,0,1] neg_lo:[0,0,1] neg_hi:[0,0,1]
	v_pk_fma_f32 v[80:81], v[80:81], v[100:101], v[96:97] op_sel_hi:[1,0,1]
	v_pk_fma_f32 v[94:95], v[82:83], v[102:103], v[106:107] op_sel_hi:[1,1,0] neg_lo:[0,0,1] neg_hi:[0,0,1]
	v_pk_fma_f32 v[96:97], v[82:83], v[108:109], v[110:111] op_sel_hi:[1,1,0]
	v_sub_f32_e32 v84, v104, v88
	v_mov_b32_e32 v86, v90
	v_mov_b32_e32 v80, v92
	v_mov_b32_e32 v82, v94
	v_mov_b32_e32 v83, v96
.LBB0_582:
	s_or_b64 exec, exec, s[30:31]
	v_or_b32_e32 v90, v124, v98
	v_mov_b64_e32 v[88:89], s[14:15]
	v_mad_i64_i32 v[88:89], s[30:31], v90, s61, v[88:89]
	v_lshl_add_u64 v[88:89], v[112:113], 1, v[88:89]
	v_cvt_pk_bf16_f32 v84, v84, v85
	v_cvt_pk_bf16_f32 v85, v86, v87
	v_cvt_pk_bf16_f32 v86, v80, v81
	v_cvt_pk_bf16_f32 v87, v82, v83
	global_store_dwordx4 v[88:89], v[84:87], off
	s_nop 0
	s_waitcnt vmcnt(18)
	v_fmamk_f32 v80, v196, 0x3b000000, v161
	v_rsq_f32_e32 v80, v80
	s_nop 0
	v_pk_mul_f32 v[76:77], v[76:77], v[80:81] op_sel_hi:[1,0]
	v_pk_mul_f32 v[78:79], v[78:79], v[80:81] op_sel_hi:[1,0]
	v_pk_mul_f32 v[72:73], v[72:73], v[80:81] op_sel_hi:[1,0]
	v_pk_mul_f32 v[74:75], v[74:75], v[80:81] op_sel_hi:[1,0]
	s_and_saveexec_b64 s[30:31], vcc
	s_cbranch_execz .LBB0_584
	s_nop 0
	v_or_b32_e32 v83, 1, v149
	v_or_b32_e32 v84, 2, v149
	v_or_b32_e32 v85, 3, v149
	v_cvt_f32_u32_e32 v82, v149
	v_cvt_f32_u32_e32 v83, v83
	v_cvt_f32_u32_e32 v84, v84
	v_cvt_f32_u32_e32 v85, v85
	v_mul_f32_e32 v82, 0xbed49a78, v82
	v_mul_f32_e32 v83, 0xbed49a78, v83
	v_mul_f32_e32 v84, 0xbed49a78, v84
	v_mul_f32_e32 v85, 0xbed49a78, v85
	v_exp_f32_e32 v82, v82
	v_exp_f32_e32 v83, v83
	v_exp_f32_e32 v84, v84
	v_exp_f32_e32 v85, v85
	s_waitcnt vmcnt(10)
	v_cvt_f32_i32_e32 v81, v204
	v_mul_f32_e32 v82, v82, v81
	v_mul_f32_e32 v86, v83, v81
	v_mul_f32_e32 v87, v84, v81
	v_mul_f32_e32 v81, v85, v81
	v_cvt_f64_f32_e32 v[82:83], v82
	v_cvt_f64_f32_e32 v[84:85], v86
	v_cvt_f64_f32_e32 v[86:87], v87
	v_cvt_f64_f32_e32 v[88:89], v81
	v_mul_f64 v[90:91], v[82:83], s[20:21]
	v_mul_f64 v[92:93], v[84:85], s[20:21]
	v_mul_f64 v[94:95], v[86:87], s[20:21]
	v_mul_f64 v[96:97], v[88:89], s[20:21]
	v_rndne_f64_e32 v[90:91], v[90:91]
	v_rndne_f64_e32 v[92:93], v[92:93]
	v_rndne_f64_e32 v[94:95], v[94:95]
	v_rndne_f64_e32 v[96:97], v[96:97]
	v_fma_f64 v[82:83], v[82:83], s[20:21], -v[90:91]
	v_fma_f64 v[84:85], v[84:85], s[20:21], -v[92:93]
	v_fma_f64 v[86:87], v[86:87], s[20:21], -v[94:95]
	v_fma_f64 v[88:89], v[88:89], s[20:21], -v[96:97]
	v_cvt_f32_f64_e32 v81, v[82:83]
	v_cvt_f32_f64_e32 v83, v[84:85]
	v_cvt_f32_f64_e32 v85, v[86:87]
	v_cvt_f32_f64_e32 v87, v[88:89]
	v_sin_f32_e32 v82, v81
	v_sin_f32_e32 v86, v83
	v_sin_f32_e32 v90, v85
	v_sin_f32_e32 v95, v87
	v_cos_f32_e32 v94, v87
	v_cos_f32_e32 v84, v81
	v_cos_f32_e32 v88, v83
	v_cos_f32_e32 v92, v85
	v_pk_mul_f32 v[82:83], v[76:77], v[82:83] op_sel:[1,0] op_sel_hi:[0,0]
	v_pk_mul_f32 v[86:87], v[78:79], v[86:87] op_sel:[1,0] op_sel_hi:[0,0]
	v_pk_mul_f32 v[90:91], v[72:73], v[90:91] op_sel:[1,0] op_sel_hi:[0,0]
	v_mul_f32_e32 v98, v75, v95
	v_mov_b32_e32 v100, v95
	v_mov_b32_e32 v101, v94
	v_mul_f32_e32 v102, v75, v94
	v_pk_mul_f32 v[96:97], v[76:77], v[84:85] op_sel_hi:[1,0]
	v_pk_fma_f32 v[76:77], v[76:77], v[84:85], v[82:83] op_sel_hi:[1,0,1]
	v_pk_fma_f32 v[84:85], v[78:79], v[88:89], v[86:87] op_sel_hi:[1,0,1] neg_lo:[0,0,1] neg_hi:[0,0,1]
	v_pk_fma_f32 v[78:79], v[78:79], v[88:89], v[86:87] op_sel_hi:[1,0,1]
	v_pk_fma_f32 v[86:87], v[72:73], v[92:93], v[90:91] op_sel_hi:[1,0,1] neg_lo:[0,0,1] neg_hi:[0,0,1]
	v_pk_fma_f32 v[72:73], v[72:73], v[92:93], v[90:91] op_sel_hi:[1,0,1]
	v_pk_fma_f32 v[88:89], v[74:75], v[94:95], v[98:99] op_sel_hi:[1,1,0] neg_lo:[0,0,1] neg_hi:[0,0,1]
	v_pk_fma_f32 v[90:91], v[74:75], v[100:101], v[102:103] op_sel_hi:[1,1,0]
	v_sub_f32_e32 v76, v96, v82
	v_mov_b32_e32 v78, v84
	v_mov_b32_e32 v72, v86
	v_mov_b32_e32 v74, v88
	v_mov_b32_e32 v75, v90
; __device__ __forceinline__ void store8(bf16_t* dst, const float* v) { u32x4 w; w.x = pk2(v[0], v[1]); w.y = pk2(v[2], v[3]); w.z = pk2(v[4], v[5]); w.w = pk2(v[6], v[7]); *(u32x4*)dst = w; }
;     __device__ __forceinline__ void operator()(const pg8::f32x4 (&acc)[2][2][4][2], const pg8::Unit& u, int wr, int wc, int fr, int fq) const {
;     ...
;                 const int row = u.pm * 256 + ai * 128 + wr * 64 + m * 16 + fr;
;                 const int bb = row >> 13, ss = row & 8191;
;                 float ssq = 0.f;
;                 float rs = 1.f;
;                 if constexpr (KIND == EK_Q || KIND == EK_KV) rs = __builtin_amdgcn_rsqf(a.ssq0[row] * (1.f / 512.f) + EPS);
;     ...
;                         const int c = pn * 256 + cl, h = c / 192, dd = c - h * 192;
; #pragma unroll
;                         for (int j = 0; j < 8; ++j) v[j] *= rs;
;                         if (dd >= 128) {
;                             const int p = a.pos[row];
; #pragma unroll
;                             for (int j = 0; j < 4; ++j) rope_pair(v[2 * j], v[2 * j + 1], p, ((dd - 128) >> 1) + j);
;                         }
;                         store8(a.o0 + ((size_t)((bb * NH + h) * SEQ + ss)) * 192 + dd, v);
.LBB0_584:
	s_or_b64 exec, exec, s[30:31]
	v_bitop3_b32 v82, v148, s64, 48 bitop3:0xc8
	v_or_b32_e32 v83, v163, v82
	v_mov_b64_e32 v[84:85], s[14:15]
	v_mov_b32_e32 v81, v80
	v_mad_i64_i32 v[84:85], s[30:31], v83, s61, v[84:85]
	v_lshl_add_u64 v[84:85], v[144:145], 1, v[84:85]
	v_cvt_pk_bf16_f32 v76, v76, v77
	v_cvt_pk_bf16_f32 v77, v78, v79
	v_cvt_pk_bf16_f32 v78, v72, v73
	v_cvt_pk_bf16_f32 v79, v74, v75
	v_pk_mul_f32 v[68:69], v[68:69], v[80:81]
	v_pk_mul_f32 v[70:71], v[70:71], v[80:81]
	v_pk_mul_f32 v[64:65], v[64:65], v[80:81]
	v_pk_mul_f32 v[66:67], v[66:67], v[80:81]
	global_store_dwordx4 v[84:85], v[76:79], off
	s_and_saveexec_b64 s[30:31], s[6:7]
	s_cbranch_execz .LBB0_586
	s_nop 0
	v_add_u32_e32 v74, 1, v122
	v_add_u32_e32 v75, 2, v122
	v_add_u32_e32 v76, 3, v122
	v_cvt_f32_u32_e32 v73, v122
	v_cvt_f32_u32_e32 v74, v74
	v_cvt_f32_u32_e32 v75, v75
	v_cvt_f32_u32_e32 v76, v76
	v_mul_f32_e32 v73, 0xbed49a78, v73
	v_mul_f32_e32 v74, 0xbed49a78, v74
	v_mul_f32_e32 v75, 0xbed49a78, v75
	v_mul_f32_e32 v76, 0xbed49a78, v76
	v_exp_f32_e32 v73, v73
	v_exp_f32_e32 v74, v74
	v_exp_f32_e32 v75, v75
	v_exp_f32_e32 v76, v76
	s_waitcnt vmcnt(11)
	v_cvt_f32_i32_e32 v72, v204
	v_mul_f32_e32 v73, v73, v72
	v_mul_f32_e32 v74, v74, v72
	v_mul_f32_e32 v77, v75, v72
	v_mul_f32_e32 v78, v76, v72
	v_cvt_f64_f32_e32 v[72:73], v73
	v_cvt_f64_f32_e32 v[74:75], v74
	v_cvt_f64_f32_e32 v[76:77], v77
	v_cvt_f64_f32_e32 v[78:79], v78
	v_mul_f64 v[80:81], v[72:73], s[20:21]
	v_mul_f64 v[84:85], v[74:75], s[20:21]
	v_mul_f64 v[86:87], v[76:77], s[20:21]
	v_mul_f64 v[88:89], v[78:79], s[20:21]
	v_rndne_f64_e32 v[80:81], v[80:81]
	v_rndne_f64_e32 v[84:85], v[84:85]
	v_rndne_f64_e32 v[86:87], v[86:87]
	v_rndne_f64_e32 v[88:89], v[88:89]
	v_fma_f64 v[72:73], v[72:73], s[20:21], -v[80:81]
	v_fma_f64 v[74:75], v[74:75], s[20:21], -v[84:85]
	v_fma_f64 v[76:77], v[76:77], s[20:21], -v[86:87]
	v_fma_f64 v[78:79], v[78:79], s[20:21], -v[88:89]
	v_cvt_f32_f64_e32 v73, v[72:73]
	v_cvt_f32_f64_e32 v75, v[74:75]
	v_cvt_f32_f64_e32 v77, v[76:77]
	v_cvt_f32_f64_e32 v79, v[78:79]
	v_sin_f32_e32 v72, v73
	v_sin_f32_e32 v76, v75
	v_sin_f32_e32 v80, v77
	v_sin_f32_e32 v87, v79
	v_cos_f32_e32 v86, v79
	v_cos_f32_e32 v74, v73
	v_cos_f32_e32 v78, v75
	v_cos_f32_e32 v84, v77
	v_pk_mul_f32 v[72:73], v[68:69], v[72:73] op_sel:[1,0] op_sel_hi:[0,0]
	v_pk_mul_f32 v[76:77], v[70:71], v[76:77] op_sel:[1,0] op_sel_hi:[0,0]
	v_pk_mul_f32 v[80:81], v[64:65], v[80:81] op_sel:[1,0] op_sel_hi:[0,0]
	v_mul_f32_e32 v90, v67, v87
	v_mov_b32_e32 v92, v87
	v_mov_b32_e32 v93, v86
	v_mul_f32_e32 v94, v67, v86
	v_pk_mul_f32 v[88:89], v[68:69], v[74:75] op_sel_hi:[1,0]
	v_pk_fma_f32 v[68:69], v[68:69], v[74:75], v[72:73] op_sel_hi:[1,0,1]
	v_pk_fma_f32 v[74:75], v[70:71], v[78:79], v[76:77] op_sel_hi:[1,0,1] neg_lo:[0,0,1] neg_hi:[0,0,1]
	v_pk_fma_f32 v[70:71], v[70:71], v[78:79], v[76:77] op_sel_hi:[1,0,1]
	v_pk_fma_f32 v[76:77], v[64:65], v[84:85], v[80:81] op_sel_hi:[1,0,1] neg_lo:[0,0,1] neg_hi:[0,0,1]
	v_pk_fma_f32 v[64:65], v[64:65], v[84:85], v[80:81] op_sel_hi:[1,0,1]
	v_pk_fma_f32 v[78:79], v[66:67], v[86:87], v[90:91] op_sel_hi:[1,1,0] neg_lo:[0,0,1] neg_hi:[0,0,1]
	v_pk_fma_f32 v[80:81], v[66:67], v[92:93], v[94:95] op_sel_hi:[1,1,0]
	v_sub_f32_e32 v68, v88, v72
	v_mov_b32_e32 v70, v74
	v_mov_b32_e32 v64, v76
	v_mov_b32_e32 v66, v78
	v_mov_b32_e32 v67, v80
.LBB0_586:
	s_or_b64 exec, exec, s[30:31]
	v_or_b32_e32 v74, v124, v82
	v_mov_b64_e32 v[72:73], s[14:15]
	s_addk_i32 s23, 0x80
	v_mad_i64_i32 v[72:73], s[30:31], v74, s61, v[72:73]
	v_cvt_pk_bf16_f32 v68, v68, v69
	v_cvt_pk_bf16_f32 v69, v70, v71
	v_cvt_pk_bf16_f32 v70, v64, v65
	v_or_b32_e32 v64, s23, v153
	v_lshl_add_u64 v[72:73], v[112:113], 1, v[72:73]
	v_cvt_pk_bf16_f32 v71, v66, v67
	v_ashrrev_i32_e32 v65, 31, v64
	global_store_dwordx4 v[72:73], v[68:71], off
	v_lshl_add_u64 v[66:67], v[64:65], 2, s[8:9]
	s_nop 0
	s_waitcnt vmcnt(19)
	v_fmamk_f32 v68, v197, 0x3b000000, v161
	v_rsq_f32_e32 v68, v68
	s_nop 0
	v_pk_mul_f32 v[60:61], v[60:61], v[68:69] op_sel_hi:[1,0]
	v_pk_mul_f32 v[62:63], v[62:63], v[68:69] op_sel_hi:[1,0]
	v_pk_mul_f32 v[70:71], v[56:57], v[68:69] op_sel_hi:[1,0]
	v_pk_mul_f32 v[58:59], v[58:59], v[68:69] op_sel_hi:[1,0]
	v_lshl_add_u64 v[56:57], v[64:65], 2, s[10:11]
	s_and_saveexec_b64 s[30:31], vcc
	s_cbranch_execz .LBB0_588
	s_nop 0
	v_or_b32_e32 v72, 1, v149
	v_or_b32_e32 v73, 2, v149
	v_or_b32_e32 v74, 3, v149
	v_cvt_f32_u32_e32 v69, v149
	v_cvt_f32_u32_e32 v72, v72
	v_cvt_f32_u32_e32 v73, v73
	v_cvt_f32_u32_e32 v74, v74
	v_mul_f32_e32 v69, 0xbed49a78, v69
	v_mul_f32_e32 v72, 0xbed49a78, v72
	v_mul_f32_e32 v73, 0xbed49a78, v73
	v_mul_f32_e32 v74, 0xbed49a78, v74
	v_exp_f32_e32 v69, v69
	v_exp_f32_e32 v72, v72
	v_exp_f32_e32 v73, v73
	v_exp_f32_e32 v74, v74
	s_waitcnt vmcnt(11)
	v_cvt_f32_i32_e32 v65, v205
	v_mul_f32_e32 v69, v69, v65
	v_mul_f32_e32 v75, v72, v65
	v_mul_f32_e32 v76, v73, v65
	v_mul_f32_e32 v65, v74, v65
	v_cvt_f64_f32_e32 v[72:73], v69
	v_cvt_f64_f32_e32 v[74:75], v75
	v_cvt_f64_f32_e32 v[76:77], v76
	v_cvt_f64_f32_e32 v[78:79], v65
	v_mul_f64 v[80:81], v[72:73], s[20:21]
	v_mul_f64 v[82:83], v[74:75], s[20:21]
	v_mul_f64 v[84:85], v[76:77], s[20:21]
	v_mul_f64 v[86:87], v[78:79], s[20:21]
	v_rndne_f64_e32 v[80:81], v[80:81]
	v_rndne_f64_e32 v[82:83], v[82:83]
	v_rndne_f64_e32 v[84:85], v[84:85]
	v_rndne_f64_e32 v[86:87], v[86:87]
	v_fma_f64 v[72:73], v[72:73], s[20:21], -v[80:81]
	v_fma_f64 v[74:75], v[74:75], s[20:21], -v[82:83]
	v_fma_f64 v[76:77], v[76:77], s[20:21], -v[84:85]
	v_fma_f64 v[78:79], v[78:79], s[20:21], -v[86:87]
	v_cvt_f32_f64_e32 v65, v[72:73]
	v_cvt_f32_f64_e32 v69, v[74:75]
	v_cvt_f32_f64_e32 v73, v[76:77]
	v_cvt_f32_f64_e32 v75, v[78:79]
	v_sin_f32_e32 v72, v65
	v_sin_f32_e32 v76, v69
	v_sin_f32_e32 v80, v73
	v_sin_f32_e32 v85, v75
	v_cos_f32_e32 v84, v75
	v_cos_f32_e32 v74, v65
	v_cos_f32_e32 v78, v69
	v_cos_f32_e32 v82, v73
	v_pk_mul_f32 v[72:73], v[60:61], v[72:73] op_sel:[1,0] op_sel_hi:[0,0]
	v_pk_mul_f32 v[76:77], v[62:63], v[76:77] op_sel:[1,0] op_sel_hi:[0,0]
	v_pk_mul_f32 v[80:81], v[70:71], v[80:81] op_sel:[1,0] op_sel_hi:[0,0]
	v_mul_f32_e32 v88, v59, v85
	v_mov_b32_e32 v90, v85
	v_mov_b32_e32 v91, v84
	v_mul_f32_e32 v92, v59, v84
	v_pk_mul_f32 v[86:87], v[60:61], v[74:75] op_sel_hi:[1,0]
	v_pk_fma_f32 v[60:61], v[60:61], v[74:75], v[72:73] op_sel_hi:[1,0,1]
	v_pk_fma_f32 v[74:75], v[62:63], v[78:79], v[76:77] op_sel_hi:[1,0,1] neg_lo:[0,0,1] neg_hi:[0,0,1]
	v_pk_fma_f32 v[62:63], v[62:63], v[78:79], v[76:77] op_sel_hi:[1,0,1]
	v_pk_fma_f32 v[76:77], v[70:71], v[82:83], v[80:81] op_sel_hi:[1,0,1] neg_lo:[0,0,1] neg_hi:[0,0,1]
	v_pk_fma_f32 v[70:71], v[70:71], v[82:83], v[80:81] op_sel_hi:[1,0,1]
	v_pk_fma_f32 v[78:79], v[58:59], v[84:85], v[88:89] op_sel_hi:[1,1,0] neg_lo:[0,0,1] neg_hi:[0,0,1]
	v_pk_fma_f32 v[80:81], v[58:59], v[90:91], v[92:93] op_sel_hi:[1,1,0]
	v_sub_f32_e32 v60, v86, v72
	v_mov_b32_e32 v62, v74
	v_mov_b32_e32 v70, v76
	v_mov_b32_e32 v58, v78
	v_mov_b32_e32 v59, v80
; __device__ __forceinline__ void store8(bf16_t* dst, const float* v) { u32x4 w; w.x = pk2(v[0], v[1]); w.y = pk2(v[2], v[3]); w.z = pk2(v[4], v[5]); w.w = pk2(v[6], v[7]); *(u32x4*)dst = w; }
;     __device__ __forceinline__ void operator()(const pg8::f32x4 (&acc)[2][2][4][2], const pg8::Unit& u, int wr, int wc, int fr, int fq) const {
;     ...
;                 const int row = u.pm * 256 + ai * 128 + wr * 64 + m * 16 + fr;
;                 const int bb = row >> 13, ss = row & 8191;
;                 float ssq = 0.f;
;                 float rs = 1.f;
;                 if constexpr (KIND == EK_Q || KIND == EK_KV) rs = __builtin_amdgcn_rsqf(a.ssq0[row] * (1.f / 512.f) + EPS);
;     ...
;                         const int c = pn * 256 + cl, h = c / 192, dd = c - h * 192;
; #pragma unroll
;                         for (int j = 0; j < 8; ++j) v[j] *= rs;
;                         if (dd >= 128) {
;                             const int p = a.pos[row];
; #pragma unroll
;                             for (int j = 0; j < 4; ++j) rope_pair(v[2 * j], v[2 * j + 1], p, ((dd - 128) >> 1) + j);
;                         }
;                         store8(a.o0 + ((size_t)((bb * NH + h) * SEQ + ss)) * 192 + dd, v);
.LBB0_588:
	s_or_b64 exec, exec, s[30:31]
	s_ashr_i32 s23, s23, 10
	s_and_b32 s23, s23, -8
	v_and_b32_e32 v72, 0x1fcf, v64
	v_add_lshl_u32 v65, s23, v162, 13
	v_or_b32_e32 v73, v65, v72
	v_mov_b64_e32 v[74:75], s[14:15]
	v_mov_b32_e32 v69, v68
	v_mad_i64_i32 v[74:75], s[30:31], v73, s61, v[74:75]
	v_lshl_add_u64 v[74:75], v[144:145], 1, v[74:75]
	v_cvt_pk_bf16_f32 v60, v60, v61
	v_cvt_pk_bf16_f32 v61, v62, v63
	v_cvt_pk_bf16_f32 v62, v70, v71
	v_cvt_pk_bf16_f32 v63, v58, v59
	v_pk_mul_f32 v[52:53], v[52:53], v[68:69]
	v_pk_mul_f32 v[54:55], v[54:55], v[68:69]
	v_pk_mul_f32 v[48:49], v[48:49], v[68:69]
	v_pk_mul_f32 v[50:51], v[50:51], v[68:69]
	global_store_dwordx4 v[74:75], v[60:63], off
	s_and_saveexec_b64 s[30:31], s[6:7]
	s_cbranch_execz .LBB0_590
	s_nop 0
	v_add_u32_e32 v60, 1, v122
	v_add_u32_e32 v61, 2, v122
	v_add_u32_e32 v62, 3, v122
	v_cvt_f32_u32_e32 v59, v122
	v_cvt_f32_u32_e32 v60, v60
	v_cvt_f32_u32_e32 v61, v61
	v_cvt_f32_u32_e32 v62, v62
	v_mul_f32_e32 v59, 0xbed49a78, v59
	v_mul_f32_e32 v60, 0xbed49a78, v60
	v_mul_f32_e32 v61, 0xbed49a78, v61
	v_mul_f32_e32 v62, 0xbed49a78, v62
	v_exp_f32_e32 v59, v59
	v_exp_f32_e32 v60, v60
	v_exp_f32_e32 v61, v61
	v_exp_f32_e32 v62, v62
	s_waitcnt vmcnt(12)
	v_cvt_f32_i32_e32 v58, v205
	v_mul_f32_e32 v59, v59, v58
	v_mul_f32_e32 v60, v60, v58
	v_mul_f32_e32 v63, v61, v58
	v_mul_f32_e32 v68, v62, v58
	v_cvt_f64_f32_e32 v[58:59], v59
	v_cvt_f64_f32_e32 v[60:61], v60
	v_cvt_f64_f32_e32 v[62:63], v63
	v_cvt_f64_f32_e32 v[68:69], v68
	v_mul_f64 v[70:71], v[58:59], s[20:21]
	v_mul_f64 v[74:75], v[60:61], s[20:21]
	v_mul_f64 v[76:77], v[62:63], s[20:21]
	v_mul_f64 v[78:79], v[68:69], s[20:21]
	v_rndne_f64_e32 v[70:71], v[70:71]
	v_rndne_f64_e32 v[74:75], v[74:75]
	v_rndne_f64_e32 v[76:77], v[76:77]
	v_rndne_f64_e32 v[78:79], v[78:79]
	v_fma_f64 v[58:59], v[58:59], s[20:21], -v[70:71]
	v_fma_f64 v[60:61], v[60:61], s[20:21], -v[74:75]
	v_fma_f64 v[62:63], v[62:63], s[20:21], -v[76:77]
	v_fma_f64 v[68:69], v[68:69], s[20:21], -v[78:79]
	v_cvt_f32_f64_e32 v59, v[58:59]
	v_cvt_f32_f64_e32 v61, v[60:61]
	v_cvt_f32_f64_e32 v63, v[62:63]
	v_cvt_f32_f64_e32 v69, v[68:69]
	v_sin_f32_e32 v58, v59
	v_sin_f32_e32 v62, v61
	v_sin_f32_e32 v70, v63
	v_sin_f32_e32 v77, v69
	v_cos_f32_e32 v76, v69
	v_cos_f32_e32 v60, v59
	v_cos_f32_e32 v68, v61
	v_cos_f32_e32 v74, v63
	v_pk_mul_f32 v[58:59], v[52:53], v[58:59] op_sel:[1,0] op_sel_hi:[0,0]
	v_pk_mul_f32 v[62:63], v[54:55], v[62:63] op_sel:[1,0] op_sel_hi:[0,0]
	v_pk_mul_f32 v[70:71], v[48:49], v[70:71] op_sel:[1,0] op_sel_hi:[0,0]
	v_mul_f32_e32 v80, v51, v77
	v_mov_b32_e32 v82, v77
	v_mov_b32_e32 v83, v76
	v_mul_f32_e32 v84, v51, v76
	v_pk_mul_f32 v[78:79], v[52:53], v[60:61] op_sel_hi:[1,0]
	v_pk_fma_f32 v[52:53], v[52:53], v[60:61], v[58:59] op_sel_hi:[1,0,1]
	v_pk_fma_f32 v[60:61], v[54:55], v[68:69], v[62:63] op_sel_hi:[1,0,1] neg_lo:[0,0,1] neg_hi:[0,0,1]
	v_pk_fma_f32 v[54:55], v[54:55], v[68:69], v[62:63] op_sel_hi:[1,0,1]
	v_pk_fma_f32 v[62:63], v[48:49], v[74:75], v[70:71] op_sel_hi:[1,0,1] neg_lo:[0,0,1] neg_hi:[0,0,1]
	v_pk_fma_f32 v[48:49], v[48:49], v[74:75], v[70:71] op_sel_hi:[1,0,1]
	v_pk_fma_f32 v[68:69], v[50:51], v[76:77], v[80:81] op_sel_hi:[1,1,0] neg_lo:[0,0,1] neg_hi:[0,0,1]
	v_pk_fma_f32 v[70:71], v[50:51], v[82:83], v[84:85] op_sel_hi:[1,1,0]
	v_sub_f32_e32 v52, v78, v58
	v_mov_b32_e32 v54, v60
	v_mov_b32_e32 v48, v62
	v_mov_b32_e32 v50, v68
	v_mov_b32_e32 v51, v70
.LBB0_590:
	s_or_b64 exec, exec, s[30:31]
	v_add_lshl_u32 v58, s23, v123, 13
	v_or_b32_e32 v59, v58, v72
	v_mov_b64_e32 v[60:61], s[14:15]
	v_mad_i64_i32 v[60:61], s[30:31], v59, s61, v[60:61]
	v_lshl_add_u64 v[60:61], v[112:113], 1, v[60:61]
	v_cvt_pk_bf16_f32 v52, v52, v53
	v_cvt_pk_bf16_f32 v53, v54, v55
	v_cvt_pk_bf16_f32 v54, v48, v49
	v_cvt_pk_bf16_f32 v55, v50, v51
	global_store_dwordx4 v[60:61], v[52:55], off
	s_nop 0
	s_waitcnt vmcnt(20)
	v_fmamk_f32 v48, v198, 0x3b000000, v161
	v_rsq_f32_e32 v48, v48
	s_nop 0
	v_pk_mul_f32 v[44:45], v[44:45], v[48:49] op_sel_hi:[1,0]
	v_pk_mul_f32 v[46:47], v[46:47], v[48:49] op_sel_hi:[1,0]
	v_pk_mul_f32 v[40:41], v[40:41], v[48:49] op_sel_hi:[1,0]
	v_pk_mul_f32 v[42:43], v[42:43], v[48:49] op_sel_hi:[1,0]
	s_and_saveexec_b64 s[30:31], vcc
	s_cbranch_execz .LBB0_592
	s_nop 0
	v_or_b32_e32 v51, 1, v149
	v_or_b32_e32 v52, 2, v149
	v_or_b32_e32 v53, 3, v149
	v_cvt_f32_u32_e32 v50, v149
	v_cvt_f32_u32_e32 v51, v51
	v_cvt_f32_u32_e32 v52, v52
	v_cvt_f32_u32_e32 v53, v53
	v_mul_f32_e32 v50, 0xbed49a78, v50
	v_mul_f32_e32 v51, 0xbed49a78, v51
	v_mul_f32_e32 v52, 0xbed49a78, v52
	v_mul_f32_e32 v53, 0xbed49a78, v53
	v_exp_f32_e32 v50, v50
	v_exp_f32_e32 v51, v51
	v_exp_f32_e32 v52, v52
	v_exp_f32_e32 v53, v53
	s_waitcnt vmcnt(12)
	v_cvt_f32_i32_e32 v49, v206
	v_mul_f32_e32 v50, v50, v49
	v_mul_f32_e32 v54, v51, v49
	v_mul_f32_e32 v55, v52, v49
	v_mul_f32_e32 v49, v53, v49
	v_cvt_f64_f32_e32 v[50:51], v50
	v_cvt_f64_f32_e32 v[52:53], v54
	v_cvt_f64_f32_e32 v[54:55], v55
	v_cvt_f64_f32_e32 v[60:61], v49
	v_mul_f64 v[62:63], v[50:51], s[20:21]
	v_mul_f64 v[68:69], v[52:53], s[20:21]
	v_mul_f64 v[70:71], v[54:55], s[20:21]
	v_mul_f64 v[72:73], v[60:61], s[20:21]
	v_rndne_f64_e32 v[62:63], v[62:63]
	v_rndne_f64_e32 v[68:69], v[68:69]
	v_rndne_f64_e32 v[70:71], v[70:71]
	v_rndne_f64_e32 v[72:73], v[72:73]
	v_fma_f64 v[50:51], v[50:51], s[20:21], -v[62:63]
	v_fma_f64 v[52:53], v[52:53], s[20:21], -v[68:69]
	v_fma_f64 v[54:55], v[54:55], s[20:21], -v[70:71]
	v_fma_f64 v[60:61], v[60:61], s[20:21], -v[72:73]
	v_cvt_f32_f64_e32 v49, v[50:51]
	v_cvt_f32_f64_e32 v51, v[52:53]
	v_cvt_f32_f64_e32 v53, v[54:55]
	v_cvt_f32_f64_e32 v55, v[60:61]
	v_sin_f32_e32 v50, v49
	v_sin_f32_e32 v54, v51
	v_sin_f32_e32 v62, v53
	v_sin_f32_e32 v71, v55
	v_cos_f32_e32 v70, v55
	v_cos_f32_e32 v52, v49
	v_cos_f32_e32 v60, v51
	v_cos_f32_e32 v68, v53
	v_pk_mul_f32 v[50:51], v[44:45], v[50:51] op_sel:[1,0] op_sel_hi:[0,0]
	v_pk_mul_f32 v[54:55], v[46:47], v[54:55] op_sel:[1,0] op_sel_hi:[0,0]
	v_pk_mul_f32 v[62:63], v[40:41], v[62:63] op_sel:[1,0] op_sel_hi:[0,0]
	v_mul_f32_e32 v74, v43, v71
	v_mov_b32_e32 v76, v71
	v_mov_b32_e32 v77, v70
	v_mul_f32_e32 v78, v43, v70
	v_pk_mul_f32 v[72:73], v[44:45], v[52:53] op_sel_hi:[1,0]
	v_pk_fma_f32 v[44:45], v[44:45], v[52:53], v[50:51] op_sel_hi:[1,0,1]
	v_pk_fma_f32 v[52:53], v[46:47], v[60:61], v[54:55] op_sel_hi:[1,0,1] neg_lo:[0,0,1] neg_hi:[0,0,1]
	v_pk_fma_f32 v[46:47], v[46:47], v[60:61], v[54:55] op_sel_hi:[1,0,1]
	v_pk_fma_f32 v[54:55], v[40:41], v[68:69], v[62:63] op_sel_hi:[1,0,1] neg_lo:[0,0,1] neg_hi:[0,0,1]
	v_pk_fma_f32 v[40:41], v[40:41], v[68:69], v[62:63] op_sel_hi:[1,0,1]
	v_pk_fma_f32 v[60:61], v[42:43], v[70:71], v[74:75] op_sel_hi:[1,1,0] neg_lo:[0,0,1] neg_hi:[0,0,1]
	v_pk_fma_f32 v[62:63], v[42:43], v[76:77], v[78:79] op_sel_hi:[1,1,0]
	v_sub_f32_e32 v44, v72, v50
	v_mov_b32_e32 v46, v52
	v_mov_b32_e32 v40, v54
	v_mov_b32_e32 v42, v60
	v_mov_b32_e32 v43, v62
; __device__ __forceinline__ void store8(bf16_t* dst, const float* v) { u32x4 w; w.x = pk2(v[0], v[1]); w.y = pk2(v[2], v[3]); w.z = pk2(v[4], v[5]); w.w = pk2(v[6], v[7]); *(u32x4*)dst = w; }
;     __device__ __forceinline__ void operator()(const pg8::f32x4 (&acc)[2][2][4][2], const pg8::Unit& u, int wr, int wc, int fr, int fq) const {
;     ...
;                 const int row = u.pm * 256 + ai * 128 + wr * 64 + m * 16 + fr;
;                 const int bb = row >> 13, ss = row & 8191;
;                 float ssq = 0.f;
;                 float rs = 1.f;
;                 if constexpr (KIND == EK_Q || KIND == EK_KV) rs = __builtin_amdgcn_rsqf(a.ssq0[row] * (1.f / 512.f) + EPS);
;     ...
;                         const int c = pn * 256 + cl, h = c / 192, dd = c - h * 192;
; #pragma unroll
;                         for (int j = 0; j < 8; ++j) v[j] *= rs;
;                         if (dd >= 128) {
;                             const int p = a.pos[row];
; #pragma unroll
;                             for (int j = 0; j < 4; ++j) rope_pair(v[2 * j], v[2 * j + 1], p, ((dd - 128) >> 1) + j);
;                         }
;                         store8(a.o0 + ((size_t)((bb * NH + h) * SEQ + ss)) * 192 + dd, v);
.LBB0_592:
	s_or_b64 exec, exec, s[30:31]
	v_bitop3_b32 v50, v64, s62, 16 bitop3:0xc8
	v_or_b32_e32 v51, v65, v50
	v_mov_b64_e32 v[52:53], s[14:15]
	v_mov_b32_e32 v49, v48
	v_mad_i64_i32 v[52:53], s[30:31], v51, s61, v[52:53]
	v_lshl_add_u64 v[52:53], v[144:145], 1, v[52:53]
	v_cvt_pk_bf16_f32 v44, v44, v45
	v_cvt_pk_bf16_f32 v45, v46, v47
	v_cvt_pk_bf16_f32 v46, v40, v41
	v_cvt_pk_bf16_f32 v47, v42, v43
	v_pk_mul_f32 v[36:37], v[36:37], v[48:49]
	v_pk_mul_f32 v[38:39], v[38:39], v[48:49]
	v_pk_mul_f32 v[32:33], v[32:33], v[48:49]
	v_pk_mul_f32 v[34:35], v[34:35], v[48:49]
	global_store_dwordx4 v[52:53], v[44:47], off
	s_and_saveexec_b64 s[30:31], s[6:7]
	s_cbranch_execz .LBB0_594
	s_nop 0
	v_add_u32_e32 v42, 1, v122
	v_add_u32_e32 v43, 2, v122
	v_add_u32_e32 v44, 3, v122
	v_cvt_f32_u32_e32 v41, v122
	v_cvt_f32_u32_e32 v42, v42
	v_cvt_f32_u32_e32 v43, v43
	v_cvt_f32_u32_e32 v44, v44
	v_mul_f32_e32 v41, 0xbed49a78, v41
	v_mul_f32_e32 v42, 0xbed49a78, v42
	v_mul_f32_e32 v43, 0xbed49a78, v43
	v_mul_f32_e32 v44, 0xbed49a78, v44
	v_exp_f32_e32 v41, v41
	v_exp_f32_e32 v42, v42
	v_exp_f32_e32 v43, v43
	v_exp_f32_e32 v44, v44
	s_waitcnt vmcnt(13)
	v_cvt_f32_i32_e32 v40, v206
	v_mul_f32_e32 v41, v41, v40
	v_mul_f32_e32 v42, v42, v40
	v_mul_f32_e32 v45, v43, v40
	v_mul_f32_e32 v46, v44, v40
	v_cvt_f64_f32_e32 v[40:41], v41
	v_cvt_f64_f32_e32 v[42:43], v42
	v_cvt_f64_f32_e32 v[44:45], v45
	v_cvt_f64_f32_e32 v[46:47], v46
	v_mul_f64 v[48:49], v[40:41], s[20:21]
	v_mul_f64 v[52:53], v[42:43], s[20:21]
	v_mul_f64 v[54:55], v[44:45], s[20:21]
	v_mul_f64 v[60:61], v[46:47], s[20:21]
	v_rndne_f64_e32 v[48:49], v[48:49]
	v_rndne_f64_e32 v[52:53], v[52:53]
	v_rndne_f64_e32 v[54:55], v[54:55]
	v_rndne_f64_e32 v[60:61], v[60:61]
	v_fma_f64 v[40:41], v[40:41], s[20:21], -v[48:49]
	v_fma_f64 v[42:43], v[42:43], s[20:21], -v[52:53]
	v_fma_f64 v[44:45], v[44:45], s[20:21], -v[54:55]
	v_fma_f64 v[46:47], v[46:47], s[20:21], -v[60:61]
	v_cvt_f32_f64_e32 v41, v[40:41]
	v_cvt_f32_f64_e32 v43, v[42:43]
	v_cvt_f32_f64_e32 v45, v[44:45]
	v_cvt_f32_f64_e32 v47, v[46:47]
	v_sin_f32_e32 v40, v41
	v_sin_f32_e32 v44, v43
	v_sin_f32_e32 v48, v45
	v_sin_f32_e32 v55, v47
	v_cos_f32_e32 v54, v47
	v_cos_f32_e32 v42, v41
	v_cos_f32_e32 v46, v43
	v_cos_f32_e32 v52, v45
	v_pk_mul_f32 v[40:41], v[36:37], v[40:41] op_sel:[1,0] op_sel_hi:[0,0]
	v_pk_mul_f32 v[44:45], v[38:39], v[44:45] op_sel:[1,0] op_sel_hi:[0,0]
	v_pk_mul_f32 v[48:49], v[32:33], v[48:49] op_sel:[1,0] op_sel_hi:[0,0]
	v_mul_f32_e32 v62, v35, v55
	v_mov_b32_e32 v68, v55
	v_mov_b32_e32 v69, v54
	v_mul_f32_e32 v70, v35, v54
	v_pk_mul_f32 v[60:61], v[36:37], v[42:43] op_sel_hi:[1,0]
	v_pk_fma_f32 v[36:37], v[36:37], v[42:43], v[40:41] op_sel_hi:[1,0,1]
	v_pk_fma_f32 v[42:43], v[38:39], v[46:47], v[44:45] op_sel_hi:[1,0,1] neg_lo:[0,0,1] neg_hi:[0,0,1]
	v_pk_fma_f32 v[38:39], v[38:39], v[46:47], v[44:45] op_sel_hi:[1,0,1]
	v_pk_fma_f32 v[44:45], v[32:33], v[52:53], v[48:49] op_sel_hi:[1,0,1] neg_lo:[0,0,1] neg_hi:[0,0,1]
	v_pk_fma_f32 v[32:33], v[32:33], v[52:53], v[48:49] op_sel_hi:[1,0,1]
	v_pk_fma_f32 v[46:47], v[34:35], v[54:55], v[62:63] op_sel_hi:[1,1,0] neg_lo:[0,0,1] neg_hi:[0,0,1]
	v_pk_fma_f32 v[48:49], v[34:35], v[68:69], v[70:71] op_sel_hi:[1,1,0]
	v_sub_f32_e32 v36, v60, v40
	v_mov_b32_e32 v38, v42
	v_mov_b32_e32 v32, v44
	v_mov_b32_e32 v34, v46
	v_mov_b32_e32 v35, v48
.LBB0_594:
	s_or_b64 exec, exec, s[30:31]
	v_or_b32_e32 v42, v58, v50
	v_mov_b64_e32 v[40:41], s[14:15]
	v_mad_i64_i32 v[40:41], s[30:31], v42, s61, v[40:41]
	v_lshl_add_u64 v[40:41], v[112:113], 1, v[40:41]
	v_cvt_pk_bf16_f32 v36, v36, v37
	v_cvt_pk_bf16_f32 v37, v38, v39
	v_cvt_pk_bf16_f32 v38, v32, v33
	v_cvt_pk_bf16_f32 v39, v34, v35
	global_store_dwordx4 v[40:41], v[36:39], off
	s_nop 0
	s_waitcnt vmcnt(21)
	v_fmamk_f32 v32, v199, 0x3b000000, v161
	v_rsq_f32_e32 v32, v32
	s_nop 0
	v_pk_mul_f32 v[28:29], v[28:29], v[32:33] op_sel_hi:[1,0]
	v_pk_mul_f32 v[30:31], v[30:31], v[32:33] op_sel_hi:[1,0]
	v_pk_mul_f32 v[24:25], v[24:25], v[32:33] op_sel_hi:[1,0]
	v_pk_mul_f32 v[26:27], v[26:27], v[32:33] op_sel_hi:[1,0]
	s_and_saveexec_b64 s[30:31], vcc
	s_cbranch_execz .LBB0_596
	s_nop 0
	v_or_b32_e32 v35, 1, v149
	v_or_b32_e32 v36, 2, v149
	v_or_b32_e32 v37, 3, v149
	v_cvt_f32_u32_e32 v34, v149
	v_cvt_f32_u32_e32 v35, v35
	v_cvt_f32_u32_e32 v36, v36
	v_cvt_f32_u32_e32 v37, v37
	v_mul_f32_e32 v34, 0xbed49a78, v34
	v_mul_f32_e32 v35, 0xbed49a78, v35
	v_mul_f32_e32 v36, 0xbed49a78, v36
	v_mul_f32_e32 v37, 0xbed49a78, v37
	v_exp_f32_e32 v34, v34
	v_exp_f32_e32 v35, v35
	v_exp_f32_e32 v36, v36
	v_exp_f32_e32 v37, v37
	s_waitcnt vmcnt(13)
	v_cvt_f32_i32_e32 v33, v207
	v_mul_f32_e32 v34, v34, v33
	v_mul_f32_e32 v38, v35, v33
	v_mul_f32_e32 v39, v36, v33
	v_mul_f32_e32 v33, v37, v33
	v_cvt_f64_f32_e32 v[34:35], v34
	v_cvt_f64_f32_e32 v[36:37], v38
	v_cvt_f64_f32_e32 v[38:39], v39
	v_cvt_f64_f32_e32 v[40:41], v33
	v_mul_f64 v[42:43], v[34:35], s[20:21]
	v_mul_f64 v[44:45], v[36:37], s[20:21]
	v_mul_f64 v[46:47], v[38:39], s[20:21]
	v_mul_f64 v[48:49], v[40:41], s[20:21]
	v_rndne_f64_e32 v[42:43], v[42:43]
	v_rndne_f64_e32 v[44:45], v[44:45]
	v_rndne_f64_e32 v[46:47], v[46:47]
	v_rndne_f64_e32 v[48:49], v[48:49]
	v_fma_f64 v[34:35], v[34:35], s[20:21], -v[42:43]
	v_fma_f64 v[36:37], v[36:37], s[20:21], -v[44:45]
	v_fma_f64 v[38:39], v[38:39], s[20:21], -v[46:47]
	v_fma_f64 v[40:41], v[40:41], s[20:21], -v[48:49]
	v_cvt_f32_f64_e32 v33, v[34:35]
	v_cvt_f32_f64_e32 v35, v[36:37]
	v_cvt_f32_f64_e32 v37, v[38:39]
	v_cvt_f32_f64_e32 v39, v[40:41]
	v_sin_f32_e32 v34, v33
	v_sin_f32_e32 v38, v35
	v_sin_f32_e32 v42, v37
	v_sin_f32_e32 v47, v39
	v_cos_f32_e32 v46, v39
	v_cos_f32_e32 v36, v33
	v_cos_f32_e32 v40, v35
	v_cos_f32_e32 v44, v37
	v_pk_mul_f32 v[34:35], v[28:29], v[34:35] op_sel:[1,0] op_sel_hi:[0,0]
	v_pk_mul_f32 v[38:39], v[30:31], v[38:39] op_sel:[1,0] op_sel_hi:[0,0]
	v_pk_mul_f32 v[42:43], v[24:25], v[42:43] op_sel:[1,0] op_sel_hi:[0,0]
	v_mul_f32_e32 v50, v27, v47
	v_mov_b32_e32 v52, v47
	v_mov_b32_e32 v53, v46
	v_mul_f32_e32 v54, v27, v46
	v_pk_mul_f32 v[48:49], v[28:29], v[36:37] op_sel_hi:[1,0]
	v_pk_fma_f32 v[28:29], v[28:29], v[36:37], v[34:35] op_sel_hi:[1,0,1]
	v_pk_fma_f32 v[36:37], v[30:31], v[40:41], v[38:39] op_sel_hi:[1,0,1] neg_lo:[0,0,1] neg_hi:[0,0,1]
	v_pk_fma_f32 v[30:31], v[30:31], v[40:41], v[38:39] op_sel_hi:[1,0,1]
	v_pk_fma_f32 v[38:39], v[24:25], v[44:45], v[42:43] op_sel_hi:[1,0,1] neg_lo:[0,0,1] neg_hi:[0,0,1]
	v_pk_fma_f32 v[24:25], v[24:25], v[44:45], v[42:43] op_sel_hi:[1,0,1]
	v_pk_fma_f32 v[40:41], v[26:27], v[46:47], v[50:51] op_sel_hi:[1,1,0] neg_lo:[0,0,1] neg_hi:[0,0,1]
	v_pk_fma_f32 v[42:43], v[26:27], v[52:53], v[54:55] op_sel_hi:[1,1,0]
	v_sub_f32_e32 v28, v48, v34
	v_mov_b32_e32 v30, v36
	v_mov_b32_e32 v24, v38
	v_mov_b32_e32 v26, v40
	v_mov_b32_e32 v27, v42
; __device__ __forceinline__ void store8(bf16_t* dst, const float* v) { u32x4 w; w.x = pk2(v[0], v[1]); w.y = pk2(v[2], v[3]); w.z = pk2(v[4], v[5]); w.w = pk2(v[6], v[7]); *(u32x4*)dst = w; }
; __device__ __forceinline__ void rope_pair(float& a, float& b, int pos, int i) {
;     const float inv = __builtin_amdgcn_exp2f(-(float)i * 0.41524101186092029f);
;     const float ang = (float)pos * inv;
;     double rev = (double)ang * 0.15915494309189535;
;     rev -= __builtin_rint(rev);
;     const float fr = (float)rev;
;     const float s = __builtin_amdgcn_sinf(fr), c = __builtin_amdgcn_cosf(fr);
;     const float na = a * c - b * s, nb = a * s + b * c; a = na; b = nb;
; }
;     __device__ __forceinline__ void operator()(const pg8::f32x4 (&acc)[2][2][4][2], const pg8::Unit& u, int wr, int wc, int fr, int fq) const {
;     ...
;                         const int c = pn * 256 + cl, h = c / 192, dd = c - h * 192;
; #pragma unroll
;                         for (int j = 0; j < 8; ++j) v[j] *= rs;
;                         if (dd >= 128) {
;                             const int p = a.pos[row];
; #pragma unroll
;                             for (int j = 0; j < 4; ++j) rope_pair(v[2 * j], v[2 * j + 1], p, ((dd - 128) >> 1) + j);
;                         }
;                         store8(a.o0 + ((size_t)((bb * NH + h) * SEQ + ss)) * 192 + dd, v);
.LBB0_596:
	s_or_b64 exec, exec, s[30:31]
	v_bitop3_b32 v34, v64, s63, 32 bitop3:0xc8
	v_or_b32_e32 v35, v65, v34
	v_mov_b64_e32 v[36:37], s[14:15]
	v_mov_b32_e32 v33, v32
	v_mad_i64_i32 v[36:37], s[30:31], v35, s61, v[36:37]
	v_lshl_add_u64 v[36:37], v[144:145], 1, v[36:37]
	v_cvt_pk_bf16_f32 v28, v28, v29
	v_cvt_pk_bf16_f32 v29, v30, v31
	v_cvt_pk_bf16_f32 v30, v24, v25
	v_cvt_pk_bf16_f32 v31, v26, v27
	v_pk_mul_f32 v[20:21], v[20:21], v[32:33]
	v_pk_mul_f32 v[22:23], v[22:23], v[32:33]
	v_pk_mul_f32 v[16:17], v[16:17], v[32:33]
	v_pk_mul_f32 v[18:19], v[18:19], v[32:33]
	global_store_dwordx4 v[36:37], v[28:31], off
	s_and_saveexec_b64 s[30:31], s[6:7]
	s_cbranch_execz .LBB0_598
	s_nop 0
	v_add_u32_e32 v26, 1, v122
	v_add_u32_e32 v27, 2, v122
	v_add_u32_e32 v28, 3, v122
	v_cvt_f32_u32_e32 v25, v122
	v_cvt_f32_u32_e32 v26, v26
	v_cvt_f32_u32_e32 v27, v27
	v_cvt_f32_u32_e32 v28, v28
	v_mul_f32_e32 v25, 0xbed49a78, v25
	v_mul_f32_e32 v26, 0xbed49a78, v26
	v_mul_f32_e32 v27, 0xbed49a78, v27
	v_mul_f32_e32 v28, 0xbed49a78, v28
	v_exp_f32_e32 v25, v25
	v_exp_f32_e32 v26, v26
	v_exp_f32_e32 v27, v27
	v_exp_f32_e32 v28, v28
	s_waitcnt vmcnt(14)
	v_cvt_f32_i32_e32 v24, v207
	v_mul_f32_e32 v25, v25, v24
	v_mul_f32_e32 v26, v26, v24
	v_mul_f32_e32 v29, v27, v24
	v_mul_f32_e32 v30, v28, v24
	v_cvt_f64_f32_e32 v[24:25], v25
	v_cvt_f64_f32_e32 v[26:27], v26
	v_cvt_f64_f32_e32 v[28:29], v29
	v_cvt_f64_f32_e32 v[30:31], v30
	v_mul_f64 v[32:33], v[24:25], s[20:21]
	v_mul_f64 v[36:37], v[26:27], s[20:21]
	v_mul_f64 v[38:39], v[28:29], s[20:21]
	v_mul_f64 v[40:41], v[30:31], s[20:21]
	v_rndne_f64_e32 v[32:33], v[32:33]
	v_rndne_f64_e32 v[36:37], v[36:37]
	v_rndne_f64_e32 v[38:39], v[38:39]
	v_rndne_f64_e32 v[40:41], v[40:41]
	v_fma_f64 v[24:25], v[24:25], s[20:21], -v[32:33]
	v_fma_f64 v[26:27], v[26:27], s[20:21], -v[36:37]
	v_fma_f64 v[28:29], v[28:29], s[20:21], -v[38:39]
	v_fma_f64 v[30:31], v[30:31], s[20:21], -v[40:41]
	v_cvt_f32_f64_e32 v25, v[24:25]
	v_cvt_f32_f64_e32 v27, v[26:27]
	v_cvt_f32_f64_e32 v29, v[28:29]
	v_cvt_f32_f64_e32 v31, v[30:31]
	v_sin_f32_e32 v24, v25
	v_sin_f32_e32 v28, v27
	v_sin_f32_e32 v32, v29
	v_sin_f32_e32 v39, v31
	v_cos_f32_e32 v38, v31
	v_cos_f32_e32 v26, v25
	v_cos_f32_e32 v30, v27
	v_cos_f32_e32 v36, v29
	v_pk_mul_f32 v[24:25], v[20:21], v[24:25] op_sel:[1,0] op_sel_hi:[0,0]
	v_pk_mul_f32 v[28:29], v[22:23], v[28:29] op_sel:[1,0] op_sel_hi:[0,0]
	v_pk_mul_f32 v[32:33], v[16:17], v[32:33] op_sel:[1,0] op_sel_hi:[0,0]
	v_mul_f32_e32 v42, v19, v39
	v_mov_b32_e32 v44, v39
	v_mov_b32_e32 v45, v38
	v_mul_f32_e32 v46, v19, v38
	v_pk_mul_f32 v[40:41], v[20:21], v[26:27] op_sel_hi:[1,0]
	v_pk_fma_f32 v[20:21], v[20:21], v[26:27], v[24:25] op_sel_hi:[1,0,1]
	v_pk_fma_f32 v[26:27], v[22:23], v[30:31], v[28:29] op_sel_hi:[1,0,1] neg_lo:[0,0,1] neg_hi:[0,0,1]
	v_pk_fma_f32 v[22:23], v[22:23], v[30:31], v[28:29] op_sel_hi:[1,0,1]
	v_pk_fma_f32 v[28:29], v[16:17], v[36:37], v[32:33] op_sel_hi:[1,0,1] neg_lo:[0,0,1] neg_hi:[0,0,1]
	v_pk_fma_f32 v[16:17], v[16:17], v[36:37], v[32:33] op_sel_hi:[1,0,1]
	v_pk_fma_f32 v[30:31], v[18:19], v[38:39], v[42:43] op_sel_hi:[1,1,0] neg_lo:[0,0,1] neg_hi:[0,0,1]
	v_pk_fma_f32 v[32:33], v[18:19], v[44:45], v[46:47] op_sel_hi:[1,1,0]
	v_sub_f32_e32 v20, v40, v24
	v_mov_b32_e32 v22, v26
	v_mov_b32_e32 v16, v28
	v_mov_b32_e32 v18, v30
	v_mov_b32_e32 v19, v32
; __device__ __forceinline__ void store8(bf16_t* dst, const float* v) { u32x4 w; w.x = pk2(v[0], v[1]); w.y = pk2(v[2], v[3]); w.z = pk2(v[4], v[5]); w.w = pk2(v[6], v[7]); *(u32x4*)dst = w; }
;     __device__ __forceinline__ void operator()(const pg8::f32x4 (&acc)[2][2][4][2], const pg8::Unit& u, int wr, int wc, int fr, int fq) const {
;     ...
;                 const int row = u.pm * 256 + ai * 128 + wr * 64 + m * 16 + fr;
;                 const int bb = row >> 13, ss = row & 8191;
;                 float ssq = 0.f;
;                 float rs = 1.f;
;                 if constexpr (KIND == EK_Q || KIND == EK_KV) rs = __builtin_amdgcn_rsqf(a.ssq0[row] * (1.f / 512.f) + EPS);
;     ...
;                         const int c = pn * 256 + cl, h = c / 192, dd = c - h * 192;
; #pragma unroll
;                         for (int j = 0; j < 8; ++j) v[j] *= rs;
;                         if (dd >= 128) {
;                             const int p = a.pos[row];
; #pragma unroll
;                             for (int j = 0; j < 4; ++j) rope_pair(v[2 * j], v[2 * j + 1], p, ((dd - 128) >> 1) + j);
;                         }
;                         store8(a.o0 + ((size_t)((bb * NH + h) * SEQ + ss)) * 192 + dd, v);
.LBB0_598:
	s_or_b64 exec, exec, s[30:31]
	v_or_b32_e32 v26, v58, v34
	v_mov_b64_e32 v[24:25], s[14:15]
	v_mad_i64_i32 v[24:25], s[30:31], v26, s61, v[24:25]
	v_lshl_add_u64 v[24:25], v[112:113], 1, v[24:25]
	v_cvt_pk_bf16_f32 v20, v20, v21
	v_cvt_pk_bf16_f32 v21, v22, v23
	v_cvt_pk_bf16_f32 v22, v16, v17
	v_cvt_pk_bf16_f32 v23, v18, v19
	global_store_dwordx4 v[24:25], v[20:23], off
	s_nop 0
	s_waitcnt vmcnt(22)
	v_fmamk_f32 v16, v200, 0x3b000000, v161
	v_rsq_f32_e32 v16, v16
	s_nop 0
	v_pk_mul_f32 v[12:13], v[12:13], v[16:17] op_sel_hi:[1,0]
	v_pk_mul_f32 v[14:15], v[14:15], v[16:17] op_sel_hi:[1,0]
	v_pk_mul_f32 v[8:9], v[8:9], v[16:17] op_sel_hi:[1,0]
	v_pk_mul_f32 v[10:11], v[10:11], v[16:17] op_sel_hi:[1,0]
	s_and_saveexec_b64 s[30:31], vcc
	s_cbranch_execz .LBB0_600
	s_nop 0
	v_or_b32_e32 v19, 1, v149
	v_or_b32_e32 v20, 2, v149
	v_or_b32_e32 v21, 3, v149
	v_cvt_f32_u32_e32 v18, v149
	v_cvt_f32_u32_e32 v19, v19
	v_cvt_f32_u32_e32 v20, v20
	v_cvt_f32_u32_e32 v21, v21
	v_mul_f32_e32 v18, 0xbed49a78, v18
	v_mul_f32_e32 v19, 0xbed49a78, v19
	v_mul_f32_e32 v20, 0xbed49a78, v20
	v_mul_f32_e32 v21, 0xbed49a78, v21
	v_exp_f32_e32 v18, v18
	v_exp_f32_e32 v19, v19
	v_exp_f32_e32 v20, v20
	v_exp_f32_e32 v21, v21
	s_waitcnt vmcnt(14)
	v_cvt_f32_i32_e32 v17, v208
	v_mul_f32_e32 v18, v18, v17
	v_mul_f32_e32 v22, v19, v17
	v_mul_f32_e32 v23, v20, v17
	v_mul_f32_e32 v17, v21, v17
	v_cvt_f64_f32_e32 v[18:19], v18
	v_cvt_f64_f32_e32 v[20:21], v22
	v_cvt_f64_f32_e32 v[22:23], v23
	v_cvt_f64_f32_e32 v[24:25], v17
	v_mul_f64 v[26:27], v[18:19], s[20:21]
	v_mul_f64 v[28:29], v[20:21], s[20:21]
	v_mul_f64 v[30:31], v[22:23], s[20:21]
	v_mul_f64 v[32:33], v[24:25], s[20:21]
	v_rndne_f64_e32 v[26:27], v[26:27]
	v_rndne_f64_e32 v[28:29], v[28:29]
	v_rndne_f64_e32 v[30:31], v[30:31]
	v_rndne_f64_e32 v[32:33], v[32:33]
	v_fma_f64 v[18:19], v[18:19], s[20:21], -v[26:27]
	v_fma_f64 v[20:21], v[20:21], s[20:21], -v[28:29]
	v_fma_f64 v[22:23], v[22:23], s[20:21], -v[30:31]
	v_fma_f64 v[24:25], v[24:25], s[20:21], -v[32:33]
	v_cvt_f32_f64_e32 v17, v[18:19]
	v_cvt_f32_f64_e32 v19, v[20:21]
	v_cvt_f32_f64_e32 v21, v[22:23]
	v_cvt_f32_f64_e32 v23, v[24:25]
	v_sin_f32_e32 v18, v17
	v_sin_f32_e32 v22, v19
	v_sin_f32_e32 v26, v21
	v_sin_f32_e32 v31, v23
	v_cos_f32_e32 v30, v23
	v_cos_f32_e32 v20, v17
	v_cos_f32_e32 v24, v19
	v_cos_f32_e32 v28, v21
	v_pk_mul_f32 v[18:19], v[12:13], v[18:19] op_sel:[1,0] op_sel_hi:[0,0]
	v_pk_mul_f32 v[22:23], v[14:15], v[22:23] op_sel:[1,0] op_sel_hi:[0,0]
	v_pk_mul_f32 v[26:27], v[8:9], v[26:27] op_sel:[1,0] op_sel_hi:[0,0]
	v_mul_f32_e32 v34, v11, v31
	v_mov_b32_e32 v36, v31
	v_mov_b32_e32 v37, v30
	v_mul_f32_e32 v38, v11, v30
	v_pk_mul_f32 v[32:33], v[12:13], v[20:21] op_sel_hi:[1,0]
	v_pk_fma_f32 v[12:13], v[12:13], v[20:21], v[18:19] op_sel_hi:[1,0,1]
	v_pk_fma_f32 v[20:21], v[14:15], v[24:25], v[22:23] op_sel_hi:[1,0,1] neg_lo:[0,0,1] neg_hi:[0,0,1]
	v_pk_fma_f32 v[14:15], v[14:15], v[24:25], v[22:23] op_sel_hi:[1,0,1]
	v_pk_fma_f32 v[22:23], v[8:9], v[28:29], v[26:27] op_sel_hi:[1,0,1] neg_lo:[0,0,1] neg_hi:[0,0,1]
	v_pk_fma_f32 v[8:9], v[8:9], v[28:29], v[26:27] op_sel_hi:[1,0,1]
	v_pk_fma_f32 v[24:25], v[10:11], v[30:31], v[34:35] op_sel_hi:[1,1,0] neg_lo:[0,0,1] neg_hi:[0,0,1]
	v_pk_fma_f32 v[26:27], v[10:11], v[36:37], v[38:39] op_sel_hi:[1,1,0]
	v_sub_f32_e32 v12, v32, v18
	v_mov_b32_e32 v14, v20
	v_mov_b32_e32 v8, v22
	v_mov_b32_e32 v10, v24
	v_mov_b32_e32 v11, v26
.LBB0_600:
	s_or_b64 exec, exec, s[30:31]
	v_bitop3_b32 v18, v64, s64, 48 bitop3:0xc8
	v_or_b32_e32 v19, v65, v18
	v_mov_b64_e32 v[20:21], s[14:15]
	v_mov_b32_e32 v17, v16
	v_mad_i64_i32 v[20:21], s[30:31], v19, s61, v[20:21]
	v_lshl_add_u64 v[20:21], v[144:145], 1, v[20:21]
	v_cvt_pk_bf16_f32 v12, v12, v13
	v_cvt_pk_bf16_f32 v13, v14, v15
	v_cvt_pk_bf16_f32 v14, v8, v9
	v_cvt_pk_bf16_f32 v15, v10, v11
	v_pk_mul_f32 v[4:5], v[4:5], v[16:17]
	v_pk_mul_f32 v[6:7], v[6:7], v[16:17]
	v_pk_mul_f32 v[0:1], v[0:1], v[16:17]
	v_pk_mul_f32 v[2:3], v[2:3], v[16:17]
	global_store_dwordx4 v[20:21], v[12:15], off
	s_and_saveexec_b64 s[30:31], s[6:7]
	s_cbranch_execz .LBB0_602
	s_nop 0
	v_add_u32_e32 v10, 1, v122
	v_add_u32_e32 v11, 2, v122
	v_add_u32_e32 v12, 3, v122
	v_cvt_f32_u32_e32 v9, v122
	v_cvt_f32_u32_e32 v10, v10
	v_cvt_f32_u32_e32 v11, v11
	v_cvt_f32_u32_e32 v12, v12
	v_mul_f32_e32 v9, 0xbed49a78, v9
	v_mul_f32_e32 v10, 0xbed49a78, v10
	v_mul_f32_e32 v11, 0xbed49a78, v11
	v_mul_f32_e32 v12, 0xbed49a78, v12
	v_exp_f32_e32 v9, v9
	v_exp_f32_e32 v10, v10
	v_exp_f32_e32 v11, v11
	v_exp_f32_e32 v12, v12
	s_waitcnt vmcnt(15)
	v_cvt_f32_i32_e32 v8, v208
	v_mul_f32_e32 v9, v9, v8
	v_mul_f32_e32 v10, v10, v8
	v_mul_f32_e32 v13, v11, v8
	v_mul_f32_e32 v14, v12, v8
	v_cvt_f64_f32_e32 v[8:9], v9
	v_cvt_f64_f32_e32 v[10:11], v10
	v_cvt_f64_f32_e32 v[12:13], v13
	v_cvt_f64_f32_e32 v[14:15], v14
	v_mul_f64 v[16:17], v[8:9], s[20:21]
	v_mul_f64 v[20:21], v[10:11], s[20:21]
	v_mul_f64 v[22:23], v[12:13], s[20:21]
	v_mul_f64 v[24:25], v[14:15], s[20:21]
	v_rndne_f64_e32 v[16:17], v[16:17]
	v_rndne_f64_e32 v[20:21], v[20:21]
	v_rndne_f64_e32 v[22:23], v[22:23]
	v_rndne_f64_e32 v[24:25], v[24:25]
	v_fma_f64 v[8:9], v[8:9], s[20:21], -v[16:17]
	v_fma_f64 v[10:11], v[10:11], s[20:21], -v[20:21]
	v_fma_f64 v[12:13], v[12:13], s[20:21], -v[22:23]
	v_fma_f64 v[14:15], v[14:15], s[20:21], -v[24:25]
	v_cvt_f32_f64_e32 v9, v[8:9]
	v_cvt_f32_f64_e32 v11, v[10:11]
	v_cvt_f32_f64_e32 v13, v[12:13]
	v_cvt_f32_f64_e32 v15, v[14:15]
	v_sin_f32_e32 v8, v9
	v_sin_f32_e32 v12, v11
	v_sin_f32_e32 v16, v13
	v_sin_f32_e32 v23, v15
	v_cos_f32_e32 v22, v15
	v_cos_f32_e32 v10, v9
	v_cos_f32_e32 v14, v11
	v_cos_f32_e32 v20, v13
	v_pk_mul_f32 v[8:9], v[4:5], v[8:9] op_sel:[1,0] op_sel_hi:[0,0]
	v_pk_mul_f32 v[12:13], v[6:7], v[12:13] op_sel:[1,0] op_sel_hi:[0,0]
	v_pk_mul_f32 v[16:17], v[0:1], v[16:17] op_sel:[1,0] op_sel_hi:[0,0]
	v_mul_f32_e32 v26, v3, v23
	v_mov_b32_e32 v28, v23
	v_mov_b32_e32 v29, v22
	v_mul_f32_e32 v30, v3, v22
	v_pk_mul_f32 v[24:25], v[4:5], v[10:11] op_sel_hi:[1,0]
	v_pk_fma_f32 v[4:5], v[4:5], v[10:11], v[8:9] op_sel_hi:[1,0,1]
	v_pk_fma_f32 v[10:11], v[6:7], v[14:15], v[12:13] op_sel_hi:[1,0,1] neg_lo:[0,0,1] neg_hi:[0,0,1]
	v_pk_fma_f32 v[6:7], v[6:7], v[14:15], v[12:13] op_sel_hi:[1,0,1]
	v_pk_fma_f32 v[12:13], v[0:1], v[20:21], v[16:17] op_sel_hi:[1,0,1] neg_lo:[0,0,1] neg_hi:[0,0,1]
	v_pk_fma_f32 v[0:1], v[0:1], v[20:21], v[16:17] op_sel_hi:[1,0,1]
	v_pk_fma_f32 v[14:15], v[2:3], v[22:23], v[26:27] op_sel_hi:[1,1,0] neg_lo:[0,0,1] neg_hi:[0,0,1]
	v_pk_fma_f32 v[16:17], v[2:3], v[28:29], v[30:31] op_sel_hi:[1,1,0]
	v_sub_f32_e32 v4, v24, v8
	v_mov_b32_e32 v6, v10
	v_mov_b32_e32 v0, v12
	v_mov_b32_e32 v2, v14
	v_mov_b32_e32 v3, v16

; __device__ __forceinline__ void store8(bf16_t* dst, const float* v) { u32x4 w; w.x = pk2(v[0], v[1]); w.y = pk2(v[2], v[3]); w.z = pk2(v[4], v[5]); w.w = pk2(v[6], v[7]); *(u32x4*)dst = w; }
;     __device__ __forceinline__ void operator()(const pg8::f32x4 (&acc)[2][2][4][2], const pg8::Unit& u, int wr, int wc, int fr, int fq) const {
;     ...
;                 const int row = u.pm * 256 + ai * 128 + wr * 64 + m * 16 + fr;
;                 const int bb = row >> 13, ss = row & 8191;
;                 float ssq = 0.f;
;                 float rs = 1.f;
;                 if constexpr (KIND == EK_Q || KIND == EK_KV) rs = __builtin_amdgcn_rsqf(a.ssq0[row] * (1.f / 512.f) + EPS);
;     ...
;                     } else if constexpr (KIND == EK_KV) {
; #pragma unroll
;                         for (int j = 0; j < 8; ++j) v[j] *= rs;
;                         store8((bj ? a.o1 : a.o0) + ((size_t)((bb * NH + pn) * SEQ + ss)) * 128 + (cl & 127), v);
.LBB0_626:
	s_lshl_b32 s15, s22, 8
	s_add_i32 s15, s15, s41
	v_or_b32_e32 v148, s15, v150
	v_lshlrev_b32_e32 v232, 2, v148
	global_load_dword v233, v232, s[8:9]
	global_load_dword v234, v232, s[8:9] offset:64
	global_load_dword v235, v232, s[8:9] offset:128
	global_load_dword v236, v232, s[8:9] offset:192
	global_load_dword v237, v232, s[8:9] offset:512
	global_load_dword v238, v232, s[8:9] offset:576
	global_load_dword v239, v232, s[8:9] offset:640
	global_load_dword v240, v232, s[8:9] offset:704
	v_ashrrev_i32_e32 v149, 31, v148
	v_lshl_add_u64 v[158:159], v[148:149], 2, s[8:9]
	s_nop 0
	s_lshr_b32 s17, s15, 10
	s_and_b32 s17, s17, 0x7fff8
	s_add_i32 s17, s17, s50
	v_bitop3_b32 v157, s15, v156, v150 bitop3:0xc8
	s_lshl_b32 s17, s17, 13
	v_or_b32_e32 v160, s17, v157
	v_ashrrev_i32_e32 v161, 31, v160
	v_or_b32_e32 v158, 16, v148
	v_lshlrev_b64 v[160:161], 8, v[160:161]
	v_ashrrev_i32_e32 v159, 31, v158
	v_lshl_add_u64 v[164:165], v[136:137], 0, v[160:161]
	v_lshl_add_u64 v[158:159], v[158:159], 2, s[8:9]
	v_lshl_add_u64 v[160:161], v[138:139], 0, v[160:161]
	s_addk_i32 s15, 0x80
	s_andn2_b64 vcc, exec, s[4:5]
	s_mov_b64 s[4:5], -1
	s_waitcnt vmcnt(7)
	v_fmamk_f32 v149, v233, 0x3b000000, v155
	v_rsq_f32_e32 v162, v149
	s_nop 0
	v_pk_mul_f32 v[124:125], v[124:125], v[162:163] op_sel_hi:[1,0]
	v_pk_mul_f32 v[126:127], v[126:127], v[162:163] op_sel_hi:[1,0]
	v_pk_mul_f32 v[120:121], v[120:121], v[162:163] op_sel_hi:[1,0]
	v_pk_mul_f32 v[122:123], v[122:123], v[162:163] op_sel_hi:[1,0]
	v_pk_mul_f32 v[116:117], v[116:117], v[162:163] op_sel_hi:[1,0]
	v_pk_mul_f32 v[118:119], v[118:119], v[162:163] op_sel_hi:[1,0]
	v_pk_mul_f32 v[168:169], v[112:113], v[162:163] op_sel_hi:[1,0]
	v_pk_mul_f32 v[162:163], v[114:115], v[162:163] op_sel_hi:[1,0]
	v_cvt_pk_bf16_f32 v112, v124, v125
	v_cvt_pk_bf16_f32 v113, v126, v127
	v_cvt_pk_bf16_f32 v114, v120, v121
	v_cvt_pk_bf16_f32 v115, v122, v123
	v_cvt_pk_bf16_f32 v116, v116, v117
	v_cvt_pk_bf16_f32 v117, v118, v119
	v_cvt_pk_bf16_f32 v118, v168, v169
	v_cvt_pk_bf16_f32 v119, v162, v163
	global_store_dwordx4 v[164:165], v[112:115], off
	global_store_dwordx4 v[160:161], v[116:119], off
	s_nop 0
	v_bitop3_b32 v114, v148, s47, 16 bitop3:0xc8
	v_or_b32_e32 v114, s17, v114
	v_ashrrev_i32_e32 v115, 31, v114
	v_or_b32_e32 v112, 32, v148
	v_lshlrev_b64 v[114:115], 8, v[114:115]
	v_ashrrev_i32_e32 v113, 31, v112
	v_lshl_add_u64 v[118:119], v[136:137], 0, v[114:115]
	v_lshl_add_u64 v[112:113], v[112:113], 2, s[8:9]
	v_lshl_add_u64 v[114:115], v[138:139], 0, v[114:115]
	s_waitcnt vmcnt(8)
	v_fmamk_f32 v116, v234, 0x3b000000, v155
	v_rsq_f32_e32 v116, v116
	s_nop 0
	v_pk_mul_f32 v[108:109], v[108:109], v[116:117] op_sel_hi:[1,0]
	v_pk_mul_f32 v[110:111], v[110:111], v[116:117] op_sel_hi:[1,0]
	v_pk_mul_f32 v[104:105], v[104:105], v[116:117] op_sel_hi:[1,0]
	v_pk_mul_f32 v[106:107], v[106:107], v[116:117] op_sel_hi:[1,0]
	v_pk_mul_f32 v[100:101], v[100:101], v[116:117] op_sel_hi:[1,0]
	v_pk_mul_f32 v[102:103], v[102:103], v[116:117] op_sel_hi:[1,0]
	v_pk_mul_f32 v[120:121], v[96:97], v[116:117] op_sel_hi:[1,0]
	v_pk_mul_f32 v[116:117], v[98:99], v[116:117] op_sel_hi:[1,0]
	v_cvt_pk_bf16_f32 v96, v108, v109
	v_cvt_pk_bf16_f32 v97, v110, v111
	v_cvt_pk_bf16_f32 v98, v104, v105
	v_cvt_pk_bf16_f32 v99, v106, v107
	v_cvt_pk_bf16_f32 v100, v100, v101
	v_cvt_pk_bf16_f32 v101, v102, v103
	v_cvt_pk_bf16_f32 v102, v120, v121
	v_cvt_pk_bf16_f32 v103, v116, v117
	global_store_dwordx4 v[118:119], v[96:99], off
	global_store_dwordx4 v[114:115], v[100:103], off
	s_nop 0
	v_bitop3_b32 v98, v148, s48, 32 bitop3:0xc8
	v_or_b32_e32 v98, s17, v98
	v_ashrrev_i32_e32 v99, 31, v98
	v_or_b32_e32 v96, 48, v148
	v_lshlrev_b64 v[98:99], 8, v[98:99]
	v_ashrrev_i32_e32 v97, 31, v96
	v_lshl_add_u64 v[102:103], v[136:137], 0, v[98:99]
	v_lshl_add_u64 v[96:97], v[96:97], 2, s[8:9]
	v_lshl_add_u64 v[98:99], v[138:139], 0, v[98:99]
	s_waitcnt vmcnt(9)
	v_fmamk_f32 v100, v235, 0x3b000000, v155
	v_rsq_f32_e32 v100, v100
	s_nop 0
	v_pk_mul_f32 v[92:93], v[92:93], v[100:101] op_sel_hi:[1,0]
	v_pk_mul_f32 v[94:95], v[94:95], v[100:101] op_sel_hi:[1,0]
	v_pk_mul_f32 v[88:89], v[88:89], v[100:101] op_sel_hi:[1,0]
	v_pk_mul_f32 v[90:91], v[90:91], v[100:101] op_sel_hi:[1,0]
	v_pk_mul_f32 v[84:85], v[84:85], v[100:101] op_sel_hi:[1,0]
	v_pk_mul_f32 v[86:87], v[86:87], v[100:101] op_sel_hi:[1,0]
	v_pk_mul_f32 v[104:105], v[80:81], v[100:101] op_sel_hi:[1,0]
	v_pk_mul_f32 v[100:101], v[82:83], v[100:101] op_sel_hi:[1,0]
	v_cvt_pk_bf16_f32 v80, v92, v93
	v_cvt_pk_bf16_f32 v81, v94, v95
	v_cvt_pk_bf16_f32 v82, v88, v89
	v_cvt_pk_bf16_f32 v83, v90, v91
	v_cvt_pk_bf16_f32 v84, v84, v85
	v_cvt_pk_bf16_f32 v85, v86, v87
	v_cvt_pk_bf16_f32 v86, v104, v105
	v_cvt_pk_bf16_f32 v87, v100, v101
	global_store_dwordx4 v[102:103], v[80:83], off
	global_store_dwordx4 v[98:99], v[84:87], off
	s_nop 0
	v_or_b32_e32 v80, s15, v150
	v_ashrrev_i32_e32 v81, 31, v80
	v_lshl_add_u64 v[82:83], v[80:81], 2, s[8:9]
	v_bitop3_b32 v84, v148, s49, 48 bitop3:0xc8
	v_or_b32_e32 v84, s17, v84
	v_ashrrev_i32_e32 v85, 31, v84
	v_lshlrev_b64 v[84:85], 8, v[84:85]
	v_lshl_add_u64 v[88:89], v[136:137], 0, v[84:85]
	v_lshl_add_u64 v[84:85], v[138:139], 0, v[84:85]
	s_lshr_b32 s17, s15, 10
	s_waitcnt vmcnt(10)
; __device__ __forceinline__ void store8(bf16_t* dst, const float* v) { u32x4 w; w.x = pk2(v[0], v[1]); w.y = pk2(v[2], v[3]); w.z = pk2(v[4], v[5]); w.w = pk2(v[6], v[7]); *(u32x4*)dst = w; }
;     __device__ __forceinline__ void operator()(const pg8::f32x4 (&acc)[2][2][4][2], const pg8::Unit& u, int wr, int wc, int fr, int fq) const {
;     ...
;                 const int row = u.pm * 256 + ai * 128 + wr * 64 + m * 16 + fr;
;                 const int bb = row >> 13, ss = row & 8191;
;                 float ssq = 0.f;
;                 float rs = 1.f;
;                 if constexpr (KIND == EK_Q || KIND == EK_KV) rs = __builtin_amdgcn_rsqf(a.ssq0[row] * (1.f / 512.f) + EPS);
;     ...
;                     } else if constexpr (KIND == EK_KV) {
; #pragma unroll
;                         for (int j = 0; j < 8; ++j) v[j] *= rs;
;                         store8((bj ? a.o1 : a.o0) + ((size_t)((bb * NH + pn) * SEQ + ss)) * 128 + (cl & 127), v);
	v_fmamk_f32 v81, v236, 0x3b000000, v155
	v_rsq_f32_e32 v86, v81
	s_nop 0
	v_pk_mul_f32 v[76:77], v[76:77], v[86:87] op_sel_hi:[1,0]
	v_pk_mul_f32 v[78:79], v[78:79], v[86:87] op_sel_hi:[1,0]
	v_pk_mul_f32 v[72:73], v[72:73], v[86:87] op_sel_hi:[1,0]
	v_pk_mul_f32 v[74:75], v[74:75], v[86:87] op_sel_hi:[1,0]
	v_pk_mul_f32 v[68:69], v[68:69], v[86:87] op_sel_hi:[1,0]
	v_pk_mul_f32 v[70:71], v[70:71], v[86:87] op_sel_hi:[1,0]
	v_pk_mul_f32 v[90:91], v[64:65], v[86:87] op_sel_hi:[1,0]
	v_pk_mul_f32 v[86:87], v[66:67], v[86:87] op_sel_hi:[1,0]
	v_cvt_pk_bf16_f32 v64, v76, v77
	v_cvt_pk_bf16_f32 v65, v78, v79
	v_cvt_pk_bf16_f32 v66, v72, v73
	v_cvt_pk_bf16_f32 v67, v74, v75
	v_cvt_pk_bf16_f32 v68, v68, v69
	v_cvt_pk_bf16_f32 v69, v70, v71
	v_cvt_pk_bf16_f32 v70, v90, v91
	v_cvt_pk_bf16_f32 v71, v86, v87
	global_store_dwordx4 v[88:89], v[64:67], off
	global_store_dwordx4 v[84:85], v[68:71], off
	s_nop 0
	v_bitop3_b32 v66, s15, v156, v150 bitop3:0xc8
	s_and_b32 s15, s17, 0x7fff8
	s_add_i32 s15, s15, s50
	s_lshl_b32 s15, s15, 13
	v_or_b32_e32 v66, s15, v66
	v_ashrrev_i32_e32 v67, 31, v66
	v_or_b32_e32 v64, 16, v80
	v_lshlrev_b64 v[66:67], 8, v[66:67]
	v_ashrrev_i32_e32 v65, 31, v64
	v_lshl_add_u64 v[70:71], v[136:137], 0, v[66:67]
	v_lshl_add_u64 v[64:65], v[64:65], 2, s[8:9]
	v_lshl_add_u64 v[66:67], v[138:139], 0, v[66:67]
	s_waitcnt vmcnt(11)
	v_fmamk_f32 v68, v237, 0x3b000000, v155
	v_rsq_f32_e32 v68, v68
	s_nop 0
	v_pk_mul_f32 v[60:61], v[60:61], v[68:69] op_sel_hi:[1,0]
	v_pk_mul_f32 v[62:63], v[62:63], v[68:69] op_sel_hi:[1,0]
	v_pk_mul_f32 v[56:57], v[56:57], v[68:69] op_sel_hi:[1,0]
	v_pk_mul_f32 v[58:59], v[58:59], v[68:69] op_sel_hi:[1,0]
	v_pk_mul_f32 v[52:53], v[52:53], v[68:69] op_sel_hi:[1,0]
	v_pk_mul_f32 v[54:55], v[54:55], v[68:69] op_sel_hi:[1,0]
	v_pk_mul_f32 v[72:73], v[48:49], v[68:69] op_sel_hi:[1,0]
	v_pk_mul_f32 v[68:69], v[50:51], v[68:69] op_sel_hi:[1,0]
	v_cvt_pk_bf16_f32 v48, v60, v61
	v_cvt_pk_bf16_f32 v49, v62, v63
	v_cvt_pk_bf16_f32 v50, v56, v57
	v_cvt_pk_bf16_f32 v51, v58, v59
	v_cvt_pk_bf16_f32 v52, v52, v53
	v_cvt_pk_bf16_f32 v53, v54, v55
	v_cvt_pk_bf16_f32 v54, v72, v73
	v_cvt_pk_bf16_f32 v55, v68, v69
	global_store_dwordx4 v[70:71], v[48:51], off
	global_store_dwordx4 v[66:67], v[52:55], off
	s_nop 0
	v_bitop3_b32 v50, v80, s47, 16 bitop3:0xc8
	v_or_b32_e32 v50, s15, v50
	v_ashrrev_i32_e32 v51, 31, v50
	v_or_b32_e32 v48, 32, v80
	v_lshlrev_b64 v[50:51], 8, v[50:51]
	v_ashrrev_i32_e32 v49, 31, v48
	v_lshl_add_u64 v[54:55], v[136:137], 0, v[50:51]
	v_lshl_add_u64 v[48:49], v[48:49], 2, s[8:9]
	v_lshl_add_u64 v[50:51], v[138:139], 0, v[50:51]
	s_waitcnt vmcnt(12)
	v_fmamk_f32 v52, v238, 0x3b000000, v155
	v_rsq_f32_e32 v52, v52
	s_nop 0
	v_pk_mul_f32 v[44:45], v[44:45], v[52:53] op_sel_hi:[1,0]
	v_pk_mul_f32 v[46:47], v[46:47], v[52:53] op_sel_hi:[1,0]
	v_pk_mul_f32 v[40:41], v[40:41], v[52:53] op_sel_hi:[1,0]
	v_pk_mul_f32 v[42:43], v[42:43], v[52:53] op_sel_hi:[1,0]
	v_pk_mul_f32 v[36:37], v[36:37], v[52:53] op_sel_hi:[1,0]
	v_pk_mul_f32 v[38:39], v[38:39], v[52:53] op_sel_hi:[1,0]
	v_pk_mul_f32 v[56:57], v[32:33], v[52:53] op_sel_hi:[1,0]
	v_pk_mul_f32 v[52:53], v[34:35], v[52:53] op_sel_hi:[1,0]
	v_cvt_pk_bf16_f32 v32, v44, v45
	v_cvt_pk_bf16_f32 v33, v46, v47
	v_cvt_pk_bf16_f32 v34, v40, v41
	v_cvt_pk_bf16_f32 v35, v42, v43
	v_cvt_pk_bf16_f32 v36, v36, v37
	v_cvt_pk_bf16_f32 v37, v38, v39
	v_cvt_pk_bf16_f32 v38, v56, v57
	v_cvt_pk_bf16_f32 v39, v52, v53
	global_store_dwordx4 v[54:55], v[32:35], off
	global_store_dwordx4 v[50:51], v[36:39], off
	s_nop 0
	v_bitop3_b32 v34, v80, s48, 32 bitop3:0xc8
	v_or_b32_e32 v34, s15, v34
	v_ashrrev_i32_e32 v35, 31, v34
	v_or_b32_e32 v32, 48, v80
	v_lshlrev_b64 v[34:35], 8, v[34:35]
	v_ashrrev_i32_e32 v33, 31, v32
	v_lshl_add_u64 v[38:39], v[136:137], 0, v[34:35]
	v_lshl_add_u64 v[32:33], v[32:33], 2, s[8:9]
	v_lshl_add_u64 v[34:35], v[138:139], 0, v[34:35]
	s_waitcnt vmcnt(13)
	v_fmamk_f32 v36, v239, 0x3b000000, v155
	v_rsq_f32_e32 v36, v36
	s_nop 0
	v_pk_mul_f32 v[28:29], v[28:29], v[36:37] op_sel_hi:[1,0]
	v_pk_mul_f32 v[30:31], v[30:31], v[36:37] op_sel_hi:[1,0]
	v_pk_mul_f32 v[24:25], v[24:25], v[36:37] op_sel_hi:[1,0]
	v_pk_mul_f32 v[26:27], v[26:27], v[36:37] op_sel_hi:[1,0]
	v_pk_mul_f32 v[20:21], v[20:21], v[36:37] op_sel_hi:[1,0]
	v_pk_mul_f32 v[22:23], v[22:23], v[36:37] op_sel_hi:[1,0]
	v_pk_mul_f32 v[40:41], v[16:17], v[36:37] op_sel_hi:[1,0]
	v_pk_mul_f32 v[36:37], v[18:19], v[36:37] op_sel_hi:[1,0]
	v_cvt_pk_bf16_f32 v16, v28, v29
	v_cvt_pk_bf16_f32 v17, v30, v31
	v_cvt_pk_bf16_f32 v18, v24, v25
	v_cvt_pk_bf16_f32 v19, v26, v27
	v_cvt_pk_bf16_f32 v20, v20, v21
	v_cvt_pk_bf16_f32 v21, v22, v23
	v_cvt_pk_bf16_f32 v22, v40, v41
	v_cvt_pk_bf16_f32 v23, v36, v37
	global_store_dwordx4 v[38:39], v[16:19], off
	global_store_dwordx4 v[34:35], v[20:23], off
	s_nop 0
	v_bitop3_b32 v16, v80, s49, 48 bitop3:0xc8
	v_or_b32_e32 v16, s15, v16
	v_ashrrev_i32_e32 v17, 31, v16
	v_lshlrev_b64 v[16:17], 8, v[16:17]
	v_lshl_add_u64 v[20:21], v[136:137], 0, v[16:17]
	v_lshl_add_u64 v[16:17], v[138:139], 0, v[16:17]
	s_waitcnt vmcnt(14)
	v_fmamk_f32 v18, v240, 0x3b000000, v155
	v_rsq_f32_e32 v18, v18
	s_nop 0
	v_pk_mul_f32 v[12:13], v[12:13], v[18:19] op_sel_hi:[1,0]
	v_pk_mul_f32 v[14:15], v[14:15], v[18:19] op_sel_hi:[1,0]
	v_pk_mul_f32 v[8:9], v[8:9], v[18:19] op_sel_hi:[1,0]
	v_pk_mul_f32 v[10:11], v[10:11], v[18:19] op_sel_hi:[1,0]
	v_pk_mul_f32 v[4:5], v[4:5], v[18:19] op_sel_hi:[1,0]
	v_pk_mul_f32 v[6:7], v[6:7], v[18:19] op_sel_hi:[1,0]
	v_pk_mul_f32 v[22:23], v[0:1], v[18:19] op_sel_hi:[1,0]
	v_pk_mul_f32 v[18:19], v[2:3], v[18:19] op_sel_hi:[1,0]
	v_cvt_pk_bf16_f32 v0, v12, v13
	v_cvt_pk_bf16_f32 v1, v14, v15
	v_cvt_pk_bf16_f32 v2, v8, v9
	v_cvt_pk_bf16_f32 v3, v10, v11
	v_cvt_pk_bf16_f32 v4, v4, v5
	v_cvt_pk_bf16_f32 v5, v6, v7
	v_cvt_pk_bf16_f32 v6, v22, v23
	v_cvt_pk_bf16_f32 v7, v18, v19
	global_store_dwordx4 v[20:21], v[0:3], off
	global_store_dwordx4 v[16:17], v[4:7], off
	s_cbranch_vccnz .LBB0_615
	s_andn2_b64 vcc, exec, s[6:7]
	s_cbranch_vccnz .LBB0_614
	s_barrier
	s_branch .LBB0_614
